# v17: v16 + redundant post-barrier lgkmcnt(0) removed in the 8 GEMM main loops
# speedup vs baseline: 1.0088x; 1.0032x over previous
; #define PG8_STAGE(bufoff, gbase, voff) do { _Pragma("unroll") for (int _i = 0; _i < 2; ++_i) \
;         __builtin_amdgcn_global_load_lds((const unsigned*)((const char*)(gbase) + (voff)[_i]), (LAS unsigned*)(lds + (bufoff) + ldsw + _i * 8192), 16, 0, 0); } while (0)
; #define PG8_LDA(dst, b, h) do { _Pragma("unroll") for (int m = 0; m < 4; ++m) _Pragma("unroll") for (int k = 0; k < 2; ++k) dst[m][k] = *(const LAS f16x8*)(lds + PG8_SA(b, h) + aoff + m * 2048 + k * 1024); } while (0)
; #define PG8_LDB(dst, b, h) do { _Pragma("unroll") for (int n = 0; n < 2; ++n) _Pragma("unroll") for (int k = 0; k < 2; ++k) dst[n][k] = *(const LAS f16x8*)(lds + PG8_SB(b, h) + boff + n * 2048 + k * 1024); } while (0)
; #define PG8_MMA(ai, bj, At, Bt) do { __builtin_amdgcn_s_setprio(1); _Pragma("unroll") for (int m = 0; m < 4; ++m) _Pragma("unroll") for (int n = 0; n < 2; ++n) _Pragma("unroll") for (int k = 0; k < 2; ++k) \
;         acc[ai][bj][m][n] = mma16_<Epi::BF16>(Bt[n][k], At[m][k], acc[ai][bj][m][n]); __builtin_amdgcn_s_setprio(0); } while (0)
; #define PG8_WAIT_V(n) asm volatile("s_waitcnt vmcnt(" #n ")" ::: "memory")
; #define PG8_WAIT_L(n) asm volatile("s_waitcnt lgkmcnt(" #n ")" ::: "memory")
; #define PG8_BAR __builtin_amdgcn_s_barrier()
; #define PG8_SCHED __builtin_amdgcn_sched_barrier(0)
;     ...
;             PG8_LDB(B0, 0, 0); PG8_LDB(B1, 0, 1); PG8_SCHED; PG8_LDA(At, 0, 0); PG8_STAGE(PG8_SA(1, 1), a1 + hA, voffA);
;             PG8_WAIT_V(8); PG8_WAIT_L(0); PG8_BAR; PG8_MMA(0, 0, At, B0); PG8_MMA(0, 1, At, B1); PG8_BAR; PG8_SCHED;
;             PG8_LDA(At, 0, 1); PG8_STAGE(PG8_SB(0, 0), b2, voffB); PG8_STAGE(PG8_SB(0, 1), b2 + hB, voffB); PG8_STAGE(PG8_SA(0, 0), a2, voffA);
;             PG8_WAIT_V(8); PG8_WAIT_L(0); PG8_BAR; if (!cur.half) { PG8_MMA(1, 0, At, B0); PG8_MMA(1, 1, At, B1); } PG8_BAR; PG8_SCHED;
.LBB0_157:
	s_add_u32 s28, s26, 0xfffc0080
	s_addc_u32 s29, s27, -1
	s_add_i32 s50, 0, 0x10000
	s_cmp_eq_u32 s49, 12
	s_cselect_b32 s31, s2, s29
	s_cselect_b32 s30, s3, s28
	s_cselect_b32 s29, s11, s48
	s_cselect_b32 s28, s19, s47
	s_add_i32 s52, 0, 0x14000
	v_add_u32_e32 v156, s50, v141
	v_add_u32_e32 v172, s52, v141
	ds_read_b128 v[144:147], v156
	ds_read_b128 v[148:151], v156 offset:1024
	ds_read_b128 v[152:155], v156 offset:2048
	ds_read_b128 v[156:159], v156 offset:3072
	ds_read_b128 v[160:163], v172
	ds_read_b128 v[164:167], v172 offset:1024
	ds_read_b128 v[168:171], v172 offset:2048
	ds_read_b128 v[172:175], v172 offset:3072
	v_lshl_add_u64 v[200:201], s[26:27], 0, v[136:137]
	s_add_i32 m0, s25, 0xc000
	ds_read_b128 v[176:179], v143
	ds_read_b128 v[180:183], v143 offset:1024
	ds_read_b128 v[184:187], v143 offset:2048
	ds_read_b128 v[188:191], v143 offset:3072
	ds_read_b128 v[192:195], v143 offset:4096
	ds_read_b128 v[214:217], v143 offset:5120
	ds_read_b128 v[218:221], v143 offset:6144
	ds_read_b128 v[222:225], v143 offset:7168
	global_load_lds_dwordx4 v[200:201], off
	v_lshl_add_u64 v[200:201], s[26:27], 0, v[138:139]
	s_add_i32 m0, s25, 0xe000
	s_nop 0
	global_load_lds_dwordx4 v[200:201], off
	s_waitcnt vmcnt(8)
	s_waitcnt lgkmcnt(0)
	s_barrier
	s_setprio 1
	v_mfma_f32_16x16x32_bf16 v[126:129], v[144:147], v[176:179], v[126:129]
	v_mfma_f32_16x16x32_bf16 v[118:121], v[152:155], v[176:179], v[118:121]
	v_mfma_f32_16x16x32_bf16 v[110:113], v[144:147], v[184:187], v[110:113]
	v_mfma_f32_16x16x32_bf16 v[102:105], v[152:155], v[184:187], v[102:105]
	v_mfma_f32_16x16x32_bf16 v[94:97], v[144:147], v[192:195], v[94:97]
	v_mfma_f32_16x16x32_bf16 v[86:89], v[152:155], v[192:195], v[86:89]
	v_mfma_f32_16x16x32_bf16 v[78:81], v[144:147], v[218:221], v[78:81]
	v_mfma_f32_16x16x32_bf16 v[70:73], v[152:155], v[218:221], v[70:73]
	v_mfma_f32_16x16x32_bf16 v[126:129], v[148:151], v[180:183], v[126:129]
	v_mfma_f32_16x16x32_bf16 v[118:121], v[156:159], v[180:183], v[118:121]
	v_mfma_f32_16x16x32_bf16 v[110:113], v[148:151], v[188:191], v[110:113]
	v_mfma_f32_16x16x32_bf16 v[102:105], v[156:159], v[188:191], v[102:105]
	v_mfma_f32_16x16x32_bf16 v[94:97], v[148:151], v[214:217], v[94:97]
	v_mfma_f32_16x16x32_bf16 v[86:89], v[156:159], v[214:217], v[86:89]
	v_mfma_f32_16x16x32_bf16 v[78:81], v[148:151], v[222:225], v[78:81]
	v_mfma_f32_16x16x32_bf16 v[70:73], v[156:159], v[222:225], v[70:73]
	s_setprio 0
	s_setprio 1
	v_mfma_f32_16x16x32_bf16 v[122:125], v[160:163], v[176:179], v[122:125]
	v_mfma_f32_16x16x32_bf16 v[114:117], v[168:171], v[176:179], v[114:117]
	v_mfma_f32_16x16x32_bf16 v[106:109], v[160:163], v[184:187], v[106:109]
	v_mfma_f32_16x16x32_bf16 v[98:101], v[168:171], v[184:187], v[98:101]
	v_mfma_f32_16x16x32_bf16 v[90:93], v[160:163], v[192:195], v[90:93]
	v_mfma_f32_16x16x32_bf16 v[82:85], v[168:171], v[192:195], v[82:85]
	v_mfma_f32_16x16x32_bf16 v[74:77], v[160:163], v[218:221], v[74:77]
	v_mfma_f32_16x16x32_bf16 v[66:69], v[168:171], v[218:221], v[66:69]
	v_mfma_f32_16x16x32_bf16 v[122:125], v[164:167], v[180:183], v[122:125]
	v_mfma_f32_16x16x32_bf16 v[114:117], v[172:175], v[180:183], v[114:117]
	v_mfma_f32_16x16x32_bf16 v[106:109], v[164:167], v[188:191], v[106:109]
	v_mfma_f32_16x16x32_bf16 v[98:101], v[172:175], v[188:191], v[98:101]
	v_mfma_f32_16x16x32_bf16 v[90:93], v[164:167], v[214:217], v[90:93]
	v_mfma_f32_16x16x32_bf16 v[82:85], v[172:175], v[214:217], v[82:85]
	v_mfma_f32_16x16x32_bf16 v[74:77], v[164:167], v[222:225], v[74:77]
	v_mfma_f32_16x16x32_bf16 v[66:69], v[172:175], v[222:225], v[66:69]
	s_setprio 0
	s_barrier
	s_add_i32 s50, s50, s34
	v_lshl_add_u64 v[200:201], s[28:29], 0, v[0:1]
	s_mov_b32 m0, s50
	ds_read_b128 v[176:179], v143 offset:16384
	ds_read_b128 v[180:183], v143 offset:17408
	ds_read_b128 v[184:187], v143 offset:18432
	ds_read_b128 v[188:191], v143 offset:19456
	ds_read_b128 v[192:195], v143 offset:20480
	ds_read_b128 v[214:217], v143 offset:21504
	ds_read_b128 v[218:221], v143 offset:22528
	ds_read_b128 v[222:225], v143 offset:23552
	global_load_lds_dwordx4 v[200:201], off
	s_add_i32 m0, s50, 0x2000
	s_add_u32 s50, s28, 0x40000
	v_lshl_add_u64 v[202:203], s[28:29], 0, v[130:131]
	s_addc_u32 s51, s29, 0
	s_add_i32 s52, s52, s34
	global_load_lds_dwordx4 v[202:203], off
	v_lshl_add_u64 v[226:227], s[50:51], 0, v[0:1]
	s_mov_b32 m0, s52
	v_lshl_add_u64 v[228:229], s[30:31], 0, v[132:133]
	global_load_lds_dwordx4 v[226:227], off
	v_lshl_add_u64 v[226:227], s[50:51], 0, v[130:131]
	s_add_i32 m0, s52, 0x2000
	s_nop 0
	global_load_lds_dwordx4 v[226:227], off
	v_lshl_add_u64 v[226:227], s[30:31], 0, v[134:135]
	s_mov_b32 m0, s25
	s_nop 0
	global_load_lds_dwordx4 v[226:227], off
	s_mov_b32 m0, s36
	s_nop 0
	global_load_lds_dwordx4 v[228:229], off
	s_waitcnt vmcnt(8)
	s_waitcnt lgkmcnt(0)
	s_barrier
; #define PG8_STAGE(bufoff, gbase, voff) do { _Pragma("unroll") for (int _i = 0; _i < 2; ++_i) \
;         __builtin_amdgcn_global_load_lds((const unsigned*)((const char*)(gbase) + (voff)[_i]), (LAS unsigned*)(lds + (bufoff) + ldsw + _i * 8192), 16, 0, 0); } while (0)
; #define PG8_LDA(dst, b, h) do { _Pragma("unroll") for (int m = 0; m < 4; ++m) _Pragma("unroll") for (int k = 0; k < 2; ++k) dst[m][k] = *(const LAS f16x8*)(lds + PG8_SA(b, h) + aoff + m * 2048 + k * 1024); } while (0)
; #define PG8_LDB(dst, b, h) do { _Pragma("unroll") for (int n = 0; n < 2; ++n) _Pragma("unroll") for (int k = 0; k < 2; ++k) dst[n][k] = *(const LAS f16x8*)(lds + PG8_SB(b, h) + boff + n * 2048 + k * 1024); } while (0)
; #define PG8_MMA(ai, bj, At, Bt) do { __builtin_amdgcn_s_setprio(1); _Pragma("unroll") for (int m = 0; m < 4; ++m) _Pragma("unroll") for (int n = 0; n < 2; ++n) _Pragma("unroll") for (int k = 0; k < 2; ++k) \
;         acc[ai][bj][m][n] = mma16_<Epi::BF16>(Bt[n][k], At[m][k], acc[ai][bj][m][n]); __builtin_amdgcn_s_setprio(0); } while (0)
; #define PG8_WAIT_V(n) asm volatile("s_waitcnt vmcnt(" #n ")" ::: "memory")
; #define PG8_WAIT_L(n) asm volatile("s_waitcnt lgkmcnt(" #n ")" ::: "memory")
; #define PG8_BAR __builtin_amdgcn_s_barrier()
; #define PG8_SCHED __builtin_amdgcn_sched_barrier(0)
;     ...
;             PG8_WAIT_V(8); PG8_WAIT_L(0); PG8_BAR; if (!cur.half) { PG8_MMA(1, 0, At, B0); PG8_MMA(1, 1, At, B1); } PG8_BAR; PG8_SCHED;
;             PG8_LDB(B0, 1, 0); PG8_LDB(B1, 1, 1); PG8_SCHED; PG8_LDA(At, 1, 0); PG8_STAGE(PG8_SA(0, 1), a2 + hA, voffA);
;             PG8_WAIT_V(8); PG8_WAIT_L(0); PG8_BAR; PG8_MMA(0, 0, At, B0); PG8_MMA(0, 1, At, B1); PG8_BAR; PG8_SCHED;
	s_setprio 1
	v_mfma_f32_16x16x32_bf16 v[62:65], v[144:147], v[176:179], v[62:65]
	v_mfma_f32_16x16x32_bf16 v[54:57], v[152:155], v[176:179], v[54:57]
	v_mfma_f32_16x16x32_bf16 v[46:49], v[144:147], v[184:187], v[46:49]
	v_mfma_f32_16x16x32_bf16 v[38:41], v[152:155], v[184:187], v[38:41]
	v_mfma_f32_16x16x32_bf16 v[30:33], v[144:147], v[192:195], v[30:33]
	v_mfma_f32_16x16x32_bf16 v[22:25], v[152:155], v[192:195], v[22:25]
	v_mfma_f32_16x16x32_bf16 v[14:17], v[144:147], v[218:221], v[14:17]
	v_mfma_f32_16x16x32_bf16 v[6:9], v[152:155], v[218:221], v[6:9]
	v_mfma_f32_16x16x32_bf16 v[62:65], v[148:151], v[180:183], v[62:65]
	v_mfma_f32_16x16x32_bf16 v[54:57], v[156:159], v[180:183], v[54:57]
	v_mfma_f32_16x16x32_bf16 v[46:49], v[148:151], v[188:191], v[46:49]
	v_mfma_f32_16x16x32_bf16 v[38:41], v[156:159], v[188:191], v[38:41]
	v_mfma_f32_16x16x32_bf16 v[30:33], v[148:151], v[214:217], v[30:33]
	v_mfma_f32_16x16x32_bf16 v[22:25], v[156:159], v[214:217], v[22:25]
	v_mfma_f32_16x16x32_bf16 v[14:17], v[148:151], v[222:225], v[14:17]
	v_mfma_f32_16x16x32_bf16 v[6:9], v[156:159], v[222:225], v[6:9]
	s_setprio 0
	s_setprio 1
	v_mfma_f32_16x16x32_bf16 v[58:61], v[160:163], v[176:179], v[58:61]
	v_mfma_f32_16x16x32_bf16 v[50:53], v[168:171], v[176:179], v[50:53]
	v_mfma_f32_16x16x32_bf16 v[42:45], v[160:163], v[184:187], v[42:45]
	v_mfma_f32_16x16x32_bf16 v[34:37], v[168:171], v[184:187], v[34:37]
	v_mfma_f32_16x16x32_bf16 v[26:29], v[160:163], v[192:195], v[26:29]
	v_mfma_f32_16x16x32_bf16 v[18:21], v[168:171], v[192:195], v[18:21]
	v_mfma_f32_16x16x32_bf16 v[10:13], v[160:163], v[218:221], v[10:13]
	v_mfma_f32_16x16x32_bf16 v[2:5], v[168:171], v[218:221], v[2:5]
	v_mfma_f32_16x16x32_bf16 v[58:61], v[164:167], v[180:183], v[58:61]
	v_mfma_f32_16x16x32_bf16 v[50:53], v[172:175], v[180:183], v[50:53]
	v_mfma_f32_16x16x32_bf16 v[42:45], v[164:167], v[188:191], v[42:45]
	v_mfma_f32_16x16x32_bf16 v[34:37], v[172:175], v[188:191], v[34:37]
	v_mfma_f32_16x16x32_bf16 v[26:29], v[164:167], v[214:217], v[26:29]
	v_mfma_f32_16x16x32_bf16 v[18:21], v[172:175], v[214:217], v[18:21]
	v_mfma_f32_16x16x32_bf16 v[10:13], v[164:167], v[222:225], v[10:13]
	v_mfma_f32_16x16x32_bf16 v[2:5], v[172:175], v[222:225], v[2:5]
	s_setprio 0
	s_barrier
	s_add_i32 s50, 0, 0x18000
	s_add_i32 s51, 0, 0x1c000
	v_add_u32_e32 v156, s50, v141
	v_add_u32_e32 v172, s51, v141
	ds_read_b128 v[144:147], v156
	ds_read_b128 v[148:151], v156 offset:1024
	ds_read_b128 v[152:155], v156 offset:2048
	ds_read_b128 v[156:159], v156 offset:3072
	ds_read_b128 v[160:163], v172
	ds_read_b128 v[164:167], v172 offset:1024
	ds_read_b128 v[168:171], v172 offset:2048
	ds_read_b128 v[172:175], v172 offset:3072
	s_add_u32 s30, s30, 0x40000
	s_addc_u32 s31, s31, 0
	s_mov_b32 m0, s37
	v_lshl_add_u64 v[230:231], s[30:31], 0, v[134:135]
	ds_read_b128 v[176:179], v143 offset:32768
	ds_read_b128 v[180:183], v143 offset:33792
	ds_read_b128 v[184:187], v143 offset:34816
	ds_read_b128 v[188:191], v143 offset:35840
	ds_read_b128 v[192:195], v143 offset:36864
	ds_read_b128 v[214:217], v143 offset:37888
	ds_read_b128 v[218:221], v143 offset:38912
	ds_read_b128 v[222:225], v143 offset:39936
	global_load_lds_dwordx4 v[230:231], off
	v_lshl_add_u64 v[230:231], s[30:31], 0, v[132:133]
	s_mov_b32 m0, s40
	s_nop 0
	global_load_lds_dwordx4 v[230:231], off
	s_waitcnt vmcnt(8)
	s_waitcnt lgkmcnt(0)
	s_barrier
	s_setprio 1
	v_mfma_f32_16x16x32_bf16 v[126:129], v[144:147], v[176:179], v[126:129]
	v_mfma_f32_16x16x32_bf16 v[118:121], v[152:155], v[176:179], v[118:121]
	v_mfma_f32_16x16x32_bf16 v[110:113], v[144:147], v[184:187], v[110:113]
	v_mfma_f32_16x16x32_bf16 v[102:105], v[152:155], v[184:187], v[102:105]
	v_mfma_f32_16x16x32_bf16 v[94:97], v[144:147], v[192:195], v[94:97]
	v_mfma_f32_16x16x32_bf16 v[86:89], v[152:155], v[192:195], v[86:89]
	v_mfma_f32_16x16x32_bf16 v[78:81], v[144:147], v[218:221], v[78:81]
	v_mfma_f32_16x16x32_bf16 v[70:73], v[152:155], v[218:221], v[70:73]
	v_mfma_f32_16x16x32_bf16 v[126:129], v[148:151], v[180:183], v[126:129]
	v_mfma_f32_16x16x32_bf16 v[118:121], v[156:159], v[180:183], v[118:121]
	v_mfma_f32_16x16x32_bf16 v[110:113], v[148:151], v[188:191], v[110:113]
	v_mfma_f32_16x16x32_bf16 v[102:105], v[156:159], v[188:191], v[102:105]
	v_mfma_f32_16x16x32_bf16 v[94:97], v[148:151], v[214:217], v[94:97]
	v_mfma_f32_16x16x32_bf16 v[86:89], v[156:159], v[214:217], v[86:89]
	v_mfma_f32_16x16x32_bf16 v[78:81], v[148:151], v[222:225], v[78:81]
	v_mfma_f32_16x16x32_bf16 v[70:73], v[156:159], v[222:225], v[70:73]
	s_setprio 0
	s_setprio 1
	v_mfma_f32_16x16x32_bf16 v[122:125], v[160:163], v[176:179], v[122:125]
	v_mfma_f32_16x16x32_bf16 v[114:117], v[168:171], v[176:179], v[114:117]
	v_mfma_f32_16x16x32_bf16 v[106:109], v[160:163], v[184:187], v[106:109]
	v_mfma_f32_16x16x32_bf16 v[98:101], v[168:171], v[184:187], v[98:101]
	v_mfma_f32_16x16x32_bf16 v[90:93], v[160:163], v[192:195], v[90:93]
	v_mfma_f32_16x16x32_bf16 v[82:85], v[168:171], v[192:195], v[82:85]
	v_mfma_f32_16x16x32_bf16 v[74:77], v[160:163], v[218:221], v[74:77]
	v_mfma_f32_16x16x32_bf16 v[66:69], v[168:171], v[218:221], v[66:69]
	v_mfma_f32_16x16x32_bf16 v[122:125], v[164:167], v[180:183], v[122:125]
	v_mfma_f32_16x16x32_bf16 v[114:117], v[172:175], v[180:183], v[114:117]
	v_mfma_f32_16x16x32_bf16 v[106:109], v[164:167], v[188:191], v[106:109]
	v_mfma_f32_16x16x32_bf16 v[98:101], v[172:175], v[188:191], v[98:101]
	v_mfma_f32_16x16x32_bf16 v[90:93], v[164:167], v[214:217], v[90:93]
	v_mfma_f32_16x16x32_bf16 v[82:85], v[172:175], v[214:217], v[82:85]
	v_mfma_f32_16x16x32_bf16 v[74:77], v[164:167], v[222:225], v[74:77]
	v_mfma_f32_16x16x32_bf16 v[66:69], v[172:175], v[222:225], v[66:69]
	s_setprio 0
	s_barrier
; #define PG8_STAGE(bufoff, gbase, voff) do { _Pragma("unroll") for (int _i = 0; _i < 2; ++_i) \
;         __builtin_amdgcn_global_load_lds((const unsigned*)((const char*)(gbase) + (voff)[_i]), (LAS unsigned*)(lds + (bufoff) + ldsw + _i * 8192), 16, 0, 0); } while (0)
; #define PG8_LDA(dst, b, h) do { _Pragma("unroll") for (int m = 0; m < 4; ++m) _Pragma("unroll") for (int k = 0; k < 2; ++k) dst[m][k] = *(const LAS f16x8*)(lds + PG8_SA(b, h) + aoff + m * 2048 + k * 1024); } while (0)
; #define PG8_LDB(dst, b, h) do { _Pragma("unroll") for (int n = 0; n < 2; ++n) _Pragma("unroll") for (int k = 0; k < 2; ++k) dst[n][k] = *(const LAS f16x8*)(lds + PG8_SB(b, h) + boff + n * 2048 + k * 1024); } while (0)
; #define PG8_WAIT_V(n) asm volatile("s_waitcnt vmcnt(" #n ")" ::: "memory")
; #define PG8_WAIT_L(n) asm volatile("s_waitcnt lgkmcnt(" #n ")" ::: "memory")
; #define PG8_BAR __builtin_amdgcn_s_barrier()
; #define PG8_SCHED __builtin_amdgcn_sched_barrier(0)
;     ...
;             const char* a1 = cA + (size_t)(t + 1) * kstep;
;             const char* a2 = last ? nA : cA + (size_t)(t + 2) * kstep; const char* b2 = last ? nB : cB + (size_t)(t + 2) * kstep;
;             const char* a3 = a2 + kstep; const char* b3 = b2 + kstep;
;             if constexpr (SP2) {
;             PG8_LDB(B0, 0, 0); PG8_LDB(B1, 0, 1); PG8_SCHED; PG8_LDA(At, 0, 0); PG8_STAGE(PG8_SA(1, 1), a1 + hA, voffA);
;             PG8_WAIT_V(8); PG8_WAIT_L(0); PG8_BAR; PG8_MMA(0, 0, At, B0); PG8_MMA(0, 1, At, B1); PG8_BAR; PG8_SCHED;
;             PG8_LDA(At, 0, 1); PG8_STAGE(PG8_SB(0, 0), b2, voffB); PG8_STAGE(PG8_SB(0, 1), b2 + hB, voffB); PG8_STAGE(PG8_SA(0, 0), a2, voffA);
;             PG8_WAIT_V(8); PG8_WAIT_L(0); PG8_BAR; if (!cur.half) { PG8_MMA(1, 0, At, B0); PG8_MMA(1, 1, At, B1); } PG8_BAR; PG8_SCHED;
;             PG8_LDB(B0, 1, 0); PG8_LDB(B1, 1, 1); PG8_SCHED; PG8_LDA(At, 1, 0); PG8_STAGE(PG8_SA(0, 1), a2 + hA, voffA);
;             PG8_WAIT_V(8); PG8_WAIT_L(0); PG8_BAR; PG8_MMA(0, 0, At, B0); PG8_MMA(0, 1, At, B1); PG8_BAR; PG8_SCHED;
;             PG8_LDA(At, 1, 1); PG8_STAGE(PG8_SB(1, 0), b3, voffB); PG8_STAGE(PG8_SB(1, 1), b3 + hB, voffB); PG8_STAGE(PG8_SA(1, 0), a3, voffA);
;             PG8_WAIT_V(8); PG8_WAIT_L(0); PG8_BAR; if (!cur.half) { PG8_MMA(1, 0, At, B0); PG8_MMA(1, 1, At, B1); } PG8_BAR; PG8_SCHED;
	s_add_i32 s30, s50, s34
	v_lshl_add_u64 v[200:201], v[200:201], 0, s[96:97]
	s_mov_b32 m0, s30
	ds_read_b128 v[176:179], v143 offset:49152
	ds_read_b128 v[180:183], v143 offset:50176
	ds_read_b128 v[184:187], v143 offset:51200
	ds_read_b128 v[188:191], v143 offset:52224
	ds_read_b128 v[192:195], v143 offset:53248
	ds_read_b128 v[214:217], v143 offset:54272
	ds_read_b128 v[218:221], v143 offset:55296
	ds_read_b128 v[222:225], v143 offset:56320
	global_load_lds_dwordx4 v[200:201], off
	s_add_i32 m0, s30, 0x2000
	s_add_u32 s28, s28, 0x40080
	v_lshl_add_u64 v[200:201], v[202:203], 0, s[96:97]
	s_addc_u32 s29, s29, 0
	s_add_i32 s30, s51, s34
	global_load_lds_dwordx4 v[200:201], off
	v_lshl_add_u64 v[200:201], s[28:29], 0, v[0:1]
	s_mov_b32 m0, s30
	s_nop 0
	global_load_lds_dwordx4 v[200:201], off
	v_lshl_add_u64 v[200:201], s[28:29], 0, v[130:131]
	s_add_i32 m0, s30, 0x2000
	s_nop 0
	global_load_lds_dwordx4 v[200:201], off
	v_lshl_add_u64 v[200:201], v[226:227], 0, s[96:97]
	s_mov_b32 m0, s41
	s_nop 0
	global_load_lds_dwordx4 v[200:201], off
	v_lshl_add_u64 v[200:201], v[228:229], 0, s[96:97]
	s_mov_b32 m0, s42
	s_nop 0
	global_load_lds_dwordx4 v[200:201], off
	s_waitcnt vmcnt(8)
	s_waitcnt lgkmcnt(0)
	s_barrier
	s_setprio 1
	v_mfma_f32_16x16x32_bf16 v[62:65], v[144:147], v[176:179], v[62:65]
	v_mfma_f32_16x16x32_bf16 v[54:57], v[152:155], v[176:179], v[54:57]
	v_mfma_f32_16x16x32_bf16 v[46:49], v[144:147], v[184:187], v[46:49]
	v_mfma_f32_16x16x32_bf16 v[38:41], v[152:155], v[184:187], v[38:41]
	v_mfma_f32_16x16x32_bf16 v[30:33], v[144:147], v[192:195], v[30:33]
	v_mfma_f32_16x16x32_bf16 v[22:25], v[152:155], v[192:195], v[22:25]
	v_mfma_f32_16x16x32_bf16 v[14:17], v[144:147], v[218:221], v[14:17]
	v_mfma_f32_16x16x32_bf16 v[6:9], v[152:155], v[218:221], v[6:9]
	v_mfma_f32_16x16x32_bf16 v[62:65], v[148:151], v[180:183], v[62:65]
	v_mfma_f32_16x16x32_bf16 v[54:57], v[156:159], v[180:183], v[54:57]
	v_mfma_f32_16x16x32_bf16 v[46:49], v[148:151], v[188:191], v[46:49]
	v_mfma_f32_16x16x32_bf16 v[38:41], v[156:159], v[188:191], v[38:41]
	v_mfma_f32_16x16x32_bf16 v[30:33], v[148:151], v[214:217], v[30:33]
	v_mfma_f32_16x16x32_bf16 v[22:25], v[156:159], v[214:217], v[22:25]
	v_mfma_f32_16x16x32_bf16 v[14:17], v[148:151], v[222:225], v[14:17]
	v_mfma_f32_16x16x32_bf16 v[6:9], v[156:159], v[222:225], v[6:9]
	s_setprio 0
	s_setprio 1
	v_mfma_f32_16x16x32_bf16 v[58:61], v[160:163], v[176:179], v[58:61]
	v_mfma_f32_16x16x32_bf16 v[50:53], v[168:171], v[176:179], v[50:53]
	v_mfma_f32_16x16x32_bf16 v[42:45], v[160:163], v[184:187], v[42:45]
	v_mfma_f32_16x16x32_bf16 v[34:37], v[168:171], v[184:187], v[34:37]
	v_mfma_f32_16x16x32_bf16 v[26:29], v[160:163], v[192:195], v[26:29]
	v_mfma_f32_16x16x32_bf16 v[18:21], v[168:171], v[192:195], v[18:21]
	v_mfma_f32_16x16x32_bf16 v[10:13], v[160:163], v[218:221], v[10:13]
	v_mfma_f32_16x16x32_bf16 v[2:5], v[168:171], v[218:221], v[2:5]
	v_mfma_f32_16x16x32_bf16 v[58:61], v[164:167], v[180:183], v[58:61]
	v_mfma_f32_16x16x32_bf16 v[50:53], v[172:175], v[180:183], v[50:53]
	v_mfma_f32_16x16x32_bf16 v[42:45], v[164:167], v[188:191], v[42:45]
	v_mfma_f32_16x16x32_bf16 v[34:37], v[172:175], v[188:191], v[34:37]
	v_mfma_f32_16x16x32_bf16 v[26:29], v[164:167], v[214:217], v[26:29]
	v_mfma_f32_16x16x32_bf16 v[18:21], v[172:175], v[214:217], v[18:21]
	v_mfma_f32_16x16x32_bf16 v[10:13], v[164:167], v[222:225], v[10:13]
	v_mfma_f32_16x16x32_bf16 v[2:5], v[172:175], v[222:225], v[2:5]
	s_setprio 0
	s_barrier
	s_add_i32 s49, s49, 2
	s_add_u32 s26, s26, 0x100
	s_addc_u32 s27, s27, 0
	s_add_u32 s47, s47, 0x100
	s_addc_u32 s48, s48, 0
	s_cmp_gt_u32 s49, 13
	s_cbranch_scc0 .LBB0_157
	s_and_b64 vcc, exec, s[8:9]
	s_cbranch_vccz .LBB0_160
	s_barrier

; #define PG8_STAGE(bufoff, gbase, voff) do { _Pragma("unroll") for (int _i = 0; _i < 2; ++_i) \
;         __builtin_amdgcn_global_load_lds((const unsigned*)((const char*)(gbase) + (voff)[_i]), (LAS unsigned*)(lds + (bufoff) + ldsw + _i * 8192), 16, 0, 0); } while (0)
; #define PG8_LDA(dst, b, h) do { _Pragma("unroll") for (int m = 0; m < 4; ++m) _Pragma("unroll") for (int k = 0; k < 2; ++k) dst[m][k] = *(const LAS f16x8*)(lds + PG8_SA(b, h) + aoff + m * 2048 + k * 1024); } while (0)
; #define PG8_LDB(dst, b, h) do { _Pragma("unroll") for (int n = 0; n < 2; ++n) _Pragma("unroll") for (int k = 0; k < 2; ++k) dst[n][k] = *(const LAS f16x8*)(lds + PG8_SB(b, h) + boff + n * 2048 + k * 1024); } while (0)
; #define PG8_MMA(ai, bj, At, Bt) do { __builtin_amdgcn_s_setprio(1); _Pragma("unroll") for (int m = 0; m < 4; ++m) _Pragma("unroll") for (int n = 0; n < 2; ++n) _Pragma("unroll") for (int k = 0; k < 2; ++k) \
;         acc[ai][bj][m][n] = mma16_<Epi::BF16>(Bt[n][k], At[m][k], acc[ai][bj][m][n]); __builtin_amdgcn_s_setprio(0); } while (0)
; #define PG8_WAIT_V(n) asm volatile("s_waitcnt vmcnt(" #n ")" ::: "memory")
; #define PG8_WAIT_L(n) asm volatile("s_waitcnt lgkmcnt(" #n ")" ::: "memory")
; #define PG8_BAR __builtin_amdgcn_s_barrier()
; #define PG8_SCHED __builtin_amdgcn_sched_barrier(0)
;     ...
;             PG8_LDB(B0, 0, 0); PG8_LDB(B1, 0, 1); PG8_SCHED; PG8_LDA(At, 0, 0); PG8_STAGE(PG8_SA(1, 1), a1 + hA, voffA);
;             PG8_WAIT_V(8); PG8_WAIT_L(0); PG8_BAR; PG8_MMA(0, 0, At, B0); PG8_MMA(0, 1, At, B1); PG8_BAR; PG8_SCHED;
;             PG8_LDA(At, 0, 1); PG8_STAGE(PG8_SB(0, 0), b2, voffB); PG8_STAGE(PG8_SB(0, 1), b2 + hB, voffB); PG8_STAGE(PG8_SA(0, 0), a2, voffA);
;             PG8_WAIT_V(8); PG8_WAIT_L(0); PG8_BAR; if (!cur.half) { PG8_MMA(1, 0, At, B0); PG8_MMA(1, 1, At, B1); } PG8_BAR; PG8_SCHED;
.LBB0_242:
	s_mov_b64 s[42:43], s[44:45]
	s_add_u32 s44, s42, 0x100
	s_addc_u32 s45, s43, 0
	s_add_i32 s37, 0, 0x10000
	s_cmp_eq_u32 s14, 40
	s_cselect_b32 s55, s9, s45
	s_cselect_b32 s54, s8, s44
	s_cselect_b32 s53, s11, s3
	s_cselect_b32 s52, s10, s2
	s_add_i32 s78, 0, 0x14000
	v_add_u32_e32 v130, s37, v243
	v_add_u32_e32 v142, s78, v243
	ds_read_b128 v[146:149], v130
	ds_read_b128 v[150:153], v130 offset:1024
	ds_read_b128 v[154:157], v130 offset:2048
	ds_read_b128 v[158:161], v130 offset:3072
	ds_read_b128 v[130:133], v142
	ds_read_b128 v[134:137], v142 offset:1024
	ds_read_b128 v[138:141], v142 offset:2048
	ds_read_b128 v[142:145], v142 offset:3072
	v_lshl_add_u64 v[200:201], s[42:43], 0, v[222:223]
	s_add_i32 m0, s63, 0xc000
	s_waitcnt lgkmcnt(0)
	ds_read_b128 v[162:165], v244
	ds_read_b128 v[166:169], v244 offset:1024
	ds_read_b128 v[170:173], v244 offset:2048
	ds_read_b128 v[174:177], v244 offset:3072
	ds_read_b128 v[178:181], v244 offset:4096
	ds_read_b128 v[182:185], v244 offset:5120
	ds_read_b128 v[186:189], v244 offset:6144
	ds_read_b128 v[190:193], v244 offset:7168
	global_load_lds_dwordx4 v[200:201], off
	v_lshl_add_u64 v[200:201], s[42:43], 0, v[224:225]
	s_add_i32 m0, s63, 0xe000
	s_nop 0
	global_load_lds_dwordx4 v[200:201], off
	s_waitcnt vmcnt(8)
	s_waitcnt lgkmcnt(0)
	s_barrier
	s_setprio 1
	v_mfma_f32_16x16x32_bf16 v[126:129], v[146:149], v[162:165], v[126:129]
	v_mfma_f32_16x16x32_bf16 v[122:125], v[154:157], v[162:165], v[122:125]
	v_mfma_f32_16x16x32_bf16 v[118:121], v[146:149], v[170:173], v[118:121]
	v_mfma_f32_16x16x32_bf16 v[114:117], v[154:157], v[170:173], v[114:117]
	v_mfma_f32_16x16x32_bf16 v[110:113], v[146:149], v[178:181], v[110:113]
	v_mfma_f32_16x16x32_bf16 v[106:109], v[154:157], v[178:181], v[106:109]
	v_mfma_f32_16x16x32_bf16 v[102:105], v[146:149], v[186:189], v[102:105]
	v_mfma_f32_16x16x32_bf16 v[98:101], v[154:157], v[186:189], v[98:101]
	v_mfma_f32_16x16x32_bf16 v[126:129], v[150:153], v[166:169], v[126:129]
	v_mfma_f32_16x16x32_bf16 v[122:125], v[158:161], v[166:169], v[122:125]
	v_mfma_f32_16x16x32_bf16 v[118:121], v[150:153], v[174:177], v[118:121]
	v_mfma_f32_16x16x32_bf16 v[114:117], v[158:161], v[174:177], v[114:117]
	v_mfma_f32_16x16x32_bf16 v[110:113], v[150:153], v[182:185], v[110:113]
	v_mfma_f32_16x16x32_bf16 v[106:109], v[158:161], v[182:185], v[106:109]
	v_mfma_f32_16x16x32_bf16 v[102:105], v[150:153], v[190:193], v[102:105]
	v_mfma_f32_16x16x32_bf16 v[98:101], v[158:161], v[190:193], v[98:101]
	s_setprio 0
	s_setprio 1
	v_mfma_f32_16x16x32_bf16 v[70:73], v[130:133], v[162:165], v[70:73]
	v_mfma_f32_16x16x32_bf16 v[66:69], v[138:141], v[162:165], v[66:69]
	v_mfma_f32_16x16x32_bf16 v[54:57], v[130:133], v[170:173], v[54:57]
	v_mfma_f32_16x16x32_bf16 v[50:53], v[138:141], v[170:173], v[50:53]
	v_mfma_f32_16x16x32_bf16 v[46:49], v[130:133], v[178:181], v[46:49]
	v_mfma_f32_16x16x32_bf16 v[42:45], v[138:141], v[178:181], v[42:45]
	v_mfma_f32_16x16x32_bf16 v[38:41], v[130:133], v[186:189], v[38:41]
	v_mfma_f32_16x16x32_bf16 v[34:37], v[138:141], v[186:189], v[34:37]
	v_mfma_f32_16x16x32_bf16 v[70:73], v[134:137], v[166:169], v[70:73]
	v_mfma_f32_16x16x32_bf16 v[66:69], v[142:145], v[166:169], v[66:69]
	v_mfma_f32_16x16x32_bf16 v[54:57], v[134:137], v[174:177], v[54:57]
	v_mfma_f32_16x16x32_bf16 v[50:53], v[142:145], v[174:177], v[50:53]
	v_mfma_f32_16x16x32_bf16 v[46:49], v[134:137], v[182:185], v[46:49]
	v_mfma_f32_16x16x32_bf16 v[42:45], v[142:145], v[182:185], v[42:45]
	v_mfma_f32_16x16x32_bf16 v[38:41], v[134:137], v[190:193], v[38:41]
	v_mfma_f32_16x16x32_bf16 v[34:37], v[142:145], v[190:193], v[34:37]
	s_setprio 0
	s_barrier
	s_add_i32 s37, s37, s62
	v_lshl_add_u64 v[226:227], s[52:53], 0, v[214:215]
	s_mov_b32 m0, s37
	ds_read_b128 v[186:189], v244 offset:16384
	ds_read_b128 v[190:193], v244 offset:17408
	ds_read_b128 v[178:181], v244 offset:18432
	ds_read_b128 v[182:185], v244 offset:19456
	ds_read_b128 v[170:173], v244 offset:20480
	ds_read_b128 v[174:177], v244 offset:21504
	ds_read_b128 v[162:165], v244 offset:22528
	ds_read_b128 v[166:169], v244 offset:23552
	global_load_lds_dwordx4 v[226:227], off
	s_add_i32 m0, s37, 0x2000
	s_add_u32 s42, s52, 0xb0000
	v_lshl_add_u64 v[228:229], s[52:53], 0, v[218:219]
	s_addc_u32 s43, s53, 0
	s_add_i32 s37, s78, s62
	global_load_lds_dwordx4 v[228:229], off
	v_lshl_add_u64 v[200:201], s[42:43], 0, v[214:215]
	s_mov_b32 m0, s37
	v_lshl_add_u64 v[230:231], s[54:55], 0, v[194:195]
	global_load_lds_dwordx4 v[200:201], off
	v_lshl_add_u64 v[200:201], s[42:43], 0, v[218:219]
	s_add_i32 m0, s37, 0x2000
	v_lshl_add_u64 v[232:233], s[54:55], 0, v[216:217]
	global_load_lds_dwordx4 v[200:201], off
	s_mov_b32 m0, s63
	v_cndmask_b32_e64 v200, 0, 1, s[50:51]
	global_load_lds_dwordx4 v[230:231], off
	s_mov_b32 m0, s64
	v_cmp_ne_u32_e64 s[42:43], 1, v200
	global_load_lds_dwordx4 v[232:233], off
	s_waitcnt vmcnt(8)
	s_waitcnt lgkmcnt(0)
	s_andn2_b64 vcc, exec, s[50:51]
	s_barrier
	s_cbranch_vccnz .LBB0_244
; #define PG8_MMA(ai, bj, At, Bt) do { __builtin_amdgcn_s_setprio(1); _Pragma("unroll") for (int m = 0; m < 4; ++m) _Pragma("unroll") for (int n = 0; n < 2; ++n) _Pragma("unroll") for (int k = 0; k < 2; ++k) \
;         acc[ai][bj][m][n] = mma16_<Epi::BF16>(Bt[n][k], At[m][k], acc[ai][bj][m][n]); __builtin_amdgcn_s_setprio(0); } while (0)
; #define PG8_WAIT_V(n) asm volatile("s_waitcnt vmcnt(" #n ")" ::: "memory")
; #define PG8_WAIT_L(n) asm volatile("s_waitcnt lgkmcnt(" #n ")" ::: "memory")
; #define PG8_BAR __builtin_amdgcn_s_barrier()
; #define PG8_SCHED __builtin_amdgcn_sched_barrier(0)
;     ...
;             PG8_WAIT_V(8); PG8_WAIT_L(0); PG8_BAR; if (!cur.half) { PG8_MMA(1, 0, At, B0); PG8_MMA(1, 1, At, B1); } PG8_BAR; PG8_SCHED;
	s_setprio 1
	v_mfma_f32_16x16x32_bf16 v[94:97], v[146:149], v[186:189], v[94:97]
	v_mfma_f32_16x16x32_bf16 v[90:93], v[154:157], v[186:189], v[90:93]
	v_mfma_f32_16x16x32_bf16 v[86:89], v[146:149], v[178:181], v[86:89]
	v_mfma_f32_16x16x32_bf16 v[82:85], v[154:157], v[178:181], v[82:85]
	v_mfma_f32_16x16x32_bf16 v[78:81], v[146:149], v[170:173], v[78:81]
	v_mfma_f32_16x16x32_bf16 v[74:77], v[154:157], v[170:173], v[74:77]
	v_mfma_f32_16x16x32_bf16 v[62:65], v[146:149], v[162:165], v[62:65]
	v_mfma_f32_16x16x32_bf16 v[58:61], v[154:157], v[162:165], v[58:61]
	v_mfma_f32_16x16x32_bf16 v[94:97], v[150:153], v[190:193], v[94:97]
	v_mfma_f32_16x16x32_bf16 v[90:93], v[158:161], v[190:193], v[90:93]
	v_mfma_f32_16x16x32_bf16 v[86:89], v[150:153], v[182:185], v[86:89]
	v_mfma_f32_16x16x32_bf16 v[82:85], v[158:161], v[182:185], v[82:85]
	v_mfma_f32_16x16x32_bf16 v[78:81], v[150:153], v[174:177], v[78:81]
	v_mfma_f32_16x16x32_bf16 v[74:77], v[158:161], v[174:177], v[74:77]
	v_mfma_f32_16x16x32_bf16 v[62:65], v[150:153], v[166:169], v[62:65]
	v_mfma_f32_16x16x32_bf16 v[58:61], v[158:161], v[166:169], v[58:61]
	s_setprio 0
	s_setprio 1
	v_mfma_f32_16x16x32_bf16 v[30:33], v[130:133], v[186:189], v[30:33]
	v_mfma_f32_16x16x32_bf16 v[26:29], v[138:141], v[186:189], v[26:29]
	v_mfma_f32_16x16x32_bf16 v[22:25], v[130:133], v[178:181], v[22:25]
	v_mfma_f32_16x16x32_bf16 v[18:21], v[138:141], v[178:181], v[18:21]
	v_mfma_f32_16x16x32_bf16 v[14:17], v[130:133], v[170:173], v[14:17]
	v_mfma_f32_16x16x32_bf16 v[10:13], v[138:141], v[170:173], v[10:13]
	v_mfma_f32_16x16x32_bf16 v[6:9], v[130:133], v[162:165], v[6:9]
	v_mfma_f32_16x16x32_bf16 v[2:5], v[138:141], v[162:165], v[2:5]
	v_mfma_f32_16x16x32_bf16 v[30:33], v[134:137], v[190:193], v[30:33]
	v_mfma_f32_16x16x32_bf16 v[26:29], v[142:145], v[190:193], v[26:29]
	v_mfma_f32_16x16x32_bf16 v[22:25], v[134:137], v[182:185], v[22:25]
	v_mfma_f32_16x16x32_bf16 v[18:21], v[142:145], v[182:185], v[18:21]
	v_mfma_f32_16x16x32_bf16 v[14:17], v[134:137], v[174:177], v[14:17]
	v_mfma_f32_16x16x32_bf16 v[10:13], v[142:145], v[174:177], v[10:13]
	v_mfma_f32_16x16x32_bf16 v[6:9], v[134:137], v[166:169], v[6:9]
	v_mfma_f32_16x16x32_bf16 v[2:5], v[142:145], v[166:169], v[2:5]
	s_setprio 0
; #define PG8_STAGE(bufoff, gbase, voff) do { _Pragma("unroll") for (int _i = 0; _i < 2; ++_i) \
;         __builtin_amdgcn_global_load_lds((const unsigned*)((const char*)(gbase) + (voff)[_i]), (LAS unsigned*)(lds + (bufoff) + ldsw + _i * 8192), 16, 0, 0); } while (0)
; #define PG8_LDA(dst, b, h) do { _Pragma("unroll") for (int m = 0; m < 4; ++m) _Pragma("unroll") for (int k = 0; k < 2; ++k) dst[m][k] = *(const LAS f16x8*)(lds + PG8_SA(b, h) + aoff + m * 2048 + k * 1024); } while (0)
; #define PG8_LDB(dst, b, h) do { _Pragma("unroll") for (int n = 0; n < 2; ++n) _Pragma("unroll") for (int k = 0; k < 2; ++k) dst[n][k] = *(const LAS f16x8*)(lds + PG8_SB(b, h) + boff + n * 2048 + k * 1024); } while (0)
; #define PG8_MMA(ai, bj, At, Bt) do { __builtin_amdgcn_s_setprio(1); _Pragma("unroll") for (int m = 0; m < 4; ++m) _Pragma("unroll") for (int n = 0; n < 2; ++n) _Pragma("unroll") for (int k = 0; k < 2; ++k) \
;         acc[ai][bj][m][n] = mma16_<Epi::BF16>(Bt[n][k], At[m][k], acc[ai][bj][m][n]); __builtin_amdgcn_s_setprio(0); } while (0)
; #define PG8_WAIT_V(n) asm volatile("s_waitcnt vmcnt(" #n ")" ::: "memory")
; #define PG8_WAIT_L(n) asm volatile("s_waitcnt lgkmcnt(" #n ")" ::: "memory")
; #define PG8_BAR __builtin_amdgcn_s_barrier()
; #define PG8_SCHED __builtin_amdgcn_sched_barrier(0)
;     ...
;             PG8_WAIT_V(8); PG8_WAIT_L(0); PG8_BAR; if (!cur.half) { PG8_MMA(1, 0, At, B0); PG8_MMA(1, 1, At, B1); } PG8_BAR; PG8_SCHED;
;             PG8_LDB(B0, 1, 0); PG8_LDB(B1, 1, 1); PG8_SCHED; PG8_LDA(At, 1, 0); PG8_STAGE(PG8_SA(0, 1), a2 + hA, voffA);
;             PG8_WAIT_V(8); PG8_WAIT_L(0); PG8_BAR; PG8_MMA(0, 0, At, B0); PG8_MMA(0, 1, At, B1); PG8_BAR; PG8_SCHED;
;             PG8_LDA(At, 1, 1); PG8_STAGE(PG8_SB(1, 0), b3, voffB); PG8_STAGE(PG8_SB(1, 1), b3 + hB, voffB); PG8_STAGE(PG8_SA(1, 0), a3, voffA);
;             PG8_WAIT_V(8); PG8_WAIT_L(0); PG8_BAR; if (!cur.half) { PG8_MMA(1, 0, At, B0); PG8_MMA(1, 1, At, B1); } PG8_BAR; PG8_SCHED;
.LBB0_244:
	s_barrier
	s_add_i32 s37, 0, 0x18000
	s_add_i32 s78, 0, 0x1c000
	v_add_u32_e32 v130, s37, v243
	v_add_u32_e32 v142, s78, v243
	ds_read_b128 v[146:149], v130
	ds_read_b128 v[150:153], v130 offset:1024
	ds_read_b128 v[154:157], v130 offset:2048
	ds_read_b128 v[158:161], v130 offset:3072
	ds_read_b128 v[130:133], v142
	ds_read_b128 v[134:137], v142 offset:1024
	ds_read_b128 v[138:141], v142 offset:2048
	ds_read_b128 v[142:145], v142 offset:3072
	s_add_u32 s54, s54, 0xb0000
	s_addc_u32 s55, s55, 0
	s_mov_b32 m0, s65
	v_lshl_add_u64 v[200:201], s[54:55], 0, v[194:195]
	s_waitcnt lgkmcnt(0)
	ds_read_b128 v[162:165], v244 offset:32768
	ds_read_b128 v[166:169], v244 offset:33792
	ds_read_b128 v[170:173], v244 offset:34816
	ds_read_b128 v[174:177], v244 offset:35840
	ds_read_b128 v[178:181], v244 offset:36864
	ds_read_b128 v[182:185], v244 offset:37888
	ds_read_b128 v[186:189], v244 offset:38912
	ds_read_b128 v[190:193], v244 offset:39936
	global_load_lds_dwordx4 v[200:201], off
	v_lshl_add_u64 v[200:201], s[54:55], 0, v[216:217]
	s_mov_b32 m0, s66
	s_nop 0
	global_load_lds_dwordx4 v[200:201], off
	s_waitcnt vmcnt(8)
	s_waitcnt lgkmcnt(0)
	s_barrier
	s_setprio 1
	v_mfma_f32_16x16x32_bf16 v[126:129], v[146:149], v[162:165], v[126:129]
	v_mfma_f32_16x16x32_bf16 v[122:125], v[154:157], v[162:165], v[122:125]
	v_mfma_f32_16x16x32_bf16 v[118:121], v[146:149], v[170:173], v[118:121]
	v_mfma_f32_16x16x32_bf16 v[114:117], v[154:157], v[170:173], v[114:117]
	v_mfma_f32_16x16x32_bf16 v[110:113], v[146:149], v[178:181], v[110:113]
	v_mfma_f32_16x16x32_bf16 v[106:109], v[154:157], v[178:181], v[106:109]
	v_mfma_f32_16x16x32_bf16 v[102:105], v[146:149], v[186:189], v[102:105]
	v_mfma_f32_16x16x32_bf16 v[98:101], v[154:157], v[186:189], v[98:101]
	v_mfma_f32_16x16x32_bf16 v[126:129], v[150:153], v[166:169], v[126:129]
	v_mfma_f32_16x16x32_bf16 v[122:125], v[158:161], v[166:169], v[122:125]
	v_mfma_f32_16x16x32_bf16 v[118:121], v[150:153], v[174:177], v[118:121]
	v_mfma_f32_16x16x32_bf16 v[114:117], v[158:161], v[174:177], v[114:117]
	v_mfma_f32_16x16x32_bf16 v[110:113], v[150:153], v[182:185], v[110:113]
	v_mfma_f32_16x16x32_bf16 v[106:109], v[158:161], v[182:185], v[106:109]
	v_mfma_f32_16x16x32_bf16 v[102:105], v[150:153], v[190:193], v[102:105]
	v_mfma_f32_16x16x32_bf16 v[98:101], v[158:161], v[190:193], v[98:101]
	s_setprio 0
	s_setprio 1
	v_mfma_f32_16x16x32_bf16 v[70:73], v[130:133], v[162:165], v[70:73]
	v_mfma_f32_16x16x32_bf16 v[66:69], v[138:141], v[162:165], v[66:69]
	v_mfma_f32_16x16x32_bf16 v[54:57], v[130:133], v[170:173], v[54:57]
	v_mfma_f32_16x16x32_bf16 v[50:53], v[138:141], v[170:173], v[50:53]
	v_mfma_f32_16x16x32_bf16 v[46:49], v[130:133], v[178:181], v[46:49]
	v_mfma_f32_16x16x32_bf16 v[42:45], v[138:141], v[178:181], v[42:45]
	v_mfma_f32_16x16x32_bf16 v[38:41], v[130:133], v[186:189], v[38:41]
	v_mfma_f32_16x16x32_bf16 v[34:37], v[138:141], v[186:189], v[34:37]
	v_mfma_f32_16x16x32_bf16 v[70:73], v[134:137], v[166:169], v[70:73]
	v_mfma_f32_16x16x32_bf16 v[66:69], v[142:145], v[166:169], v[66:69]
	v_mfma_f32_16x16x32_bf16 v[54:57], v[134:137], v[174:177], v[54:57]
	v_mfma_f32_16x16x32_bf16 v[50:53], v[142:145], v[174:177], v[50:53]
	v_mfma_f32_16x16x32_bf16 v[46:49], v[134:137], v[182:185], v[46:49]
	v_mfma_f32_16x16x32_bf16 v[42:45], v[142:145], v[182:185], v[42:45]
	v_mfma_f32_16x16x32_bf16 v[38:41], v[134:137], v[190:193], v[38:41]
	v_mfma_f32_16x16x32_bf16 v[34:37], v[142:145], v[190:193], v[34:37]
	s_setprio 0
	s_barrier
	s_add_i32 s37, s37, s62
	v_lshl_add_u64 v[200:201], v[226:227], 0, s[96:97]
	s_mov_b32 m0, s37
	ds_read_b128 v[186:189], v244 offset:49152
	ds_read_b128 v[190:193], v244 offset:50176
	ds_read_b128 v[178:181], v244 offset:51200
	ds_read_b128 v[182:185], v244 offset:52224
	ds_read_b128 v[170:173], v244 offset:53248
	ds_read_b128 v[174:177], v244 offset:54272
	ds_read_b128 v[162:165], v244 offset:55296
	ds_read_b128 v[166:169], v244 offset:56320
	global_load_lds_dwordx4 v[200:201], off
	s_add_i32 m0, s37, 0x2000
	s_add_u32 s52, s52, 0xb0080
	v_lshl_add_u64 v[200:201], v[228:229], 0, s[96:97]
	s_addc_u32 s53, s53, 0
	s_add_i32 s37, s78, s62
	global_load_lds_dwordx4 v[200:201], off
	v_lshl_add_u64 v[200:201], s[52:53], 0, v[214:215]
	s_mov_b32 m0, s37
	s_and_b64 vcc, exec, s[42:43]
	global_load_lds_dwordx4 v[200:201], off
	v_lshl_add_u64 v[200:201], s[52:53], 0, v[218:219]
	s_add_i32 m0, s37, 0x2000
	s_nop 0
	global_load_lds_dwordx4 v[200:201], off
	v_lshl_add_u64 v[200:201], v[230:231], 0, s[96:97]
	s_mov_b32 m0, s0
	s_nop 0
	global_load_lds_dwordx4 v[200:201], off
	v_lshl_add_u64 v[200:201], v[232:233], 0, s[96:97]
	s_mov_b32 m0, s69
	s_nop 0
	global_load_lds_dwordx4 v[200:201], off
	s_waitcnt vmcnt(8)
	s_waitcnt lgkmcnt(0)
	s_barrier
	s_cbranch_vccnz .LBB0_241
	s_setprio 1
	v_mfma_f32_16x16x32_bf16 v[94:97], v[146:149], v[186:189], v[94:97]
	v_mfma_f32_16x16x32_bf16 v[90:93], v[154:157], v[186:189], v[90:93]
	v_mfma_f32_16x16x32_bf16 v[86:89], v[146:149], v[178:181], v[86:89]
	v_mfma_f32_16x16x32_bf16 v[82:85], v[154:157], v[178:181], v[82:85]
	v_mfma_f32_16x16x32_bf16 v[78:81], v[146:149], v[170:173], v[78:81]
	v_mfma_f32_16x16x32_bf16 v[74:77], v[154:157], v[170:173], v[74:77]
	v_mfma_f32_16x16x32_bf16 v[62:65], v[146:149], v[162:165], v[62:65]
	v_mfma_f32_16x16x32_bf16 v[58:61], v[154:157], v[162:165], v[58:61]
	v_mfma_f32_16x16x32_bf16 v[94:97], v[150:153], v[190:193], v[94:97]
	v_mfma_f32_16x16x32_bf16 v[90:93], v[158:161], v[190:193], v[90:93]
	v_mfma_f32_16x16x32_bf16 v[86:89], v[150:153], v[182:185], v[86:89]
	v_mfma_f32_16x16x32_bf16 v[82:85], v[158:161], v[182:185], v[82:85]
	v_mfma_f32_16x16x32_bf16 v[78:81], v[150:153], v[174:177], v[78:81]
	v_mfma_f32_16x16x32_bf16 v[74:77], v[158:161], v[174:177], v[74:77]
	v_mfma_f32_16x16x32_bf16 v[62:65], v[150:153], v[166:169], v[62:65]
	v_mfma_f32_16x16x32_bf16 v[58:61], v[158:161], v[166:169], v[58:61]
	s_setprio 0
	s_setprio 1
	v_mfma_f32_16x16x32_bf16 v[30:33], v[130:133], v[186:189], v[30:33]
	v_mfma_f32_16x16x32_bf16 v[26:29], v[138:141], v[186:189], v[26:29]
	v_mfma_f32_16x16x32_bf16 v[22:25], v[130:133], v[178:181], v[22:25]
	v_mfma_f32_16x16x32_bf16 v[18:21], v[138:141], v[178:181], v[18:21]
	v_mfma_f32_16x16x32_bf16 v[14:17], v[130:133], v[170:173], v[14:17]
	v_mfma_f32_16x16x32_bf16 v[10:13], v[138:141], v[170:173], v[10:13]
	v_mfma_f32_16x16x32_bf16 v[6:9], v[130:133], v[162:165], v[6:9]
	v_mfma_f32_16x16x32_bf16 v[2:5], v[138:141], v[162:165], v[2:5]
	v_mfma_f32_16x16x32_bf16 v[30:33], v[134:137], v[190:193], v[30:33]
	v_mfma_f32_16x16x32_bf16 v[26:29], v[142:145], v[190:193], v[26:29]
	v_mfma_f32_16x16x32_bf16 v[22:25], v[134:137], v[182:185], v[22:25]
	v_mfma_f32_16x16x32_bf16 v[18:21], v[142:145], v[182:185], v[18:21]
	v_mfma_f32_16x16x32_bf16 v[14:17], v[134:137], v[174:177], v[14:17]
	v_mfma_f32_16x16x32_bf16 v[10:13], v[142:145], v[174:177], v[10:13]
	v_mfma_f32_16x16x32_bf16 v[6:9], v[134:137], v[166:169], v[6:9]
	v_mfma_f32_16x16x32_bf16 v[2:5], v[142:145], v[166:169], v[2:5]
	s_setprio 0
	s_branch .LBB0_241

; #define PG8_STAGE(bufoff, gbase, voff) do { _Pragma("unroll") for (int _i = 0; _i < 2; ++_i) \
;         __builtin_amdgcn_global_load_lds((const unsigned*)((const char*)(gbase) + (voff)[_i]), (LAS unsigned*)(lds + (bufoff) + ldsw + _i * 8192), 16, 0, 0); } while (0)
; #define PG8_LDA(dst, b, h) do { _Pragma("unroll") for (int m = 0; m < 4; ++m) _Pragma("unroll") for (int k = 0; k < 2; ++k) dst[m][k] = *(const LAS f16x8*)(lds + PG8_SA(b, h) + aoff + m * 2048 + k * 1024); } while (0)
; #define PG8_LDB(dst, b, h) do { _Pragma("unroll") for (int n = 0; n < 2; ++n) _Pragma("unroll") for (int k = 0; k < 2; ++k) dst[n][k] = *(const LAS f16x8*)(lds + PG8_SB(b, h) + boff + n * 2048 + k * 1024); } while (0)
; #define PG8_MMA(ai, bj, At, Bt) do { __builtin_amdgcn_s_setprio(1); _Pragma("unroll") for (int m = 0; m < 4; ++m) _Pragma("unroll") for (int n = 0; n < 2; ++n) _Pragma("unroll") for (int k = 0; k < 2; ++k) \
;         acc[ai][bj][m][n] = mma16_<Epi::BF16>(Bt[n][k], At[m][k], acc[ai][bj][m][n]); __builtin_amdgcn_s_setprio(0); } while (0)
; #define PG8_WAIT_V(n) asm volatile("s_waitcnt vmcnt(" #n ")" ::: "memory")
; #define PG8_WAIT_L(n) asm volatile("s_waitcnt lgkmcnt(" #n ")" ::: "memory")
; #define PG8_BAR __builtin_amdgcn_s_barrier()
; #define PG8_SCHED __builtin_amdgcn_sched_barrier(0)
;     ...
;             PG8_LDB(B0, 0, 0); PG8_LDB(B1, 0, 1); PG8_SCHED; PG8_LDA(At, 0, 0); PG8_STAGE(PG8_SA(1, 1), a1 + hA, voffA);
;             PG8_WAIT_V(8); PG8_WAIT_L(0); PG8_BAR; PG8_MMA(0, 0, At, B0); PG8_MMA(0, 1, At, B1); PG8_BAR; PG8_SCHED;
;             PG8_LDA(At, 0, 1); PG8_STAGE(PG8_SB(0, 0), b2, voffB); PG8_STAGE(PG8_SB(0, 1), b2 + hB, voffB); PG8_STAGE(PG8_SA(0, 0), a2, voffA);
;             PG8_WAIT_V(8); PG8_WAIT_L(0); PG8_BAR; if (!cur.half) { PG8_MMA(1, 0, At, B0); PG8_MMA(1, 1, At, B1); } PG8_BAR; PG8_SCHED;
.LBB0_516:
	s_add_u32 s28, s26, 0xfffc0080
	s_addc_u32 s29, s27, -1
	s_add_i32 s50, 0, 0x10000
	s_cmp_eq_u32 s49, 12
	s_cselect_b32 s31, s2, s29
	s_cselect_b32 s30, s3, s28
	v_add_u32_e32 v142, s50, v145
	s_cselect_b32 s29, s19, s48
	s_cselect_b32 s28, s21, s47
	s_add_i32 s52, 0, 0x14000
	ds_read_b128 v[148:151], v142
	ds_read_b128 v[152:155], v142 offset:1024
	ds_read_b128 v[156:159], v142 offset:2048
	ds_read_b128 v[160:163], v142 offset:3072
	v_add_u32_e32 v142, s52, v145
	ds_read_b128 v[164:167], v142
	ds_read_b128 v[168:171], v142 offset:1024
	ds_read_b128 v[172:175], v142 offset:2048
	ds_read_b128 v[176:179], v142 offset:3072
	v_lshl_add_u64 v[142:143], s[26:27], 0, v[138:139]
	s_add_i32 m0, s17, 0xc000
	ds_read_b128 v[180:183], v147
	ds_read_b128 v[184:187], v147 offset:1024
	ds_read_b128 v[188:191], v147 offset:2048
	ds_read_b128 v[192:195], v147 offset:3072
	ds_read_b128 v[214:217], v147 offset:4096
	ds_read_b128 v[218:221], v147 offset:5120
	ds_read_b128 v[222:225], v147 offset:6144
	ds_read_b128 v[226:229], v147 offset:7168
	global_load_lds_dwordx4 v[142:143], off
	v_lshl_add_u64 v[142:143], s[26:27], 0, v[140:141]
	s_add_i32 m0, s17, 0xe000
	s_nop 0
	global_load_lds_dwordx4 v[142:143], off
	s_waitcnt vmcnt(8)
	s_waitcnt lgkmcnt(0)
	s_barrier
	s_setprio 1
	v_mfma_f32_16x16x32_bf16 v[126:129], v[148:151], v[180:183], v[126:129]
	v_mfma_f32_16x16x32_bf16 v[122:125], v[156:159], v[180:183], v[122:125]
	v_mfma_f32_16x16x32_bf16 v[118:121], v[148:151], v[188:191], v[118:121]
	v_mfma_f32_16x16x32_bf16 v[114:117], v[156:159], v[188:191], v[114:117]
	v_mfma_f32_16x16x32_bf16 v[102:105], v[148:151], v[214:217], v[102:105]
	v_mfma_f32_16x16x32_bf16 v[98:101], v[156:159], v[214:217], v[98:101]
	v_mfma_f32_16x16x32_bf16 v[86:89], v[148:151], v[222:225], v[86:89]
	v_mfma_f32_16x16x32_bf16 v[82:85], v[156:159], v[222:225], v[82:85]
	v_mfma_f32_16x16x32_bf16 v[126:129], v[152:155], v[184:187], v[126:129]
	v_mfma_f32_16x16x32_bf16 v[122:125], v[160:163], v[184:187], v[122:125]
	v_mfma_f32_16x16x32_bf16 v[118:121], v[152:155], v[192:195], v[118:121]
	v_mfma_f32_16x16x32_bf16 v[114:117], v[160:163], v[192:195], v[114:117]
	v_mfma_f32_16x16x32_bf16 v[102:105], v[152:155], v[218:221], v[102:105]
	v_mfma_f32_16x16x32_bf16 v[98:101], v[160:163], v[218:221], v[98:101]
	v_mfma_f32_16x16x32_bf16 v[86:89], v[152:155], v[226:229], v[86:89]
	v_mfma_f32_16x16x32_bf16 v[82:85], v[160:163], v[226:229], v[82:85]
	s_setprio 0
	s_setprio 1
	v_mfma_f32_16x16x32_bf16 v[110:113], v[164:167], v[180:183], v[110:113]
	v_mfma_f32_16x16x32_bf16 v[106:109], v[172:175], v[180:183], v[106:109]
	v_mfma_f32_16x16x32_bf16 v[94:97], v[164:167], v[188:191], v[94:97]
	v_mfma_f32_16x16x32_bf16 v[90:93], v[172:175], v[188:191], v[90:93]
	v_mfma_f32_16x16x32_bf16 v[78:81], v[164:167], v[214:217], v[78:81]
	v_mfma_f32_16x16x32_bf16 v[74:77], v[172:175], v[214:217], v[74:77]
	v_mfma_f32_16x16x32_bf16 v[70:73], v[164:167], v[222:225], v[70:73]
	v_mfma_f32_16x16x32_bf16 v[66:69], v[172:175], v[222:225], v[66:69]
	v_mfma_f32_16x16x32_bf16 v[110:113], v[168:171], v[184:187], v[110:113]
	v_mfma_f32_16x16x32_bf16 v[106:109], v[176:179], v[184:187], v[106:109]
	v_mfma_f32_16x16x32_bf16 v[94:97], v[168:171], v[192:195], v[94:97]
	v_mfma_f32_16x16x32_bf16 v[90:93], v[176:179], v[192:195], v[90:93]
	v_mfma_f32_16x16x32_bf16 v[78:81], v[168:171], v[218:221], v[78:81]
	v_mfma_f32_16x16x32_bf16 v[74:77], v[176:179], v[218:221], v[74:77]
	v_mfma_f32_16x16x32_bf16 v[70:73], v[168:171], v[226:229], v[70:73]
	v_mfma_f32_16x16x32_bf16 v[66:69], v[176:179], v[226:229], v[66:69]
	s_setprio 0
	s_barrier
	s_add_i32 s50, s50, s34
	v_lshl_add_u64 v[142:143], s[28:29], 0, v[0:1]
	s_mov_b32 m0, s50
	ds_read_b128 v[180:183], v147 offset:16384
	ds_read_b128 v[184:187], v147 offset:17408
	ds_read_b128 v[188:191], v147 offset:18432
	ds_read_b128 v[192:195], v147 offset:19456
	ds_read_b128 v[214:217], v147 offset:20480
	ds_read_b128 v[218:221], v147 offset:21504
	ds_read_b128 v[222:225], v147 offset:22528
	ds_read_b128 v[226:229], v147 offset:23552
	global_load_lds_dwordx4 v[142:143], off
	s_add_i32 m0, s50, 0x2000
	s_add_u32 s50, s28, 0x40000
	v_lshl_add_u64 v[200:201], s[28:29], 0, v[130:131]
	s_addc_u32 s51, s29, 0
	s_add_i32 s52, s52, s34
	global_load_lds_dwordx4 v[200:201], off
	v_lshl_add_u64 v[202:203], s[50:51], 0, v[0:1]
	s_mov_b32 m0, s52
	v_lshl_add_u64 v[230:231], s[30:31], 0, v[132:133]
	global_load_lds_dwordx4 v[202:203], off
	v_lshl_add_u64 v[202:203], s[50:51], 0, v[130:131]
	s_add_i32 m0, s52, 0x2000
	s_nop 0
	global_load_lds_dwordx4 v[202:203], off
	v_lshl_add_u64 v[202:203], s[30:31], 0, v[134:135]
	s_mov_b32 m0, s17
	s_nop 0
	global_load_lds_dwordx4 v[202:203], off
	s_mov_b32 m0, s36
	s_nop 0
	global_load_lds_dwordx4 v[230:231], off
	s_waitcnt vmcnt(8)
	s_waitcnt lgkmcnt(0)
	s_barrier
; #define PG8_STAGE(bufoff, gbase, voff) do { _Pragma("unroll") for (int _i = 0; _i < 2; ++_i) \
;         __builtin_amdgcn_global_load_lds((const unsigned*)((const char*)(gbase) + (voff)[_i]), (LAS unsigned*)(lds + (bufoff) + ldsw + _i * 8192), 16, 0, 0); } while (0)
; #define PG8_LDA(dst, b, h) do { _Pragma("unroll") for (int m = 0; m < 4; ++m) _Pragma("unroll") for (int k = 0; k < 2; ++k) dst[m][k] = *(const LAS f16x8*)(lds + PG8_SA(b, h) + aoff + m * 2048 + k * 1024); } while (0)
; #define PG8_LDB(dst, b, h) do { _Pragma("unroll") for (int n = 0; n < 2; ++n) _Pragma("unroll") for (int k = 0; k < 2; ++k) dst[n][k] = *(const LAS f16x8*)(lds + PG8_SB(b, h) + boff + n * 2048 + k * 1024); } while (0)
; #define PG8_MMA(ai, bj, At, Bt) do { __builtin_amdgcn_s_setprio(1); _Pragma("unroll") for (int m = 0; m < 4; ++m) _Pragma("unroll") for (int n = 0; n < 2; ++n) _Pragma("unroll") for (int k = 0; k < 2; ++k) \
;         acc[ai][bj][m][n] = mma16_<Epi::BF16>(Bt[n][k], At[m][k], acc[ai][bj][m][n]); __builtin_amdgcn_s_setprio(0); } while (0)
; #define PG8_WAIT_V(n) asm volatile("s_waitcnt vmcnt(" #n ")" ::: "memory")
; #define PG8_WAIT_L(n) asm volatile("s_waitcnt lgkmcnt(" #n ")" ::: "memory")
; #define PG8_BAR __builtin_amdgcn_s_barrier()
; #define PG8_SCHED __builtin_amdgcn_sched_barrier(0)
;     ...
;             PG8_WAIT_V(8); PG8_WAIT_L(0); PG8_BAR; if (!cur.half) { PG8_MMA(1, 0, At, B0); PG8_MMA(1, 1, At, B1); } PG8_BAR; PG8_SCHED;
;             PG8_LDB(B0, 1, 0); PG8_LDB(B1, 1, 1); PG8_SCHED; PG8_LDA(At, 1, 0); PG8_STAGE(PG8_SA(0, 1), a2 + hA, voffA);
;             PG8_WAIT_V(8); PG8_WAIT_L(0); PG8_BAR; PG8_MMA(0, 0, At, B0); PG8_MMA(0, 1, At, B1); PG8_BAR; PG8_SCHED;
	s_setprio 1
	v_mfma_f32_16x16x32_bf16 v[62:65], v[148:151], v[180:183], v[62:65]
	v_mfma_f32_16x16x32_bf16 v[58:61], v[156:159], v[180:183], v[58:61]
	v_mfma_f32_16x16x32_bf16 v[54:57], v[148:151], v[188:191], v[54:57]
	v_mfma_f32_16x16x32_bf16 v[50:53], v[156:159], v[188:191], v[50:53]
	v_mfma_f32_16x16x32_bf16 v[38:41], v[148:151], v[214:217], v[38:41]
	v_mfma_f32_16x16x32_bf16 v[34:37], v[156:159], v[214:217], v[34:37]
	v_mfma_f32_16x16x32_bf16 v[22:25], v[148:151], v[222:225], v[22:25]
	v_mfma_f32_16x16x32_bf16 v[18:21], v[156:159], v[222:225], v[18:21]
	v_mfma_f32_16x16x32_bf16 v[62:65], v[152:155], v[184:187], v[62:65]
	v_mfma_f32_16x16x32_bf16 v[58:61], v[160:163], v[184:187], v[58:61]
	v_mfma_f32_16x16x32_bf16 v[54:57], v[152:155], v[192:195], v[54:57]
	v_mfma_f32_16x16x32_bf16 v[50:53], v[160:163], v[192:195], v[50:53]
	v_mfma_f32_16x16x32_bf16 v[38:41], v[152:155], v[218:221], v[38:41]
	v_mfma_f32_16x16x32_bf16 v[34:37], v[160:163], v[218:221], v[34:37]
	v_mfma_f32_16x16x32_bf16 v[22:25], v[152:155], v[226:229], v[22:25]
	v_mfma_f32_16x16x32_bf16 v[18:21], v[160:163], v[226:229], v[18:21]
	s_setprio 0
	s_setprio 1
	v_mfma_f32_16x16x32_bf16 v[46:49], v[164:167], v[180:183], v[46:49]
	v_mfma_f32_16x16x32_bf16 v[42:45], v[172:175], v[180:183], v[42:45]
	v_mfma_f32_16x16x32_bf16 v[30:33], v[164:167], v[188:191], v[30:33]
	v_mfma_f32_16x16x32_bf16 v[26:29], v[172:175], v[188:191], v[26:29]
	v_mfma_f32_16x16x32_bf16 v[14:17], v[164:167], v[214:217], v[14:17]
	v_mfma_f32_16x16x32_bf16 v[10:13], v[172:175], v[214:217], v[10:13]
	v_mfma_f32_16x16x32_bf16 v[6:9], v[164:167], v[222:225], v[6:9]
	v_mfma_f32_16x16x32_bf16 v[2:5], v[172:175], v[222:225], v[2:5]
	v_mfma_f32_16x16x32_bf16 v[46:49], v[168:171], v[184:187], v[46:49]
	v_mfma_f32_16x16x32_bf16 v[42:45], v[176:179], v[184:187], v[42:45]
	v_mfma_f32_16x16x32_bf16 v[30:33], v[168:171], v[192:195], v[30:33]
	v_mfma_f32_16x16x32_bf16 v[26:29], v[176:179], v[192:195], v[26:29]
	v_mfma_f32_16x16x32_bf16 v[14:17], v[168:171], v[218:221], v[14:17]
	v_mfma_f32_16x16x32_bf16 v[10:13], v[176:179], v[218:221], v[10:13]
	v_mfma_f32_16x16x32_bf16 v[6:9], v[168:171], v[226:229], v[6:9]
	v_mfma_f32_16x16x32_bf16 v[2:5], v[176:179], v[226:229], v[2:5]
	s_setprio 0
	s_barrier
	s_add_i32 s50, 0, 0x18000
	s_add_i32 s51, 0, 0x1c000
	v_add_u32_e32 v160, s50, v145
	v_add_u32_e32 v176, s51, v145
	ds_read_b128 v[148:151], v160
	ds_read_b128 v[152:155], v160 offset:1024
	ds_read_b128 v[156:159], v160 offset:2048
	ds_read_b128 v[160:163], v160 offset:3072
	ds_read_b128 v[164:167], v176
	ds_read_b128 v[168:171], v176 offset:1024
	ds_read_b128 v[172:175], v176 offset:2048
	ds_read_b128 v[176:179], v176 offset:3072
	s_add_u32 s30, s30, 0x40000
	s_addc_u32 s31, s31, 0
	s_mov_b32 m0, s37
	v_lshl_add_u64 v[232:233], s[30:31], 0, v[134:135]
	ds_read_b128 v[180:183], v147 offset:32768
	ds_read_b128 v[184:187], v147 offset:33792
	ds_read_b128 v[188:191], v147 offset:34816
	ds_read_b128 v[192:195], v147 offset:35840
	ds_read_b128 v[214:217], v147 offset:36864
	ds_read_b128 v[218:221], v147 offset:37888
	ds_read_b128 v[222:225], v147 offset:38912
	ds_read_b128 v[226:229], v147 offset:39936
	global_load_lds_dwordx4 v[232:233], off
	v_lshl_add_u64 v[232:233], s[30:31], 0, v[132:133]
	s_mov_b32 m0, s40
	s_nop 0
	global_load_lds_dwordx4 v[232:233], off
	s_waitcnt vmcnt(8)
	s_waitcnt lgkmcnt(0)
	s_barrier
	s_setprio 1
	v_mfma_f32_16x16x32_bf16 v[126:129], v[148:151], v[180:183], v[126:129]
	v_mfma_f32_16x16x32_bf16 v[122:125], v[156:159], v[180:183], v[122:125]
	v_mfma_f32_16x16x32_bf16 v[118:121], v[148:151], v[188:191], v[118:121]
	v_mfma_f32_16x16x32_bf16 v[114:117], v[156:159], v[188:191], v[114:117]
	v_mfma_f32_16x16x32_bf16 v[102:105], v[148:151], v[214:217], v[102:105]
	v_mfma_f32_16x16x32_bf16 v[98:101], v[156:159], v[214:217], v[98:101]
	v_mfma_f32_16x16x32_bf16 v[86:89], v[148:151], v[222:225], v[86:89]
	v_mfma_f32_16x16x32_bf16 v[82:85], v[156:159], v[222:225], v[82:85]
	v_mfma_f32_16x16x32_bf16 v[126:129], v[152:155], v[184:187], v[126:129]
	v_mfma_f32_16x16x32_bf16 v[122:125], v[160:163], v[184:187], v[122:125]
	v_mfma_f32_16x16x32_bf16 v[118:121], v[152:155], v[192:195], v[118:121]
	v_mfma_f32_16x16x32_bf16 v[114:117], v[160:163], v[192:195], v[114:117]
	v_mfma_f32_16x16x32_bf16 v[102:105], v[152:155], v[218:221], v[102:105]
	v_mfma_f32_16x16x32_bf16 v[98:101], v[160:163], v[218:221], v[98:101]
	v_mfma_f32_16x16x32_bf16 v[86:89], v[152:155], v[226:229], v[86:89]
	v_mfma_f32_16x16x32_bf16 v[82:85], v[160:163], v[226:229], v[82:85]
	s_setprio 0
	s_setprio 1
	v_mfma_f32_16x16x32_bf16 v[110:113], v[164:167], v[180:183], v[110:113]
	v_mfma_f32_16x16x32_bf16 v[106:109], v[172:175], v[180:183], v[106:109]
	v_mfma_f32_16x16x32_bf16 v[94:97], v[164:167], v[188:191], v[94:97]
	v_mfma_f32_16x16x32_bf16 v[90:93], v[172:175], v[188:191], v[90:93]
	v_mfma_f32_16x16x32_bf16 v[78:81], v[164:167], v[214:217], v[78:81]
	v_mfma_f32_16x16x32_bf16 v[74:77], v[172:175], v[214:217], v[74:77]
	v_mfma_f32_16x16x32_bf16 v[70:73], v[164:167], v[222:225], v[70:73]
	v_mfma_f32_16x16x32_bf16 v[66:69], v[172:175], v[222:225], v[66:69]
	v_mfma_f32_16x16x32_bf16 v[110:113], v[168:171], v[184:187], v[110:113]
	v_mfma_f32_16x16x32_bf16 v[106:109], v[176:179], v[184:187], v[106:109]
	v_mfma_f32_16x16x32_bf16 v[94:97], v[168:171], v[192:195], v[94:97]
	v_mfma_f32_16x16x32_bf16 v[90:93], v[176:179], v[192:195], v[90:93]
	v_mfma_f32_16x16x32_bf16 v[78:81], v[168:171], v[218:221], v[78:81]
	v_mfma_f32_16x16x32_bf16 v[74:77], v[176:179], v[218:221], v[74:77]
	v_mfma_f32_16x16x32_bf16 v[70:73], v[168:171], v[226:229], v[70:73]
	v_mfma_f32_16x16x32_bf16 v[66:69], v[176:179], v[226:229], v[66:69]
	s_setprio 0
	s_barrier
; #define PG8_STAGE(bufoff, gbase, voff) do { _Pragma("unroll") for (int _i = 0; _i < 2; ++_i) \
;         __builtin_amdgcn_global_load_lds((const unsigned*)((const char*)(gbase) + (voff)[_i]), (LAS unsigned*)(lds + (bufoff) + ldsw + _i * 8192), 16, 0, 0); } while (0)
; #define PG8_LDA(dst, b, h) do { _Pragma("unroll") for (int m = 0; m < 4; ++m) _Pragma("unroll") for (int k = 0; k < 2; ++k) dst[m][k] = *(const LAS f16x8*)(lds + PG8_SA(b, h) + aoff + m * 2048 + k * 1024); } while (0)
; #define PG8_LDB(dst, b, h) do { _Pragma("unroll") for (int n = 0; n < 2; ++n) _Pragma("unroll") for (int k = 0; k < 2; ++k) dst[n][k] = *(const LAS f16x8*)(lds + PG8_SB(b, h) + boff + n * 2048 + k * 1024); } while (0)
; #define PG8_WAIT_V(n) asm volatile("s_waitcnt vmcnt(" #n ")" ::: "memory")
; #define PG8_WAIT_L(n) asm volatile("s_waitcnt lgkmcnt(" #n ")" ::: "memory")
; #define PG8_BAR __builtin_amdgcn_s_barrier()
; #define PG8_SCHED __builtin_amdgcn_sched_barrier(0)
;     ...
;             const char* a1 = cA + (size_t)(t + 1) * kstep;
;             const char* a2 = last ? nA : cA + (size_t)(t + 2) * kstep; const char* b2 = last ? nB : cB + (size_t)(t + 2) * kstep;
;             const char* a3 = a2 + kstep; const char* b3 = b2 + kstep;
;             if constexpr (SP2) {
;             PG8_LDB(B0, 0, 0); PG8_LDB(B1, 0, 1); PG8_SCHED; PG8_LDA(At, 0, 0); PG8_STAGE(PG8_SA(1, 1), a1 + hA, voffA);
;             PG8_WAIT_V(8); PG8_WAIT_L(0); PG8_BAR; PG8_MMA(0, 0, At, B0); PG8_MMA(0, 1, At, B1); PG8_BAR; PG8_SCHED;
;             PG8_LDA(At, 0, 1); PG8_STAGE(PG8_SB(0, 0), b2, voffB); PG8_STAGE(PG8_SB(0, 1), b2 + hB, voffB); PG8_STAGE(PG8_SA(0, 0), a2, voffA);
;             PG8_WAIT_V(8); PG8_WAIT_L(0); PG8_BAR; if (!cur.half) { PG8_MMA(1, 0, At, B0); PG8_MMA(1, 1, At, B1); } PG8_BAR; PG8_SCHED;
;             PG8_LDB(B0, 1, 0); PG8_LDB(B1, 1, 1); PG8_SCHED; PG8_LDA(At, 1, 0); PG8_STAGE(PG8_SA(0, 1), a2 + hA, voffA);
;             PG8_WAIT_V(8); PG8_WAIT_L(0); PG8_BAR; PG8_MMA(0, 0, At, B0); PG8_MMA(0, 1, At, B1); PG8_BAR; PG8_SCHED;
;             PG8_LDA(At, 1, 1); PG8_STAGE(PG8_SB(1, 0), b3, voffB); PG8_STAGE(PG8_SB(1, 1), b3 + hB, voffB); PG8_STAGE(PG8_SA(1, 0), a3, voffA);
;             PG8_WAIT_V(8); PG8_WAIT_L(0); PG8_BAR; if (!cur.half) { PG8_MMA(1, 0, At, B0); PG8_MMA(1, 1, At, B1); } PG8_BAR; PG8_SCHED;
	s_add_i32 s30, s50, s34
	v_lshl_add_u64 v[142:143], v[142:143], 0, s[96:97]
	s_mov_b32 m0, s30
	ds_read_b128 v[180:183], v147 offset:49152
	ds_read_b128 v[184:187], v147 offset:50176
	ds_read_b128 v[188:191], v147 offset:51200
	ds_read_b128 v[192:195], v147 offset:52224
	ds_read_b128 v[214:217], v147 offset:53248
	ds_read_b128 v[218:221], v147 offset:54272
	ds_read_b128 v[222:225], v147 offset:55296
	ds_read_b128 v[226:229], v147 offset:56320
	global_load_lds_dwordx4 v[142:143], off
	s_add_i32 m0, s30, 0x2000
	s_add_u32 s28, s28, 0x40080
	v_lshl_add_u64 v[142:143], v[200:201], 0, s[96:97]
	s_addc_u32 s29, s29, 0
	s_add_i32 s30, s51, s34
	global_load_lds_dwordx4 v[142:143], off
	v_lshl_add_u64 v[142:143], s[28:29], 0, v[0:1]
	s_mov_b32 m0, s30
	s_nop 0
	global_load_lds_dwordx4 v[142:143], off
	v_lshl_add_u64 v[142:143], s[28:29], 0, v[130:131]
	s_add_i32 m0, s30, 0x2000
	s_nop 0
	global_load_lds_dwordx4 v[142:143], off
	v_lshl_add_u64 v[142:143], v[202:203], 0, s[96:97]
	s_mov_b32 m0, s41
	s_nop 0
	global_load_lds_dwordx4 v[142:143], off
	v_lshl_add_u64 v[142:143], v[230:231], 0, s[96:97]
	s_mov_b32 m0, s42
	s_nop 0
	global_load_lds_dwordx4 v[142:143], off
	s_waitcnt vmcnt(8)
	s_waitcnt lgkmcnt(0)
	s_barrier
	s_setprio 1
	v_mfma_f32_16x16x32_bf16 v[62:65], v[148:151], v[180:183], v[62:65]
	v_mfma_f32_16x16x32_bf16 v[58:61], v[156:159], v[180:183], v[58:61]
	v_mfma_f32_16x16x32_bf16 v[54:57], v[148:151], v[188:191], v[54:57]
	v_mfma_f32_16x16x32_bf16 v[50:53], v[156:159], v[188:191], v[50:53]
	v_mfma_f32_16x16x32_bf16 v[38:41], v[148:151], v[214:217], v[38:41]
	v_mfma_f32_16x16x32_bf16 v[34:37], v[156:159], v[214:217], v[34:37]
	v_mfma_f32_16x16x32_bf16 v[22:25], v[148:151], v[222:225], v[22:25]
	v_mfma_f32_16x16x32_bf16 v[18:21], v[156:159], v[222:225], v[18:21]
	v_mfma_f32_16x16x32_bf16 v[62:65], v[152:155], v[184:187], v[62:65]
	v_mfma_f32_16x16x32_bf16 v[58:61], v[160:163], v[184:187], v[58:61]
	v_mfma_f32_16x16x32_bf16 v[54:57], v[152:155], v[192:195], v[54:57]
	v_mfma_f32_16x16x32_bf16 v[50:53], v[160:163], v[192:195], v[50:53]
	v_mfma_f32_16x16x32_bf16 v[38:41], v[152:155], v[218:221], v[38:41]
	v_mfma_f32_16x16x32_bf16 v[34:37], v[160:163], v[218:221], v[34:37]
	v_mfma_f32_16x16x32_bf16 v[22:25], v[152:155], v[226:229], v[22:25]
	v_mfma_f32_16x16x32_bf16 v[18:21], v[160:163], v[226:229], v[18:21]
	s_setprio 0
	s_setprio 1
	v_mfma_f32_16x16x32_bf16 v[46:49], v[164:167], v[180:183], v[46:49]
	v_mfma_f32_16x16x32_bf16 v[42:45], v[172:175], v[180:183], v[42:45]
	v_mfma_f32_16x16x32_bf16 v[30:33], v[164:167], v[188:191], v[30:33]
	v_mfma_f32_16x16x32_bf16 v[26:29], v[172:175], v[188:191], v[26:29]
	v_mfma_f32_16x16x32_bf16 v[14:17], v[164:167], v[214:217], v[14:17]
	v_mfma_f32_16x16x32_bf16 v[10:13], v[172:175], v[214:217], v[10:13]
	v_mfma_f32_16x16x32_bf16 v[6:9], v[164:167], v[222:225], v[6:9]
	v_mfma_f32_16x16x32_bf16 v[2:5], v[172:175], v[222:225], v[2:5]
	v_mfma_f32_16x16x32_bf16 v[46:49], v[168:171], v[184:187], v[46:49]
	v_mfma_f32_16x16x32_bf16 v[42:45], v[176:179], v[184:187], v[42:45]
	v_mfma_f32_16x16x32_bf16 v[30:33], v[168:171], v[192:195], v[30:33]
	v_mfma_f32_16x16x32_bf16 v[26:29], v[176:179], v[192:195], v[26:29]
	v_mfma_f32_16x16x32_bf16 v[14:17], v[168:171], v[218:221], v[14:17]
	v_mfma_f32_16x16x32_bf16 v[10:13], v[176:179], v[218:221], v[10:13]
	v_mfma_f32_16x16x32_bf16 v[6:9], v[168:171], v[226:229], v[6:9]
	v_mfma_f32_16x16x32_bf16 v[2:5], v[176:179], v[226:229], v[2:5]
	s_setprio 0
	s_barrier
	s_add_i32 s49, s49, 2
	s_add_u32 s26, s26, 0x100
	s_addc_u32 s27, s27, 0
	s_add_u32 s47, s47, 0x100
	s_addc_u32 s48, s48, 0
	s_cmp_gt_u32 s49, 13
	s_cbranch_scc0 .LBB0_516
	s_and_b64 vcc, exec, s[8:9]
	s_cbranch_vccnz .LBB0_521
	v_lshl_add_u32 v142, s16, 8, v144
	s_cmp_gt_i32 s46, 25
	s_mov_b64 s[2:3], -1
	s_cbranch_scc1 .LBB0_522

; #define PG8_STAGE(bufoff, gbase, voff) do { _Pragma("unroll") for (int _i = 0; _i < 2; ++_i) \
;         __builtin_amdgcn_global_load_lds((const unsigned*)((const char*)(gbase) + (voff)[_i]), (LAS unsigned*)(lds + (bufoff) + ldsw + _i * 8192), 16, 0, 0); } while (0)
; #define PG8_LDA(dst, b, h) do { _Pragma("unroll") for (int m = 0; m < 4; ++m) _Pragma("unroll") for (int k = 0; k < 2; ++k) dst[m][k] = *(const LAS f16x8*)(lds + PG8_SA(b, h) + aoff + m * 2048 + k * 1024); } while (0)
; #define PG8_LDB(dst, b, h) do { _Pragma("unroll") for (int n = 0; n < 2; ++n) _Pragma("unroll") for (int k = 0; k < 2; ++k) dst[n][k] = *(const LAS f16x8*)(lds + PG8_SB(b, h) + boff + n * 2048 + k * 1024); } while (0)
; #define PG8_MMA(ai, bj, At, Bt) do { __builtin_amdgcn_s_setprio(1); _Pragma("unroll") for (int m = 0; m < 4; ++m) _Pragma("unroll") for (int n = 0; n < 2; ++n) _Pragma("unroll") for (int k = 0; k < 2; ++k) \
;         acc[ai][bj][m][n] = mma16_<Epi::BF16>(Bt[n][k], At[m][k], acc[ai][bj][m][n]); __builtin_amdgcn_s_setprio(0); } while (0)
; #define PG8_WAIT_V(n) asm volatile("s_waitcnt vmcnt(" #n ")" ::: "memory")
; #define PG8_WAIT_L(n) asm volatile("s_waitcnt lgkmcnt(" #n ")" ::: "memory")
; #define PG8_BAR __builtin_amdgcn_s_barrier()
; #define PG8_SCHED __builtin_amdgcn_sched_barrier(0)
;     ...
;             PG8_LDB(B0, 0, 0); PG8_LDB(B1, 0, 1); PG8_SCHED; PG8_LDA(At, 0, 0); PG8_STAGE(PG8_SA(1, 1), a1 + hA, voffA);
;             PG8_WAIT_V(8); PG8_WAIT_L(0); PG8_BAR; PG8_MMA(0, 0, At, B0); PG8_MMA(0, 1, At, B1); PG8_BAR; PG8_SCHED;
;             PG8_LDA(At, 0, 1); PG8_STAGE(PG8_SB(0, 0), b2, voffB); PG8_STAGE(PG8_SB(0, 1), b2 + hB, voffB); PG8_STAGE(PG8_SA(0, 0), a2, voffA);
;             PG8_WAIT_V(8); PG8_WAIT_L(0); PG8_BAR; if (!cur.half) { PG8_MMA(1, 0, At, B0); PG8_MMA(1, 1, At, B1); } PG8_BAR; PG8_SCHED;
.LBB0_758:
	s_mov_b64 s[30:31], s[10:11]
	s_add_u32 s10, s30, 0x100
	s_addc_u32 s11, s31, 0
	s_add_i32 s40, 0, 0x10000
	s_cmp_eq_u32 s59, 12
	s_cselect_b32 s29, s43, s11
	s_cselect_b32 s28, s42, s10
	v_add_u32_e32 v0, s40, v233
	s_cselect_b32 s27, s2, s58
	s_cselect_b32 s26, s3, s23
	s_add_i32 s41, 0, 0x14000
	ds_read_b128 v[148:151], v0
	ds_read_b128 v[152:155], v0 offset:1024
	ds_read_b128 v[156:159], v0 offset:2048
	ds_read_b128 v[160:163], v0 offset:3072
	v_add_u32_e32 v0, s41, v233
	ds_read_b128 v[132:135], v0
	ds_read_b128 v[136:139], v0 offset:1024
	ds_read_b128 v[140:143], v0 offset:2048
	ds_read_b128 v[144:147], v0 offset:3072
	v_lshl_add_u64 v[2:3], s[30:31], 0, v[222:223]
	s_add_i32 m0, s9, 0xc000
	s_waitcnt lgkmcnt(0)
	ds_read_b128 v[164:167], v243
	ds_read_b128 v[168:171], v243 offset:1024
	ds_read_b128 v[172:175], v243 offset:2048
	ds_read_b128 v[176:179], v243 offset:3072
	ds_read_b128 v[180:183], v243 offset:4096
	ds_read_b128 v[184:187], v243 offset:5120
	ds_read_b128 v[188:191], v243 offset:6144
	ds_read_b128 v[192:195], v243 offset:7168
	global_load_lds_dwordx4 v[2:3], off
	v_lshl_add_u64 v[2:3], s[30:31], 0, v[224:225]
	s_add_i32 m0, s9, 0xe000
	s_nop 0
	global_load_lds_dwordx4 v[2:3], off
	s_waitcnt vmcnt(8)
	s_waitcnt lgkmcnt(0)
	s_barrier
	s_setprio 1
	v_mfma_f32_16x16x32_f16 v[128:131], v[148:151], v[164:167], v[128:131]
	v_mfma_f32_16x16x32_f16 v[124:127], v[156:159], v[164:167], v[124:127]
	v_mfma_f32_16x16x32_f16 v[112:115], v[148:151], v[172:175], v[112:115]
	v_mfma_f32_16x16x32_f16 v[108:111], v[156:159], v[172:175], v[108:111]
	v_mfma_f32_16x16x32_f16 v[96:99], v[148:151], v[180:183], v[96:99]
	v_mfma_f32_16x16x32_f16 v[92:95], v[156:159], v[180:183], v[92:95]
	v_mfma_f32_16x16x32_f16 v[80:83], v[148:151], v[188:191], v[80:83]
	v_mfma_f32_16x16x32_f16 v[76:79], v[156:159], v[188:191], v[76:79]
	v_mfma_f32_16x16x32_f16 v[128:131], v[152:155], v[168:171], v[128:131]
	v_mfma_f32_16x16x32_f16 v[124:127], v[160:163], v[168:171], v[124:127]
	v_mfma_f32_16x16x32_f16 v[112:115], v[152:155], v[176:179], v[112:115]
	v_mfma_f32_16x16x32_f16 v[108:111], v[160:163], v[176:179], v[108:111]
	v_mfma_f32_16x16x32_f16 v[96:99], v[152:155], v[184:187], v[96:99]
	v_mfma_f32_16x16x32_f16 v[92:95], v[160:163], v[184:187], v[92:95]
	v_mfma_f32_16x16x32_f16 v[80:83], v[152:155], v[192:195], v[80:83]
	v_mfma_f32_16x16x32_f16 v[76:79], v[160:163], v[192:195], v[76:79]
	s_setprio 0
	s_setprio 1
	v_mfma_f32_16x16x32_f16 v[120:123], v[132:135], v[164:167], v[120:123]
	v_mfma_f32_16x16x32_f16 v[116:119], v[140:143], v[164:167], v[116:119]
	v_mfma_f32_16x16x32_f16 v[104:107], v[132:135], v[172:175], v[104:107]
	v_mfma_f32_16x16x32_f16 v[100:103], v[140:143], v[172:175], v[100:103]
	v_mfma_f32_16x16x32_f16 v[88:91], v[132:135], v[180:183], v[88:91]
	v_mfma_f32_16x16x32_f16 v[84:87], v[140:143], v[180:183], v[84:87]
	v_mfma_f32_16x16x32_f16 v[72:75], v[132:135], v[188:191], v[72:75]
	v_mfma_f32_16x16x32_f16 v[68:71], v[140:143], v[188:191], v[68:71]
	v_mfma_f32_16x16x32_f16 v[120:123], v[136:139], v[168:171], v[120:123]
	v_mfma_f32_16x16x32_f16 v[116:119], v[144:147], v[168:171], v[116:119]
	v_mfma_f32_16x16x32_f16 v[104:107], v[136:139], v[176:179], v[104:107]
	v_mfma_f32_16x16x32_f16 v[100:103], v[144:147], v[176:179], v[100:103]
	v_mfma_f32_16x16x32_f16 v[88:91], v[136:139], v[184:187], v[88:91]
	v_mfma_f32_16x16x32_f16 v[84:87], v[144:147], v[184:187], v[84:87]
	v_mfma_f32_16x16x32_f16 v[72:75], v[136:139], v[192:195], v[72:75]
	v_mfma_f32_16x16x32_f16 v[68:71], v[144:147], v[192:195], v[68:71]
	s_setprio 0
	s_barrier
	s_add_i32 s30, s40, s35
	v_lshl_add_u64 v[2:3], s[26:27], 0, v[216:217]
	s_mov_b32 m0, s30
	ds_read_b128 v[188:191], v243 offset:16384
	ds_read_b128 v[192:195], v243 offset:17408
	ds_read_b128 v[180:183], v243 offset:18432
	ds_read_b128 v[184:187], v243 offset:19456
	ds_read_b128 v[172:175], v243 offset:20480
	ds_read_b128 v[176:179], v243 offset:21504
	ds_read_b128 v[164:167], v243 offset:22528
	ds_read_b128 v[168:171], v243 offset:23552
	global_load_lds_dwordx4 v[2:3], off
	s_add_i32 m0, s30, 0x2000
	s_add_u32 s30, s26, 0x40000
	v_lshl_add_u64 v[226:227], s[26:27], 0, v[220:221]
	s_addc_u32 s31, s27, 0
	s_add_i32 s40, s41, s35
	global_load_lds_dwordx4 v[226:227], off
	v_lshl_add_u64 v[200:201], s[30:31], 0, v[216:217]
	s_mov_b32 m0, s40
	v_lshl_add_u64 v[228:229], s[28:29], 0, v[214:215]
	global_load_lds_dwordx4 v[200:201], off
	v_lshl_add_u64 v[200:201], s[30:31], 0, v[220:221]
	s_add_i32 m0, s40, 0x2000
	v_lshl_add_u64 v[230:231], s[28:29], 0, v[218:219]
	global_load_lds_dwordx4 v[200:201], off
	s_mov_b32 m0, s9
	v_cndmask_b32_e64 v0, 0, 1, s[24:25]
	global_load_lds_dwordx4 v[228:229], off
	s_mov_b32 m0, s36
	v_cmp_ne_u32_e64 s[40:41], 1, v0
	global_load_lds_dwordx4 v[230:231], off
	s_waitcnt vmcnt(8)
	s_waitcnt lgkmcnt(0)
	s_andn2_b64 vcc, exec, s[24:25]
	s_barrier
	s_cbranch_vccnz .LBB0_760
; #define PG8_MMA(ai, bj, At, Bt) do { __builtin_amdgcn_s_setprio(1); _Pragma("unroll") for (int m = 0; m < 4; ++m) _Pragma("unroll") for (int n = 0; n < 2; ++n) _Pragma("unroll") for (int k = 0; k < 2; ++k) \
;         acc[ai][bj][m][n] = mma16_<Epi::BF16>(Bt[n][k], At[m][k], acc[ai][bj][m][n]); __builtin_amdgcn_s_setprio(0); } while (0)
; #define PG8_WAIT_V(n) asm volatile("s_waitcnt vmcnt(" #n ")" ::: "memory")
; #define PG8_WAIT_L(n) asm volatile("s_waitcnt lgkmcnt(" #n ")" ::: "memory")
; #define PG8_BAR __builtin_amdgcn_s_barrier()
; #define PG8_SCHED __builtin_amdgcn_sched_barrier(0)
;     ...
;             PG8_WAIT_V(8); PG8_WAIT_L(0); PG8_BAR; if (!cur.half) { PG8_MMA(1, 0, At, B0); PG8_MMA(1, 1, At, B1); } PG8_BAR; PG8_SCHED;
	s_setprio 1
	v_mfma_f32_16x16x32_f16 v[64:67], v[148:151], v[188:191], v[64:67]
	v_mfma_f32_16x16x32_f16 v[60:63], v[156:159], v[188:191], v[60:63]
	v_mfma_f32_16x16x32_f16 v[48:51], v[148:151], v[180:183], v[48:51]
	v_mfma_f32_16x16x32_f16 v[44:47], v[156:159], v[180:183], v[44:47]
	v_mfma_f32_16x16x32_f16 v[32:35], v[148:151], v[172:175], v[32:35]
	v_mfma_f32_16x16x32_f16 v[28:31], v[156:159], v[172:175], v[28:31]
	v_mfma_f32_16x16x32_f16 v[16:19], v[148:151], v[164:167], v[16:19]
	v_mfma_f32_16x16x32_f16 v[12:15], v[156:159], v[164:167], v[12:15]
	v_mfma_f32_16x16x32_f16 v[64:67], v[152:155], v[192:195], v[64:67]
	v_mfma_f32_16x16x32_f16 v[60:63], v[160:163], v[192:195], v[60:63]
	v_mfma_f32_16x16x32_f16 v[48:51], v[152:155], v[184:187], v[48:51]
	v_mfma_f32_16x16x32_f16 v[44:47], v[160:163], v[184:187], v[44:47]
	v_mfma_f32_16x16x32_f16 v[32:35], v[152:155], v[176:179], v[32:35]
	v_mfma_f32_16x16x32_f16 v[28:31], v[160:163], v[176:179], v[28:31]
	v_mfma_f32_16x16x32_f16 v[16:19], v[152:155], v[168:171], v[16:19]
	v_mfma_f32_16x16x32_f16 v[12:15], v[160:163], v[168:171], v[12:15]
	s_setprio 0
	s_setprio 1
	v_mfma_f32_16x16x32_f16 v[56:59], v[132:135], v[188:191], v[56:59]
	v_mfma_f32_16x16x32_f16 v[52:55], v[140:143], v[188:191], v[52:55]
	v_mfma_f32_16x16x32_f16 v[40:43], v[132:135], v[180:183], v[40:43]
	v_mfma_f32_16x16x32_f16 v[36:39], v[140:143], v[180:183], v[36:39]
	v_mfma_f32_16x16x32_f16 v[24:27], v[132:135], v[172:175], v[24:27]
	v_mfma_f32_16x16x32_f16 v[20:23], v[140:143], v[172:175], v[20:23]
	v_mfma_f32_16x16x32_f16 v[8:11], v[132:135], v[164:167], v[8:11]
	v_mfma_f32_16x16x32_f16 v[4:7], v[140:143], v[164:167], v[4:7]
	v_mfma_f32_16x16x32_f16 v[56:59], v[136:139], v[192:195], v[56:59]
	v_mfma_f32_16x16x32_f16 v[52:55], v[144:147], v[192:195], v[52:55]
	v_mfma_f32_16x16x32_f16 v[40:43], v[136:139], v[184:187], v[40:43]
	v_mfma_f32_16x16x32_f16 v[36:39], v[144:147], v[184:187], v[36:39]
	v_mfma_f32_16x16x32_f16 v[24:27], v[136:139], v[176:179], v[24:27]
	v_mfma_f32_16x16x32_f16 v[20:23], v[144:147], v[176:179], v[20:23]
	v_mfma_f32_16x16x32_f16 v[8:11], v[136:139], v[168:171], v[8:11]
	v_mfma_f32_16x16x32_f16 v[4:7], v[144:147], v[168:171], v[4:7]
	s_setprio 0
; #define PG8_STAGE(bufoff, gbase, voff) do { _Pragma("unroll") for (int _i = 0; _i < 2; ++_i) \
;         __builtin_amdgcn_global_load_lds((const unsigned*)((const char*)(gbase) + (voff)[_i]), (LAS unsigned*)(lds + (bufoff) + ldsw + _i * 8192), 16, 0, 0); } while (0)
; #define PG8_LDA(dst, b, h) do { _Pragma("unroll") for (int m = 0; m < 4; ++m) _Pragma("unroll") for (int k = 0; k < 2; ++k) dst[m][k] = *(const LAS f16x8*)(lds + PG8_SA(b, h) + aoff + m * 2048 + k * 1024); } while (0)
; #define PG8_LDB(dst, b, h) do { _Pragma("unroll") for (int n = 0; n < 2; ++n) _Pragma("unroll") for (int k = 0; k < 2; ++k) dst[n][k] = *(const LAS f16x8*)(lds + PG8_SB(b, h) + boff + n * 2048 + k * 1024); } while (0)
; #define PG8_MMA(ai, bj, At, Bt) do { __builtin_amdgcn_s_setprio(1); _Pragma("unroll") for (int m = 0; m < 4; ++m) _Pragma("unroll") for (int n = 0; n < 2; ++n) _Pragma("unroll") for (int k = 0; k < 2; ++k) \
;         acc[ai][bj][m][n] = mma16_<Epi::BF16>(Bt[n][k], At[m][k], acc[ai][bj][m][n]); __builtin_amdgcn_s_setprio(0); } while (0)
; #define PG8_WAIT_V(n) asm volatile("s_waitcnt vmcnt(" #n ")" ::: "memory")
; #define PG8_WAIT_L(n) asm volatile("s_waitcnt lgkmcnt(" #n ")" ::: "memory")
; #define PG8_BAR __builtin_amdgcn_s_barrier()
; #define PG8_SCHED __builtin_amdgcn_sched_barrier(0)
;     ...
;             PG8_LDB(B0, 1, 0); PG8_LDB(B1, 1, 1); PG8_SCHED; PG8_LDA(At, 1, 0); PG8_STAGE(PG8_SA(0, 1), a2 + hA, voffA);
;             PG8_WAIT_V(8); PG8_WAIT_L(0); PG8_BAR; PG8_MMA(0, 0, At, B0); PG8_MMA(0, 1, At, B1); PG8_BAR; PG8_SCHED;
;             PG8_LDA(At, 1, 1); PG8_STAGE(PG8_SB(1, 0), b3, voffB); PG8_STAGE(PG8_SB(1, 1), b3 + hB, voffB); PG8_STAGE(PG8_SA(1, 0), a3, voffA);
;             PG8_WAIT_V(8); PG8_WAIT_L(0); PG8_BAR; if (!cur.half) { PG8_MMA(1, 0, At, B0); PG8_MMA(1, 1, At, B1); } PG8_BAR; PG8_SCHED;
.LBB0_760:
	s_barrier
	s_add_i32 s30, 0, 0x18000
	v_add_u32_e32 v0, s30, v233
	s_add_i32 s31, 0, 0x1c000
	ds_read_b128 v[148:151], v0
	ds_read_b128 v[152:155], v0 offset:1024
	ds_read_b128 v[156:159], v0 offset:2048
	ds_read_b128 v[160:163], v0 offset:3072
	v_add_u32_e32 v0, s31, v233
	ds_read_b128 v[132:135], v0
	ds_read_b128 v[136:139], v0 offset:1024
	ds_read_b128 v[140:143], v0 offset:2048
	ds_read_b128 v[144:147], v0 offset:3072
	s_add_u32 s28, s28, 0x1a0000
	s_addc_u32 s29, s29, 0
	s_mov_b32 m0, s37
	v_lshl_add_u64 v[200:201], s[28:29], 0, v[214:215]
	s_waitcnt lgkmcnt(0)
	ds_read_b128 v[164:167], v243 offset:32768
	ds_read_b128 v[168:171], v243 offset:33792
	ds_read_b128 v[172:175], v243 offset:34816
	ds_read_b128 v[176:179], v243 offset:35840
	ds_read_b128 v[180:183], v243 offset:36864
	ds_read_b128 v[184:187], v243 offset:37888
	ds_read_b128 v[188:191], v243 offset:38912
	ds_read_b128 v[192:195], v243 offset:39936
	global_load_lds_dwordx4 v[200:201], off
	v_lshl_add_u64 v[200:201], s[28:29], 0, v[218:219]
	s_mov_b32 m0, s48
	s_nop 0
	global_load_lds_dwordx4 v[200:201], off
	s_waitcnt vmcnt(8)
	s_waitcnt lgkmcnt(0)
	s_barrier
	s_setprio 1
	v_mfma_f32_16x16x32_f16 v[128:131], v[148:151], v[164:167], v[128:131]
	v_mfma_f32_16x16x32_f16 v[124:127], v[156:159], v[164:167], v[124:127]
	v_mfma_f32_16x16x32_f16 v[112:115], v[148:151], v[172:175], v[112:115]
	v_mfma_f32_16x16x32_f16 v[108:111], v[156:159], v[172:175], v[108:111]
	v_mfma_f32_16x16x32_f16 v[96:99], v[148:151], v[180:183], v[96:99]
	v_mfma_f32_16x16x32_f16 v[92:95], v[156:159], v[180:183], v[92:95]
	v_mfma_f32_16x16x32_f16 v[80:83], v[148:151], v[188:191], v[80:83]
	v_mfma_f32_16x16x32_f16 v[76:79], v[156:159], v[188:191], v[76:79]
	v_mfma_f32_16x16x32_f16 v[128:131], v[152:155], v[168:171], v[128:131]
	v_mfma_f32_16x16x32_f16 v[124:127], v[160:163], v[168:171], v[124:127]
	v_mfma_f32_16x16x32_f16 v[112:115], v[152:155], v[176:179], v[112:115]
	v_mfma_f32_16x16x32_f16 v[108:111], v[160:163], v[176:179], v[108:111]
	v_mfma_f32_16x16x32_f16 v[96:99], v[152:155], v[184:187], v[96:99]
	v_mfma_f32_16x16x32_f16 v[92:95], v[160:163], v[184:187], v[92:95]
	v_mfma_f32_16x16x32_f16 v[80:83], v[152:155], v[192:195], v[80:83]
	v_mfma_f32_16x16x32_f16 v[76:79], v[160:163], v[192:195], v[76:79]
	s_setprio 0
	s_setprio 1
	v_mfma_f32_16x16x32_f16 v[120:123], v[132:135], v[164:167], v[120:123]
	v_mfma_f32_16x16x32_f16 v[116:119], v[140:143], v[164:167], v[116:119]
	v_mfma_f32_16x16x32_f16 v[104:107], v[132:135], v[172:175], v[104:107]
	v_mfma_f32_16x16x32_f16 v[100:103], v[140:143], v[172:175], v[100:103]
	v_mfma_f32_16x16x32_f16 v[88:91], v[132:135], v[180:183], v[88:91]
	v_mfma_f32_16x16x32_f16 v[84:87], v[140:143], v[180:183], v[84:87]
	v_mfma_f32_16x16x32_f16 v[72:75], v[132:135], v[188:191], v[72:75]
	v_mfma_f32_16x16x32_f16 v[68:71], v[140:143], v[188:191], v[68:71]
	v_mfma_f32_16x16x32_f16 v[120:123], v[136:139], v[168:171], v[120:123]
	v_mfma_f32_16x16x32_f16 v[116:119], v[144:147], v[168:171], v[116:119]
	v_mfma_f32_16x16x32_f16 v[104:107], v[136:139], v[176:179], v[104:107]
	v_mfma_f32_16x16x32_f16 v[100:103], v[144:147], v[176:179], v[100:103]
	v_mfma_f32_16x16x32_f16 v[88:91], v[136:139], v[184:187], v[88:91]
	v_mfma_f32_16x16x32_f16 v[84:87], v[144:147], v[184:187], v[84:87]
	v_mfma_f32_16x16x32_f16 v[72:75], v[136:139], v[192:195], v[72:75]
	v_mfma_f32_16x16x32_f16 v[68:71], v[144:147], v[192:195], v[68:71]
	s_setprio 0
	s_barrier
	s_add_i32 s28, s30, s35
	v_lshl_add_u64 v[2:3], v[2:3], 0, s[96:97]
	s_mov_b32 m0, s28
	ds_read_b128 v[188:191], v243 offset:49152
	ds_read_b128 v[192:195], v243 offset:50176
	ds_read_b128 v[180:183], v243 offset:51200
	ds_read_b128 v[184:187], v243 offset:52224
	ds_read_b128 v[172:175], v243 offset:53248
	ds_read_b128 v[176:179], v243 offset:54272
	ds_read_b128 v[164:167], v243 offset:55296
	ds_read_b128 v[168:171], v243 offset:56320
	global_load_lds_dwordx4 v[2:3], off
	s_add_i32 m0, s28, 0x2000
	s_add_u32 s26, s26, 0x40080
	v_lshl_add_u64 v[2:3], v[226:227], 0, s[96:97]
	s_addc_u32 s27, s27, 0
	s_add_i32 s28, s31, s35
	global_load_lds_dwordx4 v[2:3], off
	v_lshl_add_u64 v[2:3], s[26:27], 0, v[216:217]
	s_mov_b32 m0, s28
	s_and_b64 vcc, exec, s[40:41]
	global_load_lds_dwordx4 v[2:3], off
	v_lshl_add_u64 v[2:3], s[26:27], 0, v[220:221]
	s_add_i32 m0, s28, 0x2000
	s_nop 0
	global_load_lds_dwordx4 v[2:3], off
	v_lshl_add_u64 v[2:3], v[228:229], 0, s[96:97]
	s_mov_b32 m0, s49
	s_nop 0
	global_load_lds_dwordx4 v[2:3], off
	v_lshl_add_u64 v[2:3], v[230:231], 0, s[96:97]
	s_mov_b32 m0, s50
	s_nop 0
	global_load_lds_dwordx4 v[2:3], off
	s_waitcnt vmcnt(8)
	s_waitcnt lgkmcnt(0)
	s_barrier
	s_cbranch_vccnz .LBB0_757
	s_setprio 1
	v_mfma_f32_16x16x32_f16 v[64:67], v[148:151], v[188:191], v[64:67]
	v_mfma_f32_16x16x32_f16 v[60:63], v[156:159], v[188:191], v[60:63]
	v_mfma_f32_16x16x32_f16 v[48:51], v[148:151], v[180:183], v[48:51]
	v_mfma_f32_16x16x32_f16 v[44:47], v[156:159], v[180:183], v[44:47]
	v_mfma_f32_16x16x32_f16 v[32:35], v[148:151], v[172:175], v[32:35]
	v_mfma_f32_16x16x32_f16 v[28:31], v[156:159], v[172:175], v[28:31]
	v_mfma_f32_16x16x32_f16 v[16:19], v[148:151], v[164:167], v[16:19]
	v_mfma_f32_16x16x32_f16 v[12:15], v[156:159], v[164:167], v[12:15]
	v_mfma_f32_16x16x32_f16 v[64:67], v[152:155], v[192:195], v[64:67]
	v_mfma_f32_16x16x32_f16 v[60:63], v[160:163], v[192:195], v[60:63]
	v_mfma_f32_16x16x32_f16 v[48:51], v[152:155], v[184:187], v[48:51]
	v_mfma_f32_16x16x32_f16 v[44:47], v[160:163], v[184:187], v[44:47]
	v_mfma_f32_16x16x32_f16 v[32:35], v[152:155], v[176:179], v[32:35]
	v_mfma_f32_16x16x32_f16 v[28:31], v[160:163], v[176:179], v[28:31]
	v_mfma_f32_16x16x32_f16 v[16:19], v[152:155], v[168:171], v[16:19]
	v_mfma_f32_16x16x32_f16 v[12:15], v[160:163], v[168:171], v[12:15]
	s_setprio 0
	s_setprio 1
	v_mfma_f32_16x16x32_f16 v[56:59], v[132:135], v[188:191], v[56:59]
	v_mfma_f32_16x16x32_f16 v[52:55], v[140:143], v[188:191], v[52:55]
	v_mfma_f32_16x16x32_f16 v[40:43], v[132:135], v[180:183], v[40:43]
	v_mfma_f32_16x16x32_f16 v[36:39], v[140:143], v[180:183], v[36:39]
	v_mfma_f32_16x16x32_f16 v[24:27], v[132:135], v[172:175], v[24:27]
	v_mfma_f32_16x16x32_f16 v[20:23], v[140:143], v[172:175], v[20:23]
	v_mfma_f32_16x16x32_f16 v[8:11], v[132:135], v[164:167], v[8:11]
	v_mfma_f32_16x16x32_f16 v[2:5], v[140:143], v[164:167], v[4:7]
	v_mfma_f32_16x16x32_f16 v[56:59], v[136:139], v[192:195], v[56:59]
	v_mfma_f32_16x16x32_f16 v[52:55], v[144:147], v[192:195], v[52:55]
	v_mfma_f32_16x16x32_f16 v[40:43], v[136:139], v[184:187], v[40:43]
	v_mfma_f32_16x16x32_f16 v[36:39], v[144:147], v[184:187], v[36:39]
	v_mfma_f32_16x16x32_f16 v[24:27], v[136:139], v[176:179], v[24:27]
	v_mfma_f32_16x16x32_f16 v[20:23], v[144:147], v[176:179], v[20:23]
	v_mfma_f32_16x16x32_f16 v[8:11], v[136:139], v[168:171], v[8:11]
	v_mfma_f32_16x16x32_f16 v[4:7], v[144:147], v[168:171], v[2:5]
	s_setprio 0
	s_branch .LBB0_757

; #define PG8_STAGE(bufoff, gbase, voff) do { _Pragma("unroll") for (int _i = 0; _i < 2; ++_i) \
;         __builtin_amdgcn_global_load_lds((const unsigned*)((const char*)(gbase) + (voff)[_i]), (LAS unsigned*)(lds + (bufoff) + ldsw + _i * 8192), 16, 0, 0); } while (0)
; #define PG8_LDA(dst, b, h) do { _Pragma("unroll") for (int m = 0; m < 4; ++m) _Pragma("unroll") for (int k = 0; k < 2; ++k) dst[m][k] = *(const LAS f16x8*)(lds + PG8_SA(b, h) + aoff + m * 2048 + k * 1024); } while (0)
; #define PG8_LDB(dst, b, h) do { _Pragma("unroll") for (int n = 0; n < 2; ++n) _Pragma("unroll") for (int k = 0; k < 2; ++k) dst[n][k] = *(const LAS f16x8*)(lds + PG8_SB(b, h) + boff + n * 2048 + k * 1024); } while (0)
; #define PG8_MMA(ai, bj, At, Bt) do { __builtin_amdgcn_s_setprio(1); _Pragma("unroll") for (int m = 0; m < 4; ++m) _Pragma("unroll") for (int n = 0; n < 2; ++n) _Pragma("unroll") for (int k = 0; k < 2; ++k) \
;         acc[ai][bj][m][n] = mma16_<Epi::BF16>(Bt[n][k], At[m][k], acc[ai][bj][m][n]); __builtin_amdgcn_s_setprio(0); } while (0)
; #define PG8_WAIT_V(n) asm volatile("s_waitcnt vmcnt(" #n ")" ::: "memory")
; #define PG8_WAIT_L(n) asm volatile("s_waitcnt lgkmcnt(" #n ")" ::: "memory")
; #define PG8_BAR __builtin_amdgcn_s_barrier()
;     ...
;         const char* nA = has_next ? (const char*)g.A + (size_t)nxt.pm * tA + (nxt.roff ? hA : (size_t)0) : cA; const char* nB = has_next ? (const char*)g.Bt + (size_t)nxt.pn * tB : cB;
;         for (int t = 0; t < nt; t += 2) {
;             const bool last = (t == nt - 2);
;             const char* a1 = cA + (size_t)(t + 1) * kstep;
;             const char* a2 = last ? nA : cA + (size_t)(t + 2) * kstep; const char* b2 = last ? nB : cB + (size_t)(t + 2) * kstep;
;             const char* a3 = a2 + kstep; const char* b3 = b2 + kstep;
;             if constexpr (SP2) {
;             PG8_LDB(B0, 0, 0); PG8_LDB(B1, 0, 1); PG8_SCHED; PG8_LDA(At, 0, 0); PG8_STAGE(PG8_SA(1, 1), a1 + hA, voffA);
;             PG8_WAIT_V(8); PG8_WAIT_L(0); PG8_BAR; PG8_MMA(0, 0, At, B0); PG8_MMA(0, 1, At, B1); PG8_BAR; PG8_SCHED;
;             PG8_LDA(At, 0, 1); PG8_STAGE(PG8_SB(0, 0), b2, voffB); PG8_STAGE(PG8_SB(0, 1), b2 + hB, voffB); PG8_STAGE(PG8_SA(0, 0), a2, voffA);
;             PG8_WAIT_V(8); PG8_WAIT_L(0); PG8_BAR; if (!cur.half) { PG8_MMA(1, 0, At, B0); PG8_MMA(1, 1, At, B1); } PG8_BAR; PG8_SCHED;
.LBB0_798:
	s_mov_b64 s[24:25], s[10:11]
	s_add_u32 s10, s24, 0x100
	s_addc_u32 s11, s25, 0
	s_add_i32 s40, 0, 0x10000
	s_cmp_eq_u32 s59, 12
	s_cselect_b32 s23, s51, s11
	s_cselect_b32 s22, s50, s10
	v_add_u32_e32 v0, s40, v233
	s_cselect_b32 s21, s2, s58
	s_cselect_b32 s20, s3, s49
	s_add_i32 s41, 0, 0x14000
	ds_read_b128 v[148:151], v0
	ds_read_b128 v[152:155], v0 offset:1024
	ds_read_b128 v[156:159], v0 offset:2048
	ds_read_b128 v[160:163], v0 offset:3072
	v_add_u32_e32 v0, s41, v233
	ds_read_b128 v[132:135], v0
	ds_read_b128 v[136:139], v0 offset:1024
	ds_read_b128 v[140:143], v0 offset:2048
	ds_read_b128 v[144:147], v0 offset:3072
	v_lshl_add_u64 v[2:3], s[24:25], 0, v[222:223]
	s_add_i32 m0, s9, 0xc000
	s_waitcnt lgkmcnt(0)
	ds_read_b128 v[164:167], v243
	ds_read_b128 v[168:171], v243 offset:1024
	ds_read_b128 v[172:175], v243 offset:2048
	ds_read_b128 v[176:179], v243 offset:3072
	ds_read_b128 v[180:183], v243 offset:4096
	ds_read_b128 v[184:187], v243 offset:5120
	ds_read_b128 v[188:191], v243 offset:6144
	ds_read_b128 v[192:195], v243 offset:7168
	global_load_lds_dwordx4 v[2:3], off
	v_lshl_add_u64 v[2:3], s[24:25], 0, v[224:225]
	s_add_i32 m0, s9, 0xe000
	s_nop 0
	global_load_lds_dwordx4 v[2:3], off
	s_waitcnt vmcnt(8)
	s_waitcnt lgkmcnt(0)
	s_barrier
	s_setprio 1
	v_mfma_f32_16x16x32_f16 v[128:131], v[148:151], v[164:167], v[128:131]
	v_mfma_f32_16x16x32_f16 v[124:127], v[156:159], v[164:167], v[124:127]
	v_mfma_f32_16x16x32_f16 v[112:115], v[148:151], v[172:175], v[112:115]
	v_mfma_f32_16x16x32_f16 v[108:111], v[156:159], v[172:175], v[108:111]
	v_mfma_f32_16x16x32_f16 v[96:99], v[148:151], v[180:183], v[96:99]
	v_mfma_f32_16x16x32_f16 v[92:95], v[156:159], v[180:183], v[92:95]
	v_mfma_f32_16x16x32_f16 v[80:83], v[148:151], v[188:191], v[80:83]
	v_mfma_f32_16x16x32_f16 v[76:79], v[156:159], v[188:191], v[76:79]
	v_mfma_f32_16x16x32_f16 v[128:131], v[152:155], v[168:171], v[128:131]
	v_mfma_f32_16x16x32_f16 v[124:127], v[160:163], v[168:171], v[124:127]
	v_mfma_f32_16x16x32_f16 v[112:115], v[152:155], v[176:179], v[112:115]
	v_mfma_f32_16x16x32_f16 v[108:111], v[160:163], v[176:179], v[108:111]
	v_mfma_f32_16x16x32_f16 v[96:99], v[152:155], v[184:187], v[96:99]
	v_mfma_f32_16x16x32_f16 v[92:95], v[160:163], v[184:187], v[92:95]
	v_mfma_f32_16x16x32_f16 v[80:83], v[152:155], v[192:195], v[80:83]
	v_mfma_f32_16x16x32_f16 v[76:79], v[160:163], v[192:195], v[76:79]
	s_setprio 0
	s_setprio 1
	v_mfma_f32_16x16x32_f16 v[120:123], v[132:135], v[164:167], v[120:123]
	v_mfma_f32_16x16x32_f16 v[116:119], v[140:143], v[164:167], v[116:119]
	v_mfma_f32_16x16x32_f16 v[104:107], v[132:135], v[172:175], v[104:107]
	v_mfma_f32_16x16x32_f16 v[100:103], v[140:143], v[172:175], v[100:103]
	v_mfma_f32_16x16x32_f16 v[88:91], v[132:135], v[180:183], v[88:91]
	v_mfma_f32_16x16x32_f16 v[84:87], v[140:143], v[180:183], v[84:87]
	v_mfma_f32_16x16x32_f16 v[72:75], v[132:135], v[188:191], v[72:75]
	v_mfma_f32_16x16x32_f16 v[68:71], v[140:143], v[188:191], v[68:71]
	v_mfma_f32_16x16x32_f16 v[120:123], v[136:139], v[168:171], v[120:123]
	v_mfma_f32_16x16x32_f16 v[116:119], v[144:147], v[168:171], v[116:119]
	v_mfma_f32_16x16x32_f16 v[104:107], v[136:139], v[176:179], v[104:107]
	v_mfma_f32_16x16x32_f16 v[100:103], v[144:147], v[176:179], v[100:103]
	v_mfma_f32_16x16x32_f16 v[88:91], v[136:139], v[184:187], v[88:91]
	v_mfma_f32_16x16x32_f16 v[84:87], v[144:147], v[184:187], v[84:87]
	v_mfma_f32_16x16x32_f16 v[72:75], v[136:139], v[192:195], v[72:75]
	v_mfma_f32_16x16x32_f16 v[68:71], v[144:147], v[192:195], v[68:71]
	s_setprio 0
	s_barrier
	s_add_i32 s24, s40, s27
	v_lshl_add_u64 v[2:3], s[20:21], 0, v[216:217]
	s_mov_b32 m0, s24
	ds_read_b128 v[188:191], v243 offset:16384
	ds_read_b128 v[192:195], v243 offset:17408
	ds_read_b128 v[180:183], v243 offset:18432
	ds_read_b128 v[184:187], v243 offset:19456
	ds_read_b128 v[172:175], v243 offset:20480
	ds_read_b128 v[176:179], v243 offset:21504
	ds_read_b128 v[164:167], v243 offset:22528
	ds_read_b128 v[168:171], v243 offset:23552
	global_load_lds_dwordx4 v[2:3], off
	s_add_i32 m0, s24, 0x2000
	s_add_u32 s24, s20, 0x40000
	v_lshl_add_u64 v[226:227], s[20:21], 0, v[220:221]
	s_addc_u32 s25, s21, 0
	s_add_i32 s40, s41, s27
	global_load_lds_dwordx4 v[226:227], off
	v_lshl_add_u64 v[200:201], s[24:25], 0, v[216:217]
	s_mov_b32 m0, s40
	v_lshl_add_u64 v[228:229], s[22:23], 0, v[214:215]
	global_load_lds_dwordx4 v[200:201], off
	v_lshl_add_u64 v[200:201], s[24:25], 0, v[220:221]
	s_add_i32 m0, s40, 0x2000
	v_lshl_add_u64 v[230:231], s[22:23], 0, v[218:219]
	global_load_lds_dwordx4 v[200:201], off
	s_mov_b32 m0, s9
	v_cndmask_b32_e64 v0, 0, 1, s[18:19]
	global_load_lds_dwordx4 v[228:229], off
	s_mov_b32 m0, s28
	v_cmp_ne_u32_e64 s[40:41], 1, v0
	global_load_lds_dwordx4 v[230:231], off
	s_waitcnt vmcnt(8)
	s_waitcnt lgkmcnt(0)
	s_andn2_b64 vcc, exec, s[18:19]
	s_barrier
	s_cbranch_vccnz .LBB0_800
; #define PG8_MMA(ai, bj, At, Bt) do { __builtin_amdgcn_s_setprio(1); _Pragma("unroll") for (int m = 0; m < 4; ++m) _Pragma("unroll") for (int n = 0; n < 2; ++n) _Pragma("unroll") for (int k = 0; k < 2; ++k) \
;         acc[ai][bj][m][n] = mma16_<Epi::BF16>(Bt[n][k], At[m][k], acc[ai][bj][m][n]); __builtin_amdgcn_s_setprio(0); } while (0)
; #define PG8_WAIT_V(n) asm volatile("s_waitcnt vmcnt(" #n ")" ::: "memory")
; #define PG8_WAIT_L(n) asm volatile("s_waitcnt lgkmcnt(" #n ")" ::: "memory")
; #define PG8_BAR __builtin_amdgcn_s_barrier()
; #define PG8_SCHED __builtin_amdgcn_sched_barrier(0)
;     ...
;             PG8_WAIT_V(8); PG8_WAIT_L(0); PG8_BAR; if (!cur.half) { PG8_MMA(1, 0, At, B0); PG8_MMA(1, 1, At, B1); } PG8_BAR; PG8_SCHED;
	s_setprio 1
	v_mfma_f32_16x16x32_f16 v[64:67], v[148:151], v[188:191], v[64:67]
	v_mfma_f32_16x16x32_f16 v[60:63], v[156:159], v[188:191], v[60:63]
	v_mfma_f32_16x16x32_f16 v[48:51], v[148:151], v[180:183], v[48:51]
	v_mfma_f32_16x16x32_f16 v[44:47], v[156:159], v[180:183], v[44:47]
	v_mfma_f32_16x16x32_f16 v[32:35], v[148:151], v[172:175], v[32:35]
	v_mfma_f32_16x16x32_f16 v[28:31], v[156:159], v[172:175], v[28:31]
	v_mfma_f32_16x16x32_f16 v[16:19], v[148:151], v[164:167], v[16:19]
	v_mfma_f32_16x16x32_f16 v[12:15], v[156:159], v[164:167], v[12:15]
	v_mfma_f32_16x16x32_f16 v[64:67], v[152:155], v[192:195], v[64:67]
	v_mfma_f32_16x16x32_f16 v[60:63], v[160:163], v[192:195], v[60:63]
	v_mfma_f32_16x16x32_f16 v[48:51], v[152:155], v[184:187], v[48:51]
	v_mfma_f32_16x16x32_f16 v[44:47], v[160:163], v[184:187], v[44:47]
	v_mfma_f32_16x16x32_f16 v[32:35], v[152:155], v[176:179], v[32:35]
	v_mfma_f32_16x16x32_f16 v[28:31], v[160:163], v[176:179], v[28:31]
	v_mfma_f32_16x16x32_f16 v[16:19], v[152:155], v[168:171], v[16:19]
	v_mfma_f32_16x16x32_f16 v[12:15], v[160:163], v[168:171], v[12:15]
	s_setprio 0
	s_setprio 1
	v_mfma_f32_16x16x32_f16 v[56:59], v[132:135], v[188:191], v[56:59]
	v_mfma_f32_16x16x32_f16 v[52:55], v[140:143], v[188:191], v[52:55]
	v_mfma_f32_16x16x32_f16 v[40:43], v[132:135], v[180:183], v[40:43]
	v_mfma_f32_16x16x32_f16 v[36:39], v[140:143], v[180:183], v[36:39]
	v_mfma_f32_16x16x32_f16 v[24:27], v[132:135], v[172:175], v[24:27]
	v_mfma_f32_16x16x32_f16 v[20:23], v[140:143], v[172:175], v[20:23]
	v_mfma_f32_16x16x32_f16 v[8:11], v[132:135], v[164:167], v[8:11]
	v_mfma_f32_16x16x32_f16 v[4:7], v[140:143], v[164:167], v[4:7]
	v_mfma_f32_16x16x32_f16 v[56:59], v[136:139], v[192:195], v[56:59]
	v_mfma_f32_16x16x32_f16 v[52:55], v[144:147], v[192:195], v[52:55]
	v_mfma_f32_16x16x32_f16 v[40:43], v[136:139], v[184:187], v[40:43]
	v_mfma_f32_16x16x32_f16 v[36:39], v[144:147], v[184:187], v[36:39]
	v_mfma_f32_16x16x32_f16 v[24:27], v[136:139], v[176:179], v[24:27]
	v_mfma_f32_16x16x32_f16 v[20:23], v[144:147], v[176:179], v[20:23]
	v_mfma_f32_16x16x32_f16 v[8:11], v[136:139], v[168:171], v[8:11]
	v_mfma_f32_16x16x32_f16 v[4:7], v[144:147], v[168:171], v[4:7]
	s_setprio 0
; #define PG8_STAGE(bufoff, gbase, voff) do { _Pragma("unroll") for (int _i = 0; _i < 2; ++_i) \
;         __builtin_amdgcn_global_load_lds((const unsigned*)((const char*)(gbase) + (voff)[_i]), (LAS unsigned*)(lds + (bufoff) + ldsw + _i * 8192), 16, 0, 0); } while (0)
; #define PG8_LDA(dst, b, h) do { _Pragma("unroll") for (int m = 0; m < 4; ++m) _Pragma("unroll") for (int k = 0; k < 2; ++k) dst[m][k] = *(const LAS f16x8*)(lds + PG8_SA(b, h) + aoff + m * 2048 + k * 1024); } while (0)
; #define PG8_LDB(dst, b, h) do { _Pragma("unroll") for (int n = 0; n < 2; ++n) _Pragma("unroll") for (int k = 0; k < 2; ++k) dst[n][k] = *(const LAS f16x8*)(lds + PG8_SB(b, h) + boff + n * 2048 + k * 1024); } while (0)
; #define PG8_MMA(ai, bj, At, Bt) do { __builtin_amdgcn_s_setprio(1); _Pragma("unroll") for (int m = 0; m < 4; ++m) _Pragma("unroll") for (int n = 0; n < 2; ++n) _Pragma("unroll") for (int k = 0; k < 2; ++k) \
;         acc[ai][bj][m][n] = mma16_<Epi::BF16>(Bt[n][k], At[m][k], acc[ai][bj][m][n]); __builtin_amdgcn_s_setprio(0); } while (0)
; #define PG8_WAIT_V(n) asm volatile("s_waitcnt vmcnt(" #n ")" ::: "memory")
; #define PG8_WAIT_L(n) asm volatile("s_waitcnt lgkmcnt(" #n ")" ::: "memory")
; #define PG8_BAR __builtin_amdgcn_s_barrier()
; #define PG8_SCHED __builtin_amdgcn_sched_barrier(0)
;     ...
;             PG8_LDB(B0, 1, 0); PG8_LDB(B1, 1, 1); PG8_SCHED; PG8_LDA(At, 1, 0); PG8_STAGE(PG8_SA(0, 1), a2 + hA, voffA);
;             PG8_WAIT_V(8); PG8_WAIT_L(0); PG8_BAR; PG8_MMA(0, 0, At, B0); PG8_MMA(0, 1, At, B1); PG8_BAR; PG8_SCHED;
;             PG8_LDA(At, 1, 1); PG8_STAGE(PG8_SB(1, 0), b3, voffB); PG8_STAGE(PG8_SB(1, 1), b3 + hB, voffB); PG8_STAGE(PG8_SA(1, 0), a3, voffA);
;             PG8_WAIT_V(8); PG8_WAIT_L(0); PG8_BAR; if (!cur.half) { PG8_MMA(1, 0, At, B0); PG8_MMA(1, 1, At, B1); } PG8_BAR; PG8_SCHED;
.LBB0_800:
	s_barrier
	s_add_i32 s24, 0, 0x18000
	v_add_u32_e32 v0, s24, v233
	s_add_i32 s25, 0, 0x1c000
	ds_read_b128 v[148:151], v0
	ds_read_b128 v[152:155], v0 offset:1024
	ds_read_b128 v[156:159], v0 offset:2048
	ds_read_b128 v[160:163], v0 offset:3072
	v_add_u32_e32 v0, s25, v233
	ds_read_b128 v[132:135], v0
	ds_read_b128 v[136:139], v0 offset:1024
	ds_read_b128 v[140:143], v0 offset:2048
	ds_read_b128 v[144:147], v0 offset:3072
	s_add_u32 s22, s22, 0x1a0000
	s_addc_u32 s23, s23, 0
	s_mov_b32 m0, s29
	v_lshl_add_u64 v[200:201], s[22:23], 0, v[214:215]
	s_waitcnt lgkmcnt(0)
	ds_read_b128 v[164:167], v243 offset:32768
	ds_read_b128 v[168:171], v243 offset:33792
	ds_read_b128 v[172:175], v243 offset:34816
	ds_read_b128 v[176:179], v243 offset:35840
	ds_read_b128 v[180:183], v243 offset:36864
	ds_read_b128 v[184:187], v243 offset:37888
	ds_read_b128 v[188:191], v243 offset:38912
	ds_read_b128 v[192:195], v243 offset:39936
	global_load_lds_dwordx4 v[200:201], off
	v_lshl_add_u64 v[200:201], s[22:23], 0, v[218:219]
	s_mov_b32 m0, s30
	s_nop 0
	global_load_lds_dwordx4 v[200:201], off
	s_waitcnt vmcnt(8)
	s_waitcnt lgkmcnt(0)
	s_barrier
	s_setprio 1
	v_mfma_f32_16x16x32_f16 v[128:131], v[148:151], v[164:167], v[128:131]
	v_mfma_f32_16x16x32_f16 v[124:127], v[156:159], v[164:167], v[124:127]
	v_mfma_f32_16x16x32_f16 v[112:115], v[148:151], v[172:175], v[112:115]
	v_mfma_f32_16x16x32_f16 v[108:111], v[156:159], v[172:175], v[108:111]
	v_mfma_f32_16x16x32_f16 v[96:99], v[148:151], v[180:183], v[96:99]
	v_mfma_f32_16x16x32_f16 v[92:95], v[156:159], v[180:183], v[92:95]
	v_mfma_f32_16x16x32_f16 v[80:83], v[148:151], v[188:191], v[80:83]
	v_mfma_f32_16x16x32_f16 v[76:79], v[156:159], v[188:191], v[76:79]
	v_mfma_f32_16x16x32_f16 v[128:131], v[152:155], v[168:171], v[128:131]
	v_mfma_f32_16x16x32_f16 v[124:127], v[160:163], v[168:171], v[124:127]
	v_mfma_f32_16x16x32_f16 v[112:115], v[152:155], v[176:179], v[112:115]
	v_mfma_f32_16x16x32_f16 v[108:111], v[160:163], v[176:179], v[108:111]
	v_mfma_f32_16x16x32_f16 v[96:99], v[152:155], v[184:187], v[96:99]
	v_mfma_f32_16x16x32_f16 v[92:95], v[160:163], v[184:187], v[92:95]
	v_mfma_f32_16x16x32_f16 v[80:83], v[152:155], v[192:195], v[80:83]
	v_mfma_f32_16x16x32_f16 v[76:79], v[160:163], v[192:195], v[76:79]
	s_setprio 0
	s_setprio 1
	v_mfma_f32_16x16x32_f16 v[120:123], v[132:135], v[164:167], v[120:123]
	v_mfma_f32_16x16x32_f16 v[116:119], v[140:143], v[164:167], v[116:119]
	v_mfma_f32_16x16x32_f16 v[104:107], v[132:135], v[172:175], v[104:107]
	v_mfma_f32_16x16x32_f16 v[100:103], v[140:143], v[172:175], v[100:103]
	v_mfma_f32_16x16x32_f16 v[88:91], v[132:135], v[180:183], v[88:91]
	v_mfma_f32_16x16x32_f16 v[84:87], v[140:143], v[180:183], v[84:87]
	v_mfma_f32_16x16x32_f16 v[72:75], v[132:135], v[188:191], v[72:75]
	v_mfma_f32_16x16x32_f16 v[68:71], v[140:143], v[188:191], v[68:71]
	v_mfma_f32_16x16x32_f16 v[120:123], v[136:139], v[168:171], v[120:123]
	v_mfma_f32_16x16x32_f16 v[116:119], v[144:147], v[168:171], v[116:119]
	v_mfma_f32_16x16x32_f16 v[104:107], v[136:139], v[176:179], v[104:107]
	v_mfma_f32_16x16x32_f16 v[100:103], v[144:147], v[176:179], v[100:103]
	v_mfma_f32_16x16x32_f16 v[88:91], v[136:139], v[184:187], v[88:91]
	v_mfma_f32_16x16x32_f16 v[84:87], v[144:147], v[184:187], v[84:87]
	v_mfma_f32_16x16x32_f16 v[72:75], v[136:139], v[192:195], v[72:75]
	v_mfma_f32_16x16x32_f16 v[68:71], v[144:147], v[192:195], v[68:71]
	s_setprio 0
	s_barrier
	s_add_i32 s22, s24, s27
	v_lshl_add_u64 v[2:3], v[2:3], 0, s[96:97]
	s_mov_b32 m0, s22
	ds_read_b128 v[188:191], v243 offset:49152
	ds_read_b128 v[192:195], v243 offset:50176
	ds_read_b128 v[180:183], v243 offset:51200
	ds_read_b128 v[184:187], v243 offset:52224
	ds_read_b128 v[172:175], v243 offset:53248
	ds_read_b128 v[176:179], v243 offset:54272
	ds_read_b128 v[164:167], v243 offset:55296
	ds_read_b128 v[168:171], v243 offset:56320
	global_load_lds_dwordx4 v[2:3], off
	s_add_i32 m0, s22, 0x2000
	s_add_u32 s20, s20, 0x40080
	v_lshl_add_u64 v[2:3], v[226:227], 0, s[96:97]
	s_addc_u32 s21, s21, 0
	s_add_i32 s22, s25, s27
	global_load_lds_dwordx4 v[2:3], off
	v_lshl_add_u64 v[2:3], s[20:21], 0, v[216:217]
	s_mov_b32 m0, s22
	s_and_b64 vcc, exec, s[40:41]
	global_load_lds_dwordx4 v[2:3], off
	v_lshl_add_u64 v[2:3], s[20:21], 0, v[220:221]
	s_add_i32 m0, s22, 0x2000
	s_nop 0
	global_load_lds_dwordx4 v[2:3], off
	v_lshl_add_u64 v[2:3], v[228:229], 0, s[96:97]
	s_mov_b32 m0, s31
	s_nop 0
	global_load_lds_dwordx4 v[2:3], off
	v_lshl_add_u64 v[2:3], v[230:231], 0, s[96:97]
	s_mov_b32 m0, s34
	s_nop 0
	global_load_lds_dwordx4 v[2:3], off
	s_waitcnt vmcnt(8)
	s_waitcnt lgkmcnt(0)
	s_barrier
	s_cbranch_vccnz .LBB0_797
	s_setprio 1
	v_mfma_f32_16x16x32_f16 v[64:67], v[148:151], v[188:191], v[64:67]
	v_mfma_f32_16x16x32_f16 v[60:63], v[156:159], v[188:191], v[60:63]
	v_mfma_f32_16x16x32_f16 v[48:51], v[148:151], v[180:183], v[48:51]
	v_mfma_f32_16x16x32_f16 v[44:47], v[156:159], v[180:183], v[44:47]
	v_mfma_f32_16x16x32_f16 v[32:35], v[148:151], v[172:175], v[32:35]
	v_mfma_f32_16x16x32_f16 v[28:31], v[156:159], v[172:175], v[28:31]
	v_mfma_f32_16x16x32_f16 v[16:19], v[148:151], v[164:167], v[16:19]
	v_mfma_f32_16x16x32_f16 v[12:15], v[156:159], v[164:167], v[12:15]
	v_mfma_f32_16x16x32_f16 v[64:67], v[152:155], v[192:195], v[64:67]
	v_mfma_f32_16x16x32_f16 v[60:63], v[160:163], v[192:195], v[60:63]
	v_mfma_f32_16x16x32_f16 v[48:51], v[152:155], v[184:187], v[48:51]
	v_mfma_f32_16x16x32_f16 v[44:47], v[160:163], v[184:187], v[44:47]
	v_mfma_f32_16x16x32_f16 v[32:35], v[152:155], v[176:179], v[32:35]
	v_mfma_f32_16x16x32_f16 v[28:31], v[160:163], v[176:179], v[28:31]
	v_mfma_f32_16x16x32_f16 v[16:19], v[152:155], v[168:171], v[16:19]
	v_mfma_f32_16x16x32_f16 v[12:15], v[160:163], v[168:171], v[12:15]
	s_setprio 0
	s_setprio 1
	v_mfma_f32_16x16x32_f16 v[56:59], v[132:135], v[188:191], v[56:59]
	v_mfma_f32_16x16x32_f16 v[52:55], v[140:143], v[188:191], v[52:55]
	v_mfma_f32_16x16x32_f16 v[40:43], v[132:135], v[180:183], v[40:43]
	v_mfma_f32_16x16x32_f16 v[36:39], v[140:143], v[180:183], v[36:39]
	v_mfma_f32_16x16x32_f16 v[24:27], v[132:135], v[172:175], v[24:27]
	v_mfma_f32_16x16x32_f16 v[20:23], v[140:143], v[172:175], v[20:23]
	v_mfma_f32_16x16x32_f16 v[8:11], v[132:135], v[164:167], v[8:11]
	v_mfma_f32_16x16x32_f16 v[2:5], v[140:143], v[164:167], v[4:7]
	v_mfma_f32_16x16x32_f16 v[56:59], v[136:139], v[192:195], v[56:59]
	v_mfma_f32_16x16x32_f16 v[52:55], v[144:147], v[192:195], v[52:55]
	v_mfma_f32_16x16x32_f16 v[40:43], v[136:139], v[184:187], v[40:43]
	v_mfma_f32_16x16x32_f16 v[36:39], v[144:147], v[184:187], v[36:39]
	v_mfma_f32_16x16x32_f16 v[24:27], v[136:139], v[176:179], v[24:27]
	v_mfma_f32_16x16x32_f16 v[20:23], v[144:147], v[176:179], v[20:23]
	v_mfma_f32_16x16x32_f16 v[8:11], v[136:139], v[168:171], v[8:11]
	v_mfma_f32_16x16x32_f16 v[4:7], v[144:147], v[168:171], v[2:5]
	s_setprio 0
	s_branch .LBB0_797

; #define PG8_STAGE(bufoff, gbase, voff) do { _Pragma("unroll") for (int _i = 0; _i < 2; ++_i) \
;         __builtin_amdgcn_global_load_lds((const unsigned*)((const char*)(gbase) + (voff)[_i]), (LAS unsigned*)(lds + (bufoff) + ldsw + _i * 8192), 16, 0, 0); } while (0)
; #define PG8_LDA(dst, b, h) do { _Pragma("unroll") for (int m = 0; m < 4; ++m) _Pragma("unroll") for (int k = 0; k < 2; ++k) dst[m][k] = *(const LAS f16x8*)(lds + PG8_SA(b, h) + aoff + m * 2048 + k * 1024); } while (0)
; #define PG8_LDB(dst, b, h) do { _Pragma("unroll") for (int n = 0; n < 2; ++n) _Pragma("unroll") for (int k = 0; k < 2; ++k) dst[n][k] = *(const LAS f16x8*)(lds + PG8_SB(b, h) + boff + n * 2048 + k * 1024); } while (0)
; #define PG8_MMA(ai, bj, At, Bt) do { __builtin_amdgcn_s_setprio(1); _Pragma("unroll") for (int m = 0; m < 4; ++m) _Pragma("unroll") for (int n = 0; n < 2; ++n) _Pragma("unroll") for (int k = 0; k < 2; ++k) \
;         acc[ai][bj][m][n] = mma16_<Epi::BF16>(Bt[n][k], At[m][k], acc[ai][bj][m][n]); __builtin_amdgcn_s_setprio(0); } while (0)
; #define PG8_WAIT_V(n) asm volatile("s_waitcnt vmcnt(" #n ")" ::: "memory")
; #define PG8_WAIT_L(n) asm volatile("s_waitcnt lgkmcnt(" #n ")" ::: "memory")
; #define PG8_BAR __builtin_amdgcn_s_barrier()
;     ...
;         const char* nA = has_next ? (const char*)g.A + (size_t)nxt.pm * tA + (nxt.roff ? hA : (size_t)0) : cA; const char* nB = has_next ? (const char*)g.Bt + (size_t)nxt.pn * tB : cB;
;         for (int t = 0; t < nt; t += 2) {
;             const bool last = (t == nt - 2);
;             const char* a1 = cA + (size_t)(t + 1) * kstep;
;             const char* a2 = last ? nA : cA + (size_t)(t + 2) * kstep; const char* b2 = last ? nB : cB + (size_t)(t + 2) * kstep;
;             const char* a3 = a2 + kstep; const char* b3 = b2 + kstep;
;             if constexpr (SP2) {
;             PG8_LDB(B0, 0, 0); PG8_LDB(B1, 0, 1); PG8_SCHED; PG8_LDA(At, 0, 0); PG8_STAGE(PG8_SA(1, 1), a1 + hA, voffA);
;             PG8_WAIT_V(8); PG8_WAIT_L(0); PG8_BAR; PG8_MMA(0, 0, At, B0); PG8_MMA(0, 1, At, B1); PG8_BAR; PG8_SCHED;
;             PG8_LDA(At, 0, 1); PG8_STAGE(PG8_SB(0, 0), b2, voffB); PG8_STAGE(PG8_SB(0, 1), b2 + hB, voffB); PG8_STAGE(PG8_SA(0, 0), a2, voffA);
;             PG8_WAIT_V(8); PG8_WAIT_L(0); PG8_BAR; if (!cur.half) { PG8_MMA(1, 0, At, B0); PG8_MMA(1, 1, At, B1); } PG8_BAR; PG8_SCHED;
.LBB0_886:
	s_add_u32 s25, s36, 0xfffc0080
	s_addc_u32 s27, s37, -1
	s_add_i32 s40, 0, 0x10000
	s_cmp_eq_u32 s14, 12
	s_cselect_b32 s45, s29, s27
	s_cselect_b32 s44, s28, s25
	s_waitcnt lgkmcnt(0)
	v_add_u32_e32 v106, s40, v244
	s_cselect_b32 s43, s2, s11
	s_cselect_b32 s42, s3, s9
	s_add_i32 s25, 0, 0x14000
	ds_read_b128 v[154:157], v106
	ds_read_b128 v[158:161], v106 offset:1024
	ds_read_b128 v[162:165], v106 offset:2048
	ds_read_b128 v[166:169], v106 offset:3072
	v_add_u32_e32 v106, s25, v244
	ds_read_b128 v[138:141], v106
	ds_read_b128 v[142:145], v106 offset:1024
	ds_read_b128 v[146:149], v106 offset:2048
	ds_read_b128 v[150:153], v106 offset:3072
	v_lshl_add_u64 v[106:107], s[36:37], 0, v[222:223]
	s_add_i32 m0, s51, 0xc000
	ds_read_b128 v[170:173], v245
	ds_read_b128 v[174:177], v245 offset:1024
	ds_read_b128 v[178:181], v245 offset:2048
	ds_read_b128 v[182:185], v245 offset:3072
	ds_read_b128 v[186:189], v245 offset:4096
	ds_read_b128 v[190:193], v245 offset:5120
	ds_read_b128 v[226:229], v245 offset:6144
	ds_read_b128 v[230:233], v245 offset:7168
	global_load_lds_dwordx4 v[106:107], off
	v_lshl_add_u64 v[106:107], s[36:37], 0, v[224:225]
	s_add_i32 m0, s51, 0xe000
	s_nop 0
	global_load_lds_dwordx4 v[106:107], off
	s_waitcnt vmcnt(8)
	s_waitcnt lgkmcnt(0)
	s_barrier
	s_setprio 1
	v_mfma_f32_16x16x32_bf16 v[106:109], v[154:157], v[170:173], v[134:137]
	v_mfma_f32_16x16x32_bf16 v[110:113], v[162:165], v[170:173], v[130:133]
	v_mfma_f32_16x16x32_bf16 v[126:129], v[154:157], v[178:181], v[126:129]
	v_mfma_f32_16x16x32_bf16 v[122:125], v[162:165], v[178:181], v[122:125]
	v_mfma_f32_16x16x32_bf16 v[118:121], v[154:157], v[186:189], v[118:121]
	v_mfma_f32_16x16x32_bf16 v[114:117], v[162:165], v[186:189], v[114:117]
	v_mfma_f32_16x16x32_bf16 v[102:105], v[154:157], v[226:229], v[102:105]
	v_mfma_f32_16x16x32_bf16 v[98:101], v[162:165], v[226:229], v[98:101]
	v_mfma_f32_16x16x32_bf16 v[106:109], v[158:161], v[174:177], v[106:109]
	v_mfma_f32_16x16x32_bf16 v[110:113], v[166:169], v[174:177], v[110:113]
	v_mfma_f32_16x16x32_bf16 v[126:129], v[158:161], v[182:185], v[126:129]
	v_mfma_f32_16x16x32_bf16 v[122:125], v[166:169], v[182:185], v[122:125]
	v_mfma_f32_16x16x32_bf16 v[118:121], v[158:161], v[190:193], v[118:121]
	v_mfma_f32_16x16x32_bf16 v[114:117], v[166:169], v[190:193], v[114:117]
	v_mfma_f32_16x16x32_bf16 v[102:105], v[158:161], v[230:233], v[102:105]
	v_mfma_f32_16x16x32_bf16 v[98:101], v[166:169], v[230:233], v[98:101]
	s_setprio 0
	s_setprio 1
	v_mfma_f32_16x16x32_bf16 v[70:73], v[138:141], v[170:173], v[70:73]
	v_mfma_f32_16x16x32_bf16 v[66:69], v[146:149], v[170:173], v[66:69]
	v_mfma_f32_16x16x32_bf16 v[58:61], v[138:141], v[178:181], v[58:61]
	v_mfma_f32_16x16x32_bf16 v[50:53], v[146:149], v[178:181], v[50:53]
	v_mfma_f32_16x16x32_bf16 v[46:49], v[138:141], v[186:189], v[46:49]
	v_mfma_f32_16x16x32_bf16 v[42:45], v[146:149], v[186:189], v[42:45]
	v_mfma_f32_16x16x32_bf16 v[38:41], v[138:141], v[226:229], v[38:41]
	v_mfma_f32_16x16x32_bf16 v[34:37], v[146:149], v[226:229], v[34:37]
	v_mfma_f32_16x16x32_bf16 v[70:73], v[142:145], v[174:177], v[70:73]
	v_mfma_f32_16x16x32_bf16 v[66:69], v[150:153], v[174:177], v[66:69]
	v_mfma_f32_16x16x32_bf16 v[58:61], v[142:145], v[182:185], v[58:61]
	v_mfma_f32_16x16x32_bf16 v[50:53], v[150:153], v[182:185], v[50:53]
	v_mfma_f32_16x16x32_bf16 v[46:49], v[142:145], v[190:193], v[46:49]
	v_mfma_f32_16x16x32_bf16 v[42:45], v[150:153], v[190:193], v[42:45]
	v_mfma_f32_16x16x32_bf16 v[38:41], v[142:145], v[230:233], v[38:41]
	v_mfma_f32_16x16x32_bf16 v[34:37], v[150:153], v[230:233], v[34:37]
	s_setprio 0
	s_barrier
	s_add_i32 s27, s40, s50
	v_lshl_add_u64 v[226:227], s[42:43], 0, v[214:215]
	s_mov_b32 m0, s27
	ds_read_b128 v[186:189], v245 offset:16384
	ds_read_b128 v[190:193], v245 offset:17408
	ds_read_b128 v[178:181], v245 offset:18432
	ds_read_b128 v[182:185], v245 offset:19456
	ds_read_b128 v[170:173], v245 offset:20480
	ds_read_b128 v[174:177], v245 offset:21504
	ds_read_b128 v[130:133], v245 offset:22528
	ds_read_b128 v[134:137], v245 offset:23552
	global_load_lds_dwordx4 v[226:227], off
	s_add_i32 m0, s27, 0x2000
	s_add_u32 s40, s42, 0x40000
	v_lshl_add_u64 v[228:229], s[42:43], 0, v[218:219]
	s_addc_u32 s41, s43, 0
	s_add_i32 s25, s25, s50
	global_load_lds_dwordx4 v[228:229], off
	v_lshl_add_u64 v[200:201], s[40:41], 0, v[214:215]
	s_mov_b32 m0, s25
	v_lshl_add_u64 v[230:231], s[44:45], 0, v[194:195]
	global_load_lds_dwordx4 v[200:201], off
	v_lshl_add_u64 v[200:201], s[40:41], 0, v[218:219]
	s_add_i32 m0, s25, 0x2000
	v_lshl_add_u64 v[232:233], s[44:45], 0, v[216:217]
	global_load_lds_dwordx4 v[200:201], off
	s_mov_b32 m0, s51
	v_cndmask_b32_e64 v200, 0, 1, s[34:35]
	global_load_lds_dwordx4 v[230:231], off
	s_mov_b32 m0, s52
	v_cmp_ne_u32_e64 s[40:41], 1, v200
	global_load_lds_dwordx4 v[232:233], off
	s_waitcnt vmcnt(8)
	s_waitcnt lgkmcnt(0)
	s_andn2_b64 vcc, exec, s[34:35]
	s_barrier
	s_cbranch_vccnz .LBB0_888
; #define PG8_MMA(ai, bj, At, Bt) do { __builtin_amdgcn_s_setprio(1); _Pragma("unroll") for (int m = 0; m < 4; ++m) _Pragma("unroll") for (int n = 0; n < 2; ++n) _Pragma("unroll") for (int k = 0; k < 2; ++k) \
;         acc[ai][bj][m][n] = mma16_<Epi::BF16>(Bt[n][k], At[m][k], acc[ai][bj][m][n]); __builtin_amdgcn_s_setprio(0); } while (0)
; #define PG8_WAIT_V(n) asm volatile("s_waitcnt vmcnt(" #n ")" ::: "memory")
; #define PG8_WAIT_L(n) asm volatile("s_waitcnt lgkmcnt(" #n ")" ::: "memory")
; #define PG8_BAR __builtin_amdgcn_s_barrier()
; #define PG8_SCHED __builtin_amdgcn_sched_barrier(0)
;     ...
;             PG8_WAIT_V(8); PG8_WAIT_L(0); PG8_BAR; if (!cur.half) { PG8_MMA(1, 0, At, B0); PG8_MMA(1, 1, At, B1); } PG8_BAR; PG8_SCHED;
	s_setprio 1
	v_mfma_f32_16x16x32_bf16 v[94:97], v[154:157], v[186:189], v[94:97]
	v_mfma_f32_16x16x32_bf16 v[90:93], v[162:165], v[186:189], v[90:93]
	v_mfma_f32_16x16x32_bf16 v[86:89], v[154:157], v[178:181], v[86:89]
	v_mfma_f32_16x16x32_bf16 v[82:85], v[162:165], v[178:181], v[82:85]
	v_mfma_f32_16x16x32_bf16 v[78:81], v[154:157], v[170:173], v[78:81]
	v_mfma_f32_16x16x32_bf16 v[74:77], v[162:165], v[170:173], v[74:77]
	v_mfma_f32_16x16x32_bf16 v[62:65], v[154:157], v[130:133], v[62:65]
	v_mfma_f32_16x16x32_bf16 v[54:57], v[162:165], v[130:133], v[54:57]
	v_mfma_f32_16x16x32_bf16 v[94:97], v[158:161], v[190:193], v[94:97]
	v_mfma_f32_16x16x32_bf16 v[90:93], v[166:169], v[190:193], v[90:93]
	v_mfma_f32_16x16x32_bf16 v[86:89], v[158:161], v[182:185], v[86:89]
	v_mfma_f32_16x16x32_bf16 v[82:85], v[166:169], v[182:185], v[82:85]
	v_mfma_f32_16x16x32_bf16 v[78:81], v[158:161], v[174:177], v[78:81]
	v_mfma_f32_16x16x32_bf16 v[74:77], v[166:169], v[174:177], v[74:77]
	v_mfma_f32_16x16x32_bf16 v[62:65], v[158:161], v[134:137], v[62:65]
	v_mfma_f32_16x16x32_bf16 v[54:57], v[166:169], v[134:137], v[54:57]
	s_setprio 0
	s_setprio 1
	v_mfma_f32_16x16x32_bf16 v[30:33], v[138:141], v[186:189], v[30:33]
	v_mfma_f32_16x16x32_bf16 v[26:29], v[146:149], v[186:189], v[26:29]
	v_mfma_f32_16x16x32_bf16 v[22:25], v[138:141], v[178:181], v[22:25]
	v_mfma_f32_16x16x32_bf16 v[18:21], v[146:149], v[178:181], v[18:21]
	v_mfma_f32_16x16x32_bf16 v[14:17], v[138:141], v[170:173], v[14:17]
	v_mfma_f32_16x16x32_bf16 v[10:13], v[146:149], v[170:173], v[10:13]
	v_mfma_f32_16x16x32_bf16 v[6:9], v[138:141], v[130:133], v[6:9]
	v_mfma_f32_16x16x32_bf16 v[2:5], v[146:149], v[130:133], v[2:5]
	v_mfma_f32_16x16x32_bf16 v[30:33], v[142:145], v[190:193], v[30:33]
	v_mfma_f32_16x16x32_bf16 v[26:29], v[150:153], v[190:193], v[26:29]
	v_mfma_f32_16x16x32_bf16 v[22:25], v[142:145], v[182:185], v[22:25]
	v_mfma_f32_16x16x32_bf16 v[18:21], v[150:153], v[182:185], v[18:21]
	v_mfma_f32_16x16x32_bf16 v[14:17], v[142:145], v[174:177], v[14:17]
	v_mfma_f32_16x16x32_bf16 v[10:13], v[150:153], v[174:177], v[10:13]
	v_mfma_f32_16x16x32_bf16 v[6:9], v[142:145], v[134:137], v[6:9]
	v_mfma_f32_16x16x32_bf16 v[2:5], v[150:153], v[134:137], v[2:5]
	s_setprio 0
; #define PG8_STAGE(bufoff, gbase, voff) do { _Pragma("unroll") for (int _i = 0; _i < 2; ++_i) \
;         __builtin_amdgcn_global_load_lds((const unsigned*)((const char*)(gbase) + (voff)[_i]), (LAS unsigned*)(lds + (bufoff) + ldsw + _i * 8192), 16, 0, 0); } while (0)
; #define PG8_LDA(dst, b, h) do { _Pragma("unroll") for (int m = 0; m < 4; ++m) _Pragma("unroll") for (int k = 0; k < 2; ++k) dst[m][k] = *(const LAS f16x8*)(lds + PG8_SA(b, h) + aoff + m * 2048 + k * 1024); } while (0)
; #define PG8_LDB(dst, b, h) do { _Pragma("unroll") for (int n = 0; n < 2; ++n) _Pragma("unroll") for (int k = 0; k < 2; ++k) dst[n][k] = *(const LAS f16x8*)(lds + PG8_SB(b, h) + boff + n * 2048 + k * 1024); } while (0)
; #define PG8_MMA(ai, bj, At, Bt) do { __builtin_amdgcn_s_setprio(1); _Pragma("unroll") for (int m = 0; m < 4; ++m) _Pragma("unroll") for (int n = 0; n < 2; ++n) _Pragma("unroll") for (int k = 0; k < 2; ++k) \
;         acc[ai][bj][m][n] = mma16_<Epi::BF16>(Bt[n][k], At[m][k], acc[ai][bj][m][n]); __builtin_amdgcn_s_setprio(0); } while (0)
; #define PG8_WAIT_V(n) asm volatile("s_waitcnt vmcnt(" #n ")" ::: "memory")
; #define PG8_WAIT_L(n) asm volatile("s_waitcnt lgkmcnt(" #n ")" ::: "memory")
; #define PG8_BAR __builtin_amdgcn_s_barrier()
; #define PG8_SCHED __builtin_amdgcn_sched_barrier(0)
;     ...
;             PG8_LDB(B0, 1, 0); PG8_LDB(B1, 1, 1); PG8_SCHED; PG8_LDA(At, 1, 0); PG8_STAGE(PG8_SA(0, 1), a2 + hA, voffA);
;             PG8_WAIT_V(8); PG8_WAIT_L(0); PG8_BAR; PG8_MMA(0, 0, At, B0); PG8_MMA(0, 1, At, B1); PG8_BAR; PG8_SCHED;
;             PG8_LDA(At, 1, 1); PG8_STAGE(PG8_SB(1, 0), b3, voffB); PG8_STAGE(PG8_SB(1, 1), b3 + hB, voffB); PG8_STAGE(PG8_SA(1, 0), a3, voffA);
;             PG8_WAIT_V(8); PG8_WAIT_L(0); PG8_BAR; if (!cur.half) { PG8_MMA(1, 0, At, B0); PG8_MMA(1, 1, At, B1); } PG8_BAR; PG8_SCHED;
.LBB0_888:
	s_barrier
	s_add_i32 s25, 0, 0x18000
	s_waitcnt lgkmcnt(0)
	v_add_u32_e32 v130, s25, v244
	s_add_i32 s27, 0, 0x1c000
	ds_read_b128 v[154:157], v130
	ds_read_b128 v[158:161], v130 offset:1024
	ds_read_b128 v[162:165], v130 offset:2048
	ds_read_b128 v[166:169], v130 offset:3072
	v_add_u32_e32 v130, s27, v244
	ds_read_b128 v[138:141], v130
	ds_read_b128 v[142:145], v130 offset:1024
	ds_read_b128 v[146:149], v130 offset:2048
	ds_read_b128 v[150:153], v130 offset:3072
	s_add_u32 s44, s44, 0x40000
	s_addc_u32 s45, s45, 0
	s_mov_b32 m0, s53
	v_lshl_add_u64 v[130:131], s[44:45], 0, v[194:195]
	ds_read_b128 v[170:173], v245 offset:32768
	ds_read_b128 v[174:177], v245 offset:33792
	ds_read_b128 v[178:181], v245 offset:34816
	ds_read_b128 v[182:185], v245 offset:35840
	ds_read_b128 v[186:189], v245 offset:36864
	ds_read_b128 v[190:193], v245 offset:37888
	ds_read_b128 v[246:249], v245 offset:38912
	ds_read_b128 v[200:203], v245 offset:39936
	global_load_lds_dwordx4 v[130:131], off
	v_lshl_add_u64 v[130:131], s[44:45], 0, v[216:217]
	s_mov_b32 m0, s54
	s_nop 0
	global_load_lds_dwordx4 v[130:131], off
	s_waitcnt vmcnt(8)
	s_waitcnt lgkmcnt(0)
	s_barrier
	s_setprio 1
	v_mfma_f32_16x16x32_bf16 v[106:109], v[154:157], v[170:173], v[106:109]
	v_mfma_f32_16x16x32_bf16 v[134:137], v[158:161], v[174:177], v[106:109]
	v_mfma_f32_16x16x32_bf16 v[106:109], v[162:165], v[170:173], v[110:113]
	v_mfma_f32_16x16x32_bf16 v[130:133], v[166:169], v[174:177], v[106:109]
	v_mfma_f32_16x16x32_bf16 v[106:109], v[154:157], v[178:181], v[126:129]
	v_mfma_f32_16x16x32_bf16 v[126:129], v[158:161], v[182:185], v[106:109]
	v_mfma_f32_16x16x32_bf16 v[106:109], v[162:165], v[178:181], v[122:125]
	v_mfma_f32_16x16x32_bf16 v[122:125], v[166:169], v[182:185], v[106:109]
	v_mfma_f32_16x16x32_bf16 v[106:109], v[154:157], v[186:189], v[118:121]
	v_mfma_f32_16x16x32_bf16 v[118:121], v[158:161], v[190:193], v[106:109]
	v_mfma_f32_16x16x32_bf16 v[106:109], v[162:165], v[186:189], v[114:117]
	v_mfma_f32_16x16x32_bf16 v[102:105], v[154:157], v[246:249], v[102:105]
	v_mfma_f32_16x16x32_bf16 v[98:101], v[162:165], v[246:249], v[98:101]
	v_mfma_f32_16x16x32_bf16 v[114:117], v[166:169], v[190:193], v[106:109]
	v_mfma_f32_16x16x32_bf16 v[102:105], v[158:161], v[200:203], v[102:105]
	v_mfma_f32_16x16x32_bf16 v[98:101], v[166:169], v[200:203], v[98:101]
	s_setprio 0
	s_setprio 1
	v_mfma_f32_16x16x32_bf16 v[70:73], v[138:141], v[170:173], v[70:73]
	v_mfma_f32_16x16x32_bf16 v[66:69], v[146:149], v[170:173], v[66:69]
	v_mfma_f32_16x16x32_bf16 v[58:61], v[138:141], v[178:181], v[58:61]
	v_mfma_f32_16x16x32_bf16 v[50:53], v[146:149], v[178:181], v[50:53]
	v_mfma_f32_16x16x32_bf16 v[46:49], v[138:141], v[186:189], v[46:49]
	v_mfma_f32_16x16x32_bf16 v[42:45], v[146:149], v[186:189], v[42:45]
	v_mfma_f32_16x16x32_bf16 v[38:41], v[138:141], v[246:249], v[38:41]
	v_mfma_f32_16x16x32_bf16 v[34:37], v[146:149], v[246:249], v[34:37]
	v_mfma_f32_16x16x32_bf16 v[70:73], v[142:145], v[174:177], v[70:73]
	v_mfma_f32_16x16x32_bf16 v[66:69], v[150:153], v[174:177], v[66:69]
	v_mfma_f32_16x16x32_bf16 v[58:61], v[142:145], v[182:185], v[58:61]
	v_mfma_f32_16x16x32_bf16 v[50:53], v[150:153], v[182:185], v[50:53]
	v_mfma_f32_16x16x32_bf16 v[46:49], v[142:145], v[190:193], v[46:49]
	v_mfma_f32_16x16x32_bf16 v[42:45], v[150:153], v[190:193], v[42:45]
	v_mfma_f32_16x16x32_bf16 v[38:41], v[142:145], v[200:203], v[38:41]
	v_mfma_f32_16x16x32_bf16 v[34:37], v[150:153], v[200:203], v[34:37]
	s_setprio 0
	s_barrier
	s_add_i32 s25, s25, s50
	v_lshl_add_u64 v[200:201], v[226:227], 0, s[96:97]
	s_mov_b32 m0, s25
	ds_read_b128 v[186:189], v245 offset:49152
	ds_read_b128 v[190:193], v245 offset:50176
	ds_read_b128 v[178:181], v245 offset:51200
	ds_read_b128 v[182:185], v245 offset:52224
	ds_read_b128 v[170:173], v245 offset:53248
	ds_read_b128 v[174:177], v245 offset:54272
	ds_read_b128 v[106:109], v245 offset:55296
	ds_read_b128 v[110:113], v245 offset:56320
	global_load_lds_dwordx4 v[200:201], off
	s_add_i32 m0, s25, 0x2000
	s_add_u32 s42, s42, 0x40080
	v_lshl_add_u64 v[200:201], v[228:229], 0, s[96:97]
	s_addc_u32 s43, s43, 0
	s_add_i32 s25, s27, s50
	global_load_lds_dwordx4 v[200:201], off
	v_lshl_add_u64 v[200:201], s[42:43], 0, v[214:215]
	s_mov_b32 m0, s25
	s_and_b64 vcc, exec, s[40:41]
	global_load_lds_dwordx4 v[200:201], off
	v_lshl_add_u64 v[200:201], s[42:43], 0, v[218:219]
	s_add_i32 m0, s25, 0x2000
	s_nop 0
	global_load_lds_dwordx4 v[200:201], off
	v_lshl_add_u64 v[200:201], v[230:231], 0, s[96:97]
	s_mov_b32 m0, s57
	s_nop 0
	global_load_lds_dwordx4 v[200:201], off
	v_lshl_add_u64 v[200:201], v[232:233], 0, s[96:97]
	s_mov_b32 m0, s58
	s_nop 0
	global_load_lds_dwordx4 v[200:201], off
	s_waitcnt vmcnt(8)
	s_waitcnt lgkmcnt(0)
	s_barrier
	s_cbranch_vccnz .LBB0_885
	s_setprio 1
	v_mfma_f32_16x16x32_bf16 v[94:97], v[154:157], v[186:189], v[94:97]
	v_mfma_f32_16x16x32_bf16 v[90:93], v[162:165], v[186:189], v[90:93]
	v_mfma_f32_16x16x32_bf16 v[86:89], v[154:157], v[178:181], v[86:89]
	v_mfma_f32_16x16x32_bf16 v[82:85], v[162:165], v[178:181], v[82:85]
	v_mfma_f32_16x16x32_bf16 v[78:81], v[154:157], v[170:173], v[78:81]
	v_mfma_f32_16x16x32_bf16 v[74:77], v[162:165], v[170:173], v[74:77]
	v_mfma_f32_16x16x32_bf16 v[62:65], v[154:157], v[106:109], v[62:65]
	v_mfma_f32_16x16x32_bf16 v[54:57], v[162:165], v[106:109], v[54:57]
	v_mfma_f32_16x16x32_bf16 v[94:97], v[158:161], v[190:193], v[94:97]
	v_mfma_f32_16x16x32_bf16 v[90:93], v[166:169], v[190:193], v[90:93]
	v_mfma_f32_16x16x32_bf16 v[86:89], v[158:161], v[182:185], v[86:89]
	v_mfma_f32_16x16x32_bf16 v[82:85], v[166:169], v[182:185], v[82:85]
	v_mfma_f32_16x16x32_bf16 v[78:81], v[158:161], v[174:177], v[78:81]
	v_mfma_f32_16x16x32_bf16 v[74:77], v[166:169], v[174:177], v[74:77]
	v_mfma_f32_16x16x32_bf16 v[62:65], v[158:161], v[110:113], v[62:65]
	v_mfma_f32_16x16x32_bf16 v[54:57], v[166:169], v[110:113], v[54:57]
	s_setprio 0
	s_setprio 1
	v_mfma_f32_16x16x32_bf16 v[30:33], v[138:141], v[186:189], v[30:33]
	v_mfma_f32_16x16x32_bf16 v[26:29], v[146:149], v[186:189], v[26:29]
	v_mfma_f32_16x16x32_bf16 v[22:25], v[138:141], v[178:181], v[22:25]
	v_mfma_f32_16x16x32_bf16 v[18:21], v[146:149], v[178:181], v[18:21]
	v_mfma_f32_16x16x32_bf16 v[14:17], v[138:141], v[170:173], v[14:17]
	v_mfma_f32_16x16x32_bf16 v[10:13], v[146:149], v[170:173], v[10:13]
	v_mfma_f32_16x16x32_bf16 v[6:9], v[138:141], v[106:109], v[6:9]
	v_mfma_f32_16x16x32_bf16 v[2:5], v[146:149], v[106:109], v[2:5]
	v_mfma_f32_16x16x32_bf16 v[30:33], v[142:145], v[190:193], v[30:33]
	v_mfma_f32_16x16x32_bf16 v[26:29], v[150:153], v[190:193], v[26:29]
	v_mfma_f32_16x16x32_bf16 v[22:25], v[142:145], v[182:185], v[22:25]
	v_mfma_f32_16x16x32_bf16 v[18:21], v[150:153], v[182:185], v[18:21]
	v_mfma_f32_16x16x32_bf16 v[14:17], v[142:145], v[174:177], v[14:17]
	v_mfma_f32_16x16x32_bf16 v[10:13], v[150:153], v[174:177], v[10:13]
	v_mfma_f32_16x16x32_bf16 v[6:9], v[142:145], v[110:113], v[6:9]
	v_mfma_f32_16x16x32_bf16 v[2:5], v[150:153], v[110:113], v[2:5]
	s_setprio 0
	s_branch .LBB0_885

; #define PG8_STAGE(bufoff, gbase, voff) do { _Pragma("unroll") for (int _i = 0; _i < 2; ++_i) \
;         __builtin_amdgcn_global_load_lds((const unsigned*)((const char*)(gbase) + (voff)[_i]), (LAS unsigned*)(lds + (bufoff) + ldsw + _i * 8192), 16, 0, 0); } while (0)
; #define PG8_LDA(dst, b, h) do { _Pragma("unroll") for (int m = 0; m < 4; ++m) _Pragma("unroll") for (int k = 0; k < 2; ++k) dst[m][k] = *(const LAS f16x8*)(lds + PG8_SA(b, h) + aoff + m * 2048 + k * 1024); } while (0)
; #define PG8_LDB(dst, b, h) do { _Pragma("unroll") for (int n = 0; n < 2; ++n) _Pragma("unroll") for (int k = 0; k < 2; ++k) dst[n][k] = *(const LAS f16x8*)(lds + PG8_SB(b, h) + boff + n * 2048 + k * 1024); } while (0)
; #define PG8_MMA(ai, bj, At, Bt) do { __builtin_amdgcn_s_setprio(1); _Pragma("unroll") for (int m = 0; m < 4; ++m) _Pragma("unroll") for (int n = 0; n < 2; ++n) _Pragma("unroll") for (int k = 0; k < 2; ++k) \
;         acc[ai][bj][m][n] = mma16_<Epi::BF16>(Bt[n][k], At[m][k], acc[ai][bj][m][n]); __builtin_amdgcn_s_setprio(0); } while (0)
; #define PG8_WAIT_V(n) asm volatile("s_waitcnt vmcnt(" #n ")" ::: "memory")
; #define PG8_WAIT_L(n) asm volatile("s_waitcnt lgkmcnt(" #n ")" ::: "memory")
; #define PG8_BAR __builtin_amdgcn_s_barrier()
; #define PG8_SCHED __builtin_amdgcn_sched_barrier(0)
;     ...
;         const char* nA = has_next ? (const char*)g.A + (size_t)nxt.pm * tA + (nxt.roff ? hA : (size_t)0) : cA; const char* nB = has_next ? (const char*)g.Bt + (size_t)nxt.pn * tB : cB;
;         for (int t = 0; t < nt; t += 2) {
;             const bool last = (t == nt - 2);
;             const char* a1 = cA + (size_t)(t + 1) * kstep;
;             const char* a2 = last ? nA : cA + (size_t)(t + 2) * kstep; const char* b2 = last ? nB : cB + (size_t)(t + 2) * kstep;
;             const char* a3 = a2 + kstep; const char* b3 = b2 + kstep;
;             if constexpr (SP2) {
;             PG8_LDB(B0, 0, 0); PG8_LDB(B1, 0, 1); PG8_SCHED; PG8_LDA(At, 0, 0); PG8_STAGE(PG8_SA(1, 1), a1 + hA, voffA);
;             PG8_WAIT_V(8); PG8_WAIT_L(0); PG8_BAR; PG8_MMA(0, 0, At, B0); PG8_MMA(0, 1, At, B1); PG8_BAR; PG8_SCHED;
;             PG8_LDA(At, 0, 1); PG8_STAGE(PG8_SB(0, 0), b2, voffB); PG8_STAGE(PG8_SB(0, 1), b2 + hB, voffB); PG8_STAGE(PG8_SA(0, 0), a2, voffA);
.LBB0_1018:
	s_add_u32 s34, s30, 0xfffc0080
	s_addc_u32 s35, s31, -1
	s_add_i32 s54, 0, 0x10000
	s_cmp_eq_u32 s53, 12
	s_cselect_b32 s37, s2, s35
	s_cselect_b32 s36, s3, s34
	s_cselect_b32 s35, s19, s52
	s_cselect_b32 s34, s21, s51
	s_add_i32 s56, 0, 0x14000
	v_add_u32_e32 v156, s54, v141
	v_add_u32_e32 v172, s56, v141
	ds_read_b128 v[144:147], v156
	ds_read_b128 v[148:151], v156 offset:1024
	ds_read_b128 v[152:155], v156 offset:2048
	ds_read_b128 v[156:159], v156 offset:3072
	ds_read_b128 v[160:163], v172
	ds_read_b128 v[164:167], v172 offset:1024
	ds_read_b128 v[168:171], v172 offset:2048
	ds_read_b128 v[172:175], v172 offset:3072
	v_lshl_add_u64 v[222:223], s[30:31], 0, v[136:137]
	s_add_i32 m0, s27, 0xc000
	ds_read_b128 v[176:179], v143
	ds_read_b128 v[180:183], v143 offset:1024
	ds_read_b128 v[184:187], v143 offset:2048
	ds_read_b128 v[188:191], v143 offset:3072
	ds_read_b128 v[192:195], v143 offset:4096
	ds_read_b128 v[200:203], v143 offset:5120
	ds_read_b128 v[214:217], v143 offset:6144
	ds_read_b128 v[218:221], v143 offset:7168
	global_load_lds_dwordx4 v[222:223], off
	v_lshl_add_u64 v[222:223], s[30:31], 0, v[138:139]
	s_add_i32 m0, s27, 0xe000
	s_nop 0
	global_load_lds_dwordx4 v[222:223], off
	s_waitcnt vmcnt(8)
	s_waitcnt lgkmcnt(0)
	s_barrier
	s_setprio 1
	v_mfma_f32_16x16x32_bf16 v[126:129], v[144:147], v[176:179], v[126:129]
	v_mfma_f32_16x16x32_bf16 v[118:121], v[152:155], v[176:179], v[118:121]
	v_mfma_f32_16x16x32_bf16 v[110:113], v[144:147], v[184:187], v[110:113]
	v_mfma_f32_16x16x32_bf16 v[102:105], v[152:155], v[184:187], v[102:105]
	v_mfma_f32_16x16x32_bf16 v[94:97], v[144:147], v[192:195], v[94:97]
	v_mfma_f32_16x16x32_bf16 v[86:89], v[152:155], v[192:195], v[86:89]
	v_mfma_f32_16x16x32_bf16 v[78:81], v[144:147], v[214:217], v[78:81]
	v_mfma_f32_16x16x32_bf16 v[70:73], v[152:155], v[214:217], v[70:73]
	v_mfma_f32_16x16x32_bf16 v[126:129], v[148:151], v[180:183], v[126:129]
	v_mfma_f32_16x16x32_bf16 v[118:121], v[156:159], v[180:183], v[118:121]
	v_mfma_f32_16x16x32_bf16 v[110:113], v[148:151], v[188:191], v[110:113]
	v_mfma_f32_16x16x32_bf16 v[102:105], v[156:159], v[188:191], v[102:105]
	v_mfma_f32_16x16x32_bf16 v[94:97], v[148:151], v[200:203], v[94:97]
	v_mfma_f32_16x16x32_bf16 v[86:89], v[156:159], v[200:203], v[86:89]
	v_mfma_f32_16x16x32_bf16 v[78:81], v[148:151], v[218:221], v[78:81]
	v_mfma_f32_16x16x32_bf16 v[70:73], v[156:159], v[218:221], v[70:73]
	s_setprio 0
	s_setprio 1
	v_mfma_f32_16x16x32_bf16 v[122:125], v[160:163], v[176:179], v[122:125]
	v_mfma_f32_16x16x32_bf16 v[114:117], v[168:171], v[176:179], v[114:117]
	v_mfma_f32_16x16x32_bf16 v[106:109], v[160:163], v[184:187], v[106:109]
	v_mfma_f32_16x16x32_bf16 v[98:101], v[168:171], v[184:187], v[98:101]
	v_mfma_f32_16x16x32_bf16 v[90:93], v[160:163], v[192:195], v[90:93]
	v_mfma_f32_16x16x32_bf16 v[82:85], v[168:171], v[192:195], v[82:85]
	v_mfma_f32_16x16x32_bf16 v[74:77], v[160:163], v[214:217], v[74:77]
	v_mfma_f32_16x16x32_bf16 v[66:69], v[168:171], v[214:217], v[66:69]
	v_mfma_f32_16x16x32_bf16 v[122:125], v[164:167], v[180:183], v[122:125]
	v_mfma_f32_16x16x32_bf16 v[114:117], v[172:175], v[180:183], v[114:117]
	v_mfma_f32_16x16x32_bf16 v[106:109], v[164:167], v[188:191], v[106:109]
	v_mfma_f32_16x16x32_bf16 v[98:101], v[172:175], v[188:191], v[98:101]
	v_mfma_f32_16x16x32_bf16 v[90:93], v[164:167], v[200:203], v[90:93]
	v_mfma_f32_16x16x32_bf16 v[82:85], v[172:175], v[200:203], v[82:85]
	v_mfma_f32_16x16x32_bf16 v[74:77], v[164:167], v[218:221], v[74:77]
	v_mfma_f32_16x16x32_bf16 v[66:69], v[172:175], v[218:221], v[66:69]
	s_setprio 0
	s_barrier
	s_add_i32 s54, s54, s40
	v_lshl_add_u64 v[222:223], s[34:35], 0, v[0:1]
	s_mov_b32 m0, s54
	ds_read_b128 v[176:179], v143 offset:16384
	ds_read_b128 v[180:183], v143 offset:17408
	ds_read_b128 v[184:187], v143 offset:18432
	ds_read_b128 v[188:191], v143 offset:19456
	ds_read_b128 v[192:195], v143 offset:20480
	ds_read_b128 v[200:203], v143 offset:21504
	ds_read_b128 v[214:217], v143 offset:22528
	ds_read_b128 v[218:221], v143 offset:23552
	global_load_lds_dwordx4 v[222:223], off
	s_add_i32 m0, s54, 0x2000
	s_add_u32 s54, s34, 0x40000
	v_lshl_add_u64 v[224:225], s[34:35], 0, v[130:131]
	s_addc_u32 s55, s35, 0
	s_add_i32 s56, s56, s40
	global_load_lds_dwordx4 v[224:225], off
	v_lshl_add_u64 v[226:227], s[54:55], 0, v[0:1]
	s_mov_b32 m0, s56
	v_lshl_add_u64 v[228:229], s[36:37], 0, v[132:133]
	global_load_lds_dwordx4 v[226:227], off
	v_lshl_add_u64 v[226:227], s[54:55], 0, v[130:131]
	s_add_i32 m0, s56, 0x2000
	s_nop 0
	global_load_lds_dwordx4 v[226:227], off
	v_lshl_add_u64 v[226:227], s[36:37], 0, v[134:135]
	s_mov_b32 m0, s27
	s_nop 0
	global_load_lds_dwordx4 v[226:227], off
	s_mov_b32 m0, s29
	s_nop 0
	global_load_lds_dwordx4 v[228:229], off
	s_waitcnt vmcnt(8)
	s_waitcnt lgkmcnt(0)
	s_barrier
; #define PG8_STAGE(bufoff, gbase, voff) do { _Pragma("unroll") for (int _i = 0; _i < 2; ++_i) \
;         __builtin_amdgcn_global_load_lds((const unsigned*)((const char*)(gbase) + (voff)[_i]), (LAS unsigned*)(lds + (bufoff) + ldsw + _i * 8192), 16, 0, 0); } while (0)
; #define PG8_LDA(dst, b, h) do { _Pragma("unroll") for (int m = 0; m < 4; ++m) _Pragma("unroll") for (int k = 0; k < 2; ++k) dst[m][k] = *(const LAS f16x8*)(lds + PG8_SA(b, h) + aoff + m * 2048 + k * 1024); } while (0)
; #define PG8_LDB(dst, b, h) do { _Pragma("unroll") for (int n = 0; n < 2; ++n) _Pragma("unroll") for (int k = 0; k < 2; ++k) dst[n][k] = *(const LAS f16x8*)(lds + PG8_SB(b, h) + boff + n * 2048 + k * 1024); } while (0)
; #define PG8_MMA(ai, bj, At, Bt) do { __builtin_amdgcn_s_setprio(1); _Pragma("unroll") for (int m = 0; m < 4; ++m) _Pragma("unroll") for (int n = 0; n < 2; ++n) _Pragma("unroll") for (int k = 0; k < 2; ++k) \
;         acc[ai][bj][m][n] = mma16_<Epi::BF16>(Bt[n][k], At[m][k], acc[ai][bj][m][n]); __builtin_amdgcn_s_setprio(0); } while (0)
; #define PG8_WAIT_V(n) asm volatile("s_waitcnt vmcnt(" #n ")" ::: "memory")
; #define PG8_WAIT_L(n) asm volatile("s_waitcnt lgkmcnt(" #n ")" ::: "memory")
; #define PG8_BAR __builtin_amdgcn_s_barrier()
; #define PG8_SCHED __builtin_amdgcn_sched_barrier(0)
;     ...
;             PG8_WAIT_V(8); PG8_WAIT_L(0); PG8_BAR; if (!cur.half) { PG8_MMA(1, 0, At, B0); PG8_MMA(1, 1, At, B1); } PG8_BAR; PG8_SCHED;
;             PG8_LDB(B0, 1, 0); PG8_LDB(B1, 1, 1); PG8_SCHED; PG8_LDA(At, 1, 0); PG8_STAGE(PG8_SA(0, 1), a2 + hA, voffA);
;             PG8_WAIT_V(8); PG8_WAIT_L(0); PG8_BAR; PG8_MMA(0, 0, At, B0); PG8_MMA(0, 1, At, B1); PG8_BAR; PG8_SCHED;
	s_setprio 1
	v_mfma_f32_16x16x32_bf16 v[62:65], v[144:147], v[176:179], v[62:65]
	v_mfma_f32_16x16x32_bf16 v[54:57], v[152:155], v[176:179], v[54:57]
	v_mfma_f32_16x16x32_bf16 v[46:49], v[144:147], v[184:187], v[46:49]
	v_mfma_f32_16x16x32_bf16 v[38:41], v[152:155], v[184:187], v[38:41]
	v_mfma_f32_16x16x32_bf16 v[30:33], v[144:147], v[192:195], v[30:33]
	v_mfma_f32_16x16x32_bf16 v[22:25], v[152:155], v[192:195], v[22:25]
	v_mfma_f32_16x16x32_bf16 v[14:17], v[144:147], v[214:217], v[14:17]
	v_mfma_f32_16x16x32_bf16 v[6:9], v[152:155], v[214:217], v[6:9]
	v_mfma_f32_16x16x32_bf16 v[62:65], v[148:151], v[180:183], v[62:65]
	v_mfma_f32_16x16x32_bf16 v[54:57], v[156:159], v[180:183], v[54:57]
	v_mfma_f32_16x16x32_bf16 v[46:49], v[148:151], v[188:191], v[46:49]
	v_mfma_f32_16x16x32_bf16 v[38:41], v[156:159], v[188:191], v[38:41]
	v_mfma_f32_16x16x32_bf16 v[30:33], v[148:151], v[200:203], v[30:33]
	v_mfma_f32_16x16x32_bf16 v[22:25], v[156:159], v[200:203], v[22:25]
	v_mfma_f32_16x16x32_bf16 v[14:17], v[148:151], v[218:221], v[14:17]
	v_mfma_f32_16x16x32_bf16 v[6:9], v[156:159], v[218:221], v[6:9]
	s_setprio 0
	s_setprio 1
	v_mfma_f32_16x16x32_bf16 v[58:61], v[160:163], v[176:179], v[58:61]
	v_mfma_f32_16x16x32_bf16 v[50:53], v[168:171], v[176:179], v[50:53]
	v_mfma_f32_16x16x32_bf16 v[42:45], v[160:163], v[184:187], v[42:45]
	v_mfma_f32_16x16x32_bf16 v[34:37], v[168:171], v[184:187], v[34:37]
	v_mfma_f32_16x16x32_bf16 v[26:29], v[160:163], v[192:195], v[26:29]
	v_mfma_f32_16x16x32_bf16 v[18:21], v[168:171], v[192:195], v[18:21]
	v_mfma_f32_16x16x32_bf16 v[10:13], v[160:163], v[214:217], v[10:13]
	v_mfma_f32_16x16x32_bf16 v[2:5], v[168:171], v[214:217], v[2:5]
	v_mfma_f32_16x16x32_bf16 v[58:61], v[164:167], v[180:183], v[58:61]
	v_mfma_f32_16x16x32_bf16 v[50:53], v[172:175], v[180:183], v[50:53]
	v_mfma_f32_16x16x32_bf16 v[42:45], v[164:167], v[188:191], v[42:45]
	v_mfma_f32_16x16x32_bf16 v[34:37], v[172:175], v[188:191], v[34:37]
	v_mfma_f32_16x16x32_bf16 v[26:29], v[164:167], v[200:203], v[26:29]
	v_mfma_f32_16x16x32_bf16 v[18:21], v[172:175], v[200:203], v[18:21]
	v_mfma_f32_16x16x32_bf16 v[10:13], v[164:167], v[218:221], v[10:13]
	v_mfma_f32_16x16x32_bf16 v[2:5], v[172:175], v[218:221], v[2:5]
	s_setprio 0
	s_barrier
	s_add_i32 s54, 0, 0x18000
	s_add_i32 s55, 0, 0x1c000
	v_add_u32_e32 v156, s54, v141
	v_add_u32_e32 v172, s55, v141
	ds_read_b128 v[144:147], v156
	ds_read_b128 v[148:151], v156 offset:1024
	ds_read_b128 v[152:155], v156 offset:2048
	ds_read_b128 v[156:159], v156 offset:3072
	ds_read_b128 v[160:163], v172
	ds_read_b128 v[164:167], v172 offset:1024
	ds_read_b128 v[168:171], v172 offset:2048
	ds_read_b128 v[172:175], v172 offset:3072
	s_add_u32 s36, s36, 0x40000
	s_addc_u32 s37, s37, 0
	s_mov_b32 m0, s43
	v_lshl_add_u64 v[230:231], s[36:37], 0, v[134:135]
	ds_read_b128 v[176:179], v143 offset:32768
	ds_read_b128 v[180:183], v143 offset:33792
	ds_read_b128 v[184:187], v143 offset:34816
	ds_read_b128 v[188:191], v143 offset:35840
	ds_read_b128 v[192:195], v143 offset:36864
	ds_read_b128 v[200:203], v143 offset:37888
	ds_read_b128 v[214:217], v143 offset:38912
	ds_read_b128 v[218:221], v143 offset:39936
	global_load_lds_dwordx4 v[230:231], off
	v_lshl_add_u64 v[230:231], s[36:37], 0, v[132:133]
	s_mov_b32 m0, s44
	s_nop 0
	global_load_lds_dwordx4 v[230:231], off
	s_waitcnt vmcnt(8)
	s_waitcnt lgkmcnt(0)
	s_barrier
	s_setprio 1
	v_mfma_f32_16x16x32_bf16 v[126:129], v[144:147], v[176:179], v[126:129]
	v_mfma_f32_16x16x32_bf16 v[118:121], v[152:155], v[176:179], v[118:121]
	v_mfma_f32_16x16x32_bf16 v[110:113], v[144:147], v[184:187], v[110:113]
	v_mfma_f32_16x16x32_bf16 v[102:105], v[152:155], v[184:187], v[102:105]
	v_mfma_f32_16x16x32_bf16 v[94:97], v[144:147], v[192:195], v[94:97]
	v_mfma_f32_16x16x32_bf16 v[86:89], v[152:155], v[192:195], v[86:89]
	v_mfma_f32_16x16x32_bf16 v[78:81], v[144:147], v[214:217], v[78:81]
	v_mfma_f32_16x16x32_bf16 v[70:73], v[152:155], v[214:217], v[70:73]
	v_mfma_f32_16x16x32_bf16 v[126:129], v[148:151], v[180:183], v[126:129]
	v_mfma_f32_16x16x32_bf16 v[118:121], v[156:159], v[180:183], v[118:121]
	v_mfma_f32_16x16x32_bf16 v[110:113], v[148:151], v[188:191], v[110:113]
	v_mfma_f32_16x16x32_bf16 v[102:105], v[156:159], v[188:191], v[102:105]
	v_mfma_f32_16x16x32_bf16 v[94:97], v[148:151], v[200:203], v[94:97]
	v_mfma_f32_16x16x32_bf16 v[86:89], v[156:159], v[200:203], v[86:89]
	v_mfma_f32_16x16x32_bf16 v[78:81], v[148:151], v[218:221], v[78:81]
	v_mfma_f32_16x16x32_bf16 v[70:73], v[156:159], v[218:221], v[70:73]
	s_setprio 0
	s_setprio 1
	v_mfma_f32_16x16x32_bf16 v[122:125], v[160:163], v[176:179], v[122:125]
	v_mfma_f32_16x16x32_bf16 v[114:117], v[168:171], v[176:179], v[114:117]
	v_mfma_f32_16x16x32_bf16 v[106:109], v[160:163], v[184:187], v[106:109]
	v_mfma_f32_16x16x32_bf16 v[98:101], v[168:171], v[184:187], v[98:101]
	v_mfma_f32_16x16x32_bf16 v[90:93], v[160:163], v[192:195], v[90:93]
	v_mfma_f32_16x16x32_bf16 v[82:85], v[168:171], v[192:195], v[82:85]
	v_mfma_f32_16x16x32_bf16 v[74:77], v[160:163], v[214:217], v[74:77]
	v_mfma_f32_16x16x32_bf16 v[66:69], v[168:171], v[214:217], v[66:69]
	v_mfma_f32_16x16x32_bf16 v[122:125], v[164:167], v[180:183], v[122:125]
	v_mfma_f32_16x16x32_bf16 v[114:117], v[172:175], v[180:183], v[114:117]
	v_mfma_f32_16x16x32_bf16 v[106:109], v[164:167], v[188:191], v[106:109]
	v_mfma_f32_16x16x32_bf16 v[98:101], v[172:175], v[188:191], v[98:101]
	v_mfma_f32_16x16x32_bf16 v[90:93], v[164:167], v[200:203], v[90:93]
	v_mfma_f32_16x16x32_bf16 v[82:85], v[172:175], v[200:203], v[82:85]
	v_mfma_f32_16x16x32_bf16 v[74:77], v[164:167], v[218:221], v[74:77]
	v_mfma_f32_16x16x32_bf16 v[66:69], v[172:175], v[218:221], v[66:69]
	s_setprio 0
	s_barrier
; #define PG8_STAGE(bufoff, gbase, voff) do { _Pragma("unroll") for (int _i = 0; _i < 2; ++_i) \
;         __builtin_amdgcn_global_load_lds((const unsigned*)((const char*)(gbase) + (voff)[_i]), (LAS unsigned*)(lds + (bufoff) + ldsw + _i * 8192), 16, 0, 0); } while (0)
; #define PG8_LDA(dst, b, h) do { _Pragma("unroll") for (int m = 0; m < 4; ++m) _Pragma("unroll") for (int k = 0; k < 2; ++k) dst[m][k] = *(const LAS f16x8*)(lds + PG8_SA(b, h) + aoff + m * 2048 + k * 1024); } while (0)
; #define PG8_LDB(dst, b, h) do { _Pragma("unroll") for (int n = 0; n < 2; ++n) _Pragma("unroll") for (int k = 0; k < 2; ++k) dst[n][k] = *(const LAS f16x8*)(lds + PG8_SB(b, h) + boff + n * 2048 + k * 1024); } while (0)
;     ...
;             PG8_LDA(At, 1, 1); PG8_STAGE(PG8_SB(1, 0), b3, voffB); PG8_STAGE(PG8_SB(1, 1), b3 + hB, voffB); PG8_STAGE(PG8_SA(1, 0), a3, voffA);
;             PG8_WAIT_V(8); PG8_WAIT_L(0); PG8_BAR; if (!cur.half) { PG8_MMA(1, 0, At, B0); PG8_MMA(1, 1, At, B1); } PG8_BAR; PG8_SCHED;
;             } else {
;             PG8_LDB(B0, 0, 0); PG8_SCHED; PG8_LDA(At, 0, 0); PG8_STAGE(PG8_SA(1, 1), a1 + hA, voffA);
;             PG8_WAIT_L(8); PG8_BAR; PG8_WAIT_L(0); PG8_MMA(0, 0, At, B0); PG8_BAR; PG8_SCHED;
;             PG8_LDB(B1, 0, 1); PG8_STAGE(PG8_SB(0, 0), b2, voffB);
;             PG8_BAR; PG8_WAIT_L(0); PG8_MMA(0, 1, At, B1); PG8_BAR;
;             PG8_LDA(At, 0, 1); PG8_STAGE(PG8_SA(0, 0), a2, voffA);
;             PG8_BAR; PG8_WAIT_L(0); if (!cur.half) PG8_MMA(1, 0, At, B0); PG8_BAR; PG8_SCHED;
;             PG8_STAGE(PG8_SB(0, 1), b2 + hB, voffB);
;             PG8_WAIT_V(6); PG8_BAR; if (!cur.half) PG8_MMA(1, 1, At, B1); PG8_BAR;
;             PG8_LDB(B0, 1, 0); PG8_SCHED; PG8_LDA(At, 1, 0); PG8_STAGE(PG8_SA(0, 1), a2 + hA, voffA);
;             PG8_WAIT_L(8); PG8_BAR; PG8_WAIT_L(0); PG8_MMA(0, 0, At, B0); PG8_BAR; PG8_SCHED;
;             PG8_LDB(B1, 1, 1); PG8_STAGE(PG8_SB(1, 0), b3, voffB);
;             PG8_BAR; PG8_WAIT_L(0); PG8_MMA(0, 1, At, B1); PG8_BAR;
;             PG8_LDA(At, 1, 1); PG8_STAGE(PG8_SA(1, 0), a3, voffA);
;             PG8_BAR; PG8_WAIT_L(0); if (!cur.half) PG8_MMA(1, 0, At, B0); PG8_BAR; PG8_SCHED;
;             PG8_STAGE(PG8_SB(1, 1), b3 + hB, voffB);
;             PG8_WAIT_V(6); PG8_BAR; if (!cur.half) PG8_MMA(1, 1, At, B1); PG8_BAR;
;             }
;         }
;         if constexpr (ALIGN_EPI) { if (wr == 0) PG8_BAR; }
	s_add_i32 s36, s54, s40
	v_lshl_add_u64 v[222:223], v[222:223], 0, s[96:97]
	s_mov_b32 m0, s36
	ds_read_b128 v[176:179], v143 offset:49152
	ds_read_b128 v[180:183], v143 offset:50176
	ds_read_b128 v[184:187], v143 offset:51200
	ds_read_b128 v[188:191], v143 offset:52224
	ds_read_b128 v[192:195], v143 offset:53248
	ds_read_b128 v[200:203], v143 offset:54272
	ds_read_b128 v[214:217], v143 offset:55296
	ds_read_b128 v[218:221], v143 offset:56320
	global_load_lds_dwordx4 v[222:223], off
	s_add_i32 m0, s36, 0x2000
	s_add_u32 s34, s34, 0x40080
	v_lshl_add_u64 v[222:223], v[224:225], 0, s[96:97]
	s_addc_u32 s35, s35, 0
	s_add_i32 s36, s55, s40
	global_load_lds_dwordx4 v[222:223], off
	v_lshl_add_u64 v[222:223], s[34:35], 0, v[0:1]
	s_mov_b32 m0, s36
	s_nop 0
	global_load_lds_dwordx4 v[222:223], off
	v_lshl_add_u64 v[222:223], s[34:35], 0, v[130:131]
	s_add_i32 m0, s36, 0x2000
	s_nop 0
	global_load_lds_dwordx4 v[222:223], off
	v_lshl_add_u64 v[222:223], v[226:227], 0, s[96:97]
	s_mov_b32 m0, s45
	s_nop 0
	global_load_lds_dwordx4 v[222:223], off
	v_lshl_add_u64 v[222:223], v[228:229], 0, s[96:97]
	s_mov_b32 m0, s47
	s_nop 0
	global_load_lds_dwordx4 v[222:223], off
	s_waitcnt vmcnt(8)
	s_waitcnt lgkmcnt(0)
	s_barrier
	s_setprio 1
	v_mfma_f32_16x16x32_bf16 v[62:65], v[144:147], v[176:179], v[62:65]
	v_mfma_f32_16x16x32_bf16 v[54:57], v[152:155], v[176:179], v[54:57]
	v_mfma_f32_16x16x32_bf16 v[46:49], v[144:147], v[184:187], v[46:49]
	v_mfma_f32_16x16x32_bf16 v[38:41], v[152:155], v[184:187], v[38:41]
	v_mfma_f32_16x16x32_bf16 v[30:33], v[144:147], v[192:195], v[30:33]
	v_mfma_f32_16x16x32_bf16 v[22:25], v[152:155], v[192:195], v[22:25]
	v_mfma_f32_16x16x32_bf16 v[14:17], v[144:147], v[214:217], v[14:17]
	v_mfma_f32_16x16x32_bf16 v[6:9], v[152:155], v[214:217], v[6:9]
	v_mfma_f32_16x16x32_bf16 v[62:65], v[148:151], v[180:183], v[62:65]
	v_mfma_f32_16x16x32_bf16 v[54:57], v[156:159], v[180:183], v[54:57]
	v_mfma_f32_16x16x32_bf16 v[46:49], v[148:151], v[188:191], v[46:49]
	v_mfma_f32_16x16x32_bf16 v[38:41], v[156:159], v[188:191], v[38:41]
	v_mfma_f32_16x16x32_bf16 v[30:33], v[148:151], v[200:203], v[30:33]
	v_mfma_f32_16x16x32_bf16 v[22:25], v[156:159], v[200:203], v[22:25]
	v_mfma_f32_16x16x32_bf16 v[14:17], v[148:151], v[218:221], v[14:17]
	v_mfma_f32_16x16x32_bf16 v[6:9], v[156:159], v[218:221], v[6:9]
	s_setprio 0
	s_setprio 1
	v_mfma_f32_16x16x32_bf16 v[58:61], v[160:163], v[176:179], v[58:61]
	v_mfma_f32_16x16x32_bf16 v[50:53], v[168:171], v[176:179], v[50:53]
	v_mfma_f32_16x16x32_bf16 v[42:45], v[160:163], v[184:187], v[42:45]
	v_mfma_f32_16x16x32_bf16 v[34:37], v[168:171], v[184:187], v[34:37]
	v_mfma_f32_16x16x32_bf16 v[26:29], v[160:163], v[192:195], v[26:29]
	v_mfma_f32_16x16x32_bf16 v[18:21], v[168:171], v[192:195], v[18:21]
	v_mfma_f32_16x16x32_bf16 v[10:13], v[160:163], v[214:217], v[10:13]
	v_mfma_f32_16x16x32_bf16 v[2:5], v[168:171], v[214:217], v[2:5]
	v_mfma_f32_16x16x32_bf16 v[58:61], v[164:167], v[180:183], v[58:61]
	v_mfma_f32_16x16x32_bf16 v[50:53], v[172:175], v[180:183], v[50:53]
	v_mfma_f32_16x16x32_bf16 v[42:45], v[164:167], v[188:191], v[42:45]
	v_mfma_f32_16x16x32_bf16 v[34:37], v[172:175], v[188:191], v[34:37]
	v_mfma_f32_16x16x32_bf16 v[26:29], v[164:167], v[200:203], v[26:29]
	v_mfma_f32_16x16x32_bf16 v[18:21], v[172:175], v[200:203], v[18:21]
	v_mfma_f32_16x16x32_bf16 v[10:13], v[164:167], v[218:221], v[10:13]
	v_mfma_f32_16x16x32_bf16 v[2:5], v[172:175], v[218:221], v[2:5]
	s_setprio 0
	s_barrier
	s_add_i32 s53, s53, 2
	s_add_u32 s30, s30, 0x100
	s_addc_u32 s31, s31, 0
	s_add_u32 s51, s51, 0x100
	s_addc_u32 s52, s52, 0
	s_cmp_gt_u32 s53, 13
	s_cbranch_scc0 .LBB0_1018
	s_and_b64 vcc, exec, s[10:11]
	s_cbranch_vccz .LBB0_1021
	s_barrier

; #define PG8_STAGE(bufoff, gbase, voff) do { _Pragma("unroll") for (int _i = 0; _i < 2; ++_i) \
;         __builtin_amdgcn_global_load_lds((const unsigned*)((const char*)(gbase) + (voff)[_i]), (LAS unsigned*)(lds + (bufoff) + ldsw + _i * 8192), 16, 0, 0); } while (0)
; #define PG8_LDA(dst, b, h) do { _Pragma("unroll") for (int m = 0; m < 4; ++m) _Pragma("unroll") for (int k = 0; k < 2; ++k) dst[m][k] = *(const LAS f16x8*)(lds + PG8_SA(b, h) + aoff + m * 2048 + k * 1024); } while (0)
; #define PG8_LDB(dst, b, h) do { _Pragma("unroll") for (int n = 0; n < 2; ++n) _Pragma("unroll") for (int k = 0; k < 2; ++k) dst[n][k] = *(const LAS f16x8*)(lds + PG8_SB(b, h) + boff + n * 2048 + k * 1024); } while (0)
; #define PG8_MMA(ai, bj, At, Bt) do { __builtin_amdgcn_s_setprio(1); _Pragma("unroll") for (int m = 0; m < 4; ++m) _Pragma("unroll") for (int n = 0; n < 2; ++n) _Pragma("unroll") for (int k = 0; k < 2; ++k) \
;         acc[ai][bj][m][n] = mma16_<Epi::BF16>(Bt[n][k], At[m][k], acc[ai][bj][m][n]); __builtin_amdgcn_s_setprio(0); } while (0)
; #define PG8_WAIT_V(n) asm volatile("s_waitcnt vmcnt(" #n ")" ::: "memory")
; #define PG8_WAIT_L(n) asm volatile("s_waitcnt lgkmcnt(" #n ")" ::: "memory")
; #define PG8_BAR __builtin_amdgcn_s_barrier()
;     ...
;         const char* nA = has_next ? (const char*)g.A + (size_t)nxt.pm * tA + (nxt.roff ? hA : (size_t)0) : cA; const char* nB = has_next ? (const char*)g.Bt + (size_t)nxt.pn * tB : cB;
;         for (int t = 0; t < nt; t += 2) {
;             const bool last = (t == nt - 2);
;             const char* a1 = cA + (size_t)(t + 1) * kstep;
;             const char* a2 = last ? nA : cA + (size_t)(t + 2) * kstep; const char* b2 = last ? nB : cB + (size_t)(t + 2) * kstep;
;             const char* a3 = a2 + kstep; const char* b3 = b2 + kstep;
;             if constexpr (SP2) {
;             PG8_LDB(B0, 0, 0); PG8_LDB(B1, 0, 1); PG8_SCHED; PG8_LDA(At, 0, 0); PG8_STAGE(PG8_SA(1, 1), a1 + hA, voffA);
;             PG8_WAIT_V(8); PG8_WAIT_L(0); PG8_BAR; PG8_MMA(0, 0, At, B0); PG8_MMA(0, 1, At, B1); PG8_BAR; PG8_SCHED;
;             PG8_LDA(At, 0, 1); PG8_STAGE(PG8_SB(0, 0), b2, voffB); PG8_STAGE(PG8_SB(0, 1), b2 + hB, voffB); PG8_STAGE(PG8_SA(0, 0), a2, voffA);
;             PG8_WAIT_V(8); PG8_WAIT_L(0); PG8_BAR; if (!cur.half) { PG8_MMA(1, 0, At, B0); PG8_MMA(1, 1, At, B1); } PG8_BAR; PG8_SCHED;
.LBB0_1103:
	s_mov_b64 s[42:43], s[30:31]
	s_add_u32 s30, s42, 0x100
	s_addc_u32 s31, s43, 0
	s_add_i32 s29, 0, 0x10000
	s_cmp_eq_u32 s14, 40
	s_cselect_b32 s45, s25, s31
	s_cselect_b32 s44, s24, s30
	s_cselect_b32 s37, s27, s3
	s_cselect_b32 s36, s26, s2
	s_add_i32 s69, 0, 0x14000
	v_add_u32_e32 v130, s29, v243
	v_add_u32_e32 v142, s69, v243
	ds_read_b128 v[146:149], v130
	ds_read_b128 v[150:153], v130 offset:1024
	ds_read_b128 v[154:157], v130 offset:2048
	ds_read_b128 v[158:161], v130 offset:3072
	ds_read_b128 v[130:133], v142
	ds_read_b128 v[134:137], v142 offset:1024
	ds_read_b128 v[138:141], v142 offset:2048
	ds_read_b128 v[142:145], v142 offset:3072
	v_lshl_add_u64 v[200:201], s[42:43], 0, v[222:223]
	s_add_i32 m0, s53, 0xc000
	s_waitcnt lgkmcnt(0)
	ds_read_b128 v[162:165], v244
	ds_read_b128 v[166:169], v244 offset:1024
	ds_read_b128 v[170:173], v244 offset:2048
	ds_read_b128 v[174:177], v244 offset:3072
	ds_read_b128 v[178:181], v244 offset:4096
	ds_read_b128 v[182:185], v244 offset:5120
	ds_read_b128 v[186:189], v244 offset:6144
	ds_read_b128 v[190:193], v244 offset:7168
	global_load_lds_dwordx4 v[200:201], off
	v_lshl_add_u64 v[200:201], s[42:43], 0, v[224:225]
	s_add_i32 m0, s53, 0xe000
	s_nop 0
	global_load_lds_dwordx4 v[200:201], off
	s_waitcnt vmcnt(8)
	s_waitcnt lgkmcnt(0)
	s_barrier
	s_setprio 1
	v_mfma_f32_16x16x32_bf16 v[126:129], v[146:149], v[162:165], v[126:129]
	v_mfma_f32_16x16x32_bf16 v[122:125], v[154:157], v[162:165], v[122:125]
	v_mfma_f32_16x16x32_bf16 v[118:121], v[146:149], v[170:173], v[118:121]
	v_mfma_f32_16x16x32_bf16 v[114:117], v[154:157], v[170:173], v[114:117]
	v_mfma_f32_16x16x32_bf16 v[110:113], v[146:149], v[178:181], v[110:113]
	v_mfma_f32_16x16x32_bf16 v[106:109], v[154:157], v[178:181], v[106:109]
	v_mfma_f32_16x16x32_bf16 v[102:105], v[146:149], v[186:189], v[102:105]
	v_mfma_f32_16x16x32_bf16 v[98:101], v[154:157], v[186:189], v[98:101]
	v_mfma_f32_16x16x32_bf16 v[126:129], v[150:153], v[166:169], v[126:129]
	v_mfma_f32_16x16x32_bf16 v[122:125], v[158:161], v[166:169], v[122:125]
	v_mfma_f32_16x16x32_bf16 v[118:121], v[150:153], v[174:177], v[118:121]
	v_mfma_f32_16x16x32_bf16 v[114:117], v[158:161], v[174:177], v[114:117]
	v_mfma_f32_16x16x32_bf16 v[110:113], v[150:153], v[182:185], v[110:113]
	v_mfma_f32_16x16x32_bf16 v[106:109], v[158:161], v[182:185], v[106:109]
	v_mfma_f32_16x16x32_bf16 v[102:105], v[150:153], v[190:193], v[102:105]
	v_mfma_f32_16x16x32_bf16 v[98:101], v[158:161], v[190:193], v[98:101]
	s_setprio 0
	s_setprio 1
	v_mfma_f32_16x16x32_bf16 v[78:81], v[130:133], v[162:165], v[78:81]
	v_mfma_f32_16x16x32_bf16 v[74:77], v[138:141], v[162:165], v[74:77]
	v_mfma_f32_16x16x32_bf16 v[62:65], v[130:133], v[170:173], v[62:65]
	v_mfma_f32_16x16x32_bf16 v[58:61], v[138:141], v[170:173], v[58:61]
	v_mfma_f32_16x16x32_bf16 v[46:49], v[130:133], v[178:181], v[46:49]
	v_mfma_f32_16x16x32_bf16 v[42:45], v[138:141], v[178:181], v[42:45]
	v_mfma_f32_16x16x32_bf16 v[38:41], v[130:133], v[186:189], v[38:41]
	v_mfma_f32_16x16x32_bf16 v[34:37], v[138:141], v[186:189], v[34:37]
	v_mfma_f32_16x16x32_bf16 v[78:81], v[134:137], v[166:169], v[78:81]
	v_mfma_f32_16x16x32_bf16 v[74:77], v[142:145], v[166:169], v[74:77]
	v_mfma_f32_16x16x32_bf16 v[62:65], v[134:137], v[174:177], v[62:65]
	v_mfma_f32_16x16x32_bf16 v[58:61], v[142:145], v[174:177], v[58:61]
	v_mfma_f32_16x16x32_bf16 v[46:49], v[134:137], v[182:185], v[46:49]
	v_mfma_f32_16x16x32_bf16 v[42:45], v[142:145], v[182:185], v[42:45]
	v_mfma_f32_16x16x32_bf16 v[38:41], v[134:137], v[190:193], v[38:41]
	v_mfma_f32_16x16x32_bf16 v[34:37], v[142:145], v[190:193], v[34:37]
	s_setprio 0
	s_barrier
	s_add_i32 s29, s29, s52
	v_lshl_add_u64 v[226:227], s[36:37], 0, v[214:215]
	s_mov_b32 m0, s29
	ds_read_b128 v[186:189], v244 offset:16384
	ds_read_b128 v[190:193], v244 offset:17408
	ds_read_b128 v[178:181], v244 offset:18432
	ds_read_b128 v[182:185], v244 offset:19456
	ds_read_b128 v[170:173], v244 offset:20480
	ds_read_b128 v[174:177], v244 offset:21504
	ds_read_b128 v[162:165], v244 offset:22528
	ds_read_b128 v[166:169], v244 offset:23552
	global_load_lds_dwordx4 v[226:227], off
	s_add_i32 m0, s29, 0x2000
	s_add_u32 s42, s36, 0xb0000
	v_lshl_add_u64 v[228:229], s[36:37], 0, v[218:219]
	s_addc_u32 s43, s37, 0
	s_add_i32 s29, s69, s52
	global_load_lds_dwordx4 v[228:229], off
	v_lshl_add_u64 v[200:201], s[42:43], 0, v[214:215]
	s_mov_b32 m0, s29
	v_lshl_add_u64 v[230:231], s[44:45], 0, v[194:195]
	global_load_lds_dwordx4 v[200:201], off
	v_lshl_add_u64 v[200:201], s[42:43], 0, v[218:219]
	s_add_i32 m0, s29, 0x2000
	v_lshl_add_u64 v[232:233], s[44:45], 0, v[216:217]
	global_load_lds_dwordx4 v[200:201], off
	s_mov_b32 m0, s53
	v_cndmask_b32_e64 v200, 0, 1, s[34:35]
	global_load_lds_dwordx4 v[230:231], off
	s_mov_b32 m0, s54
	v_cmp_ne_u32_e64 s[42:43], 1, v200
	global_load_lds_dwordx4 v[232:233], off
	s_waitcnt vmcnt(8)
	s_waitcnt lgkmcnt(0)
	s_andn2_b64 vcc, exec, s[34:35]
	s_barrier
	s_cbranch_vccnz .LBB0_1105
; #define PG8_MMA(ai, bj, At, Bt) do { __builtin_amdgcn_s_setprio(1); _Pragma("unroll") for (int m = 0; m < 4; ++m) _Pragma("unroll") for (int n = 0; n < 2; ++n) _Pragma("unroll") for (int k = 0; k < 2; ++k) \
;         acc[ai][bj][m][n] = mma16_<Epi::BF16>(Bt[n][k], At[m][k], acc[ai][bj][m][n]); __builtin_amdgcn_s_setprio(0); } while (0)
; #define PG8_WAIT_V(n) asm volatile("s_waitcnt vmcnt(" #n ")" ::: "memory")
; #define PG8_WAIT_L(n) asm volatile("s_waitcnt lgkmcnt(" #n ")" ::: "memory")
; #define PG8_BAR __builtin_amdgcn_s_barrier()
; #define PG8_SCHED __builtin_amdgcn_sched_barrier(0)
;     ...
;             PG8_WAIT_V(8); PG8_WAIT_L(0); PG8_BAR; if (!cur.half) { PG8_MMA(1, 0, At, B0); PG8_MMA(1, 1, At, B1); } PG8_BAR; PG8_SCHED;
	s_setprio 1
	v_mfma_f32_16x16x32_bf16 v[94:97], v[146:149], v[186:189], v[94:97]
	v_mfma_f32_16x16x32_bf16 v[90:93], v[154:157], v[186:189], v[90:93]
	v_mfma_f32_16x16x32_bf16 v[86:89], v[146:149], v[178:181], v[86:89]
	v_mfma_f32_16x16x32_bf16 v[82:85], v[154:157], v[178:181], v[82:85]
	v_mfma_f32_16x16x32_bf16 v[70:73], v[146:149], v[170:173], v[70:73]
	v_mfma_f32_16x16x32_bf16 v[66:69], v[154:157], v[170:173], v[66:69]
	v_mfma_f32_16x16x32_bf16 v[54:57], v[146:149], v[162:165], v[54:57]
	v_mfma_f32_16x16x32_bf16 v[50:53], v[154:157], v[162:165], v[50:53]
	v_mfma_f32_16x16x32_bf16 v[94:97], v[150:153], v[190:193], v[94:97]
	v_mfma_f32_16x16x32_bf16 v[90:93], v[158:161], v[190:193], v[90:93]
	v_mfma_f32_16x16x32_bf16 v[86:89], v[150:153], v[182:185], v[86:89]
	v_mfma_f32_16x16x32_bf16 v[82:85], v[158:161], v[182:185], v[82:85]
	v_mfma_f32_16x16x32_bf16 v[70:73], v[150:153], v[174:177], v[70:73]
	v_mfma_f32_16x16x32_bf16 v[66:69], v[158:161], v[174:177], v[66:69]
	v_mfma_f32_16x16x32_bf16 v[54:57], v[150:153], v[166:169], v[54:57]
	v_mfma_f32_16x16x32_bf16 v[50:53], v[158:161], v[166:169], v[50:53]
	s_setprio 0
	s_setprio 1
	v_mfma_f32_16x16x32_bf16 v[30:33], v[130:133], v[186:189], v[30:33]
	v_mfma_f32_16x16x32_bf16 v[26:29], v[138:141], v[186:189], v[26:29]
	v_mfma_f32_16x16x32_bf16 v[22:25], v[130:133], v[178:181], v[22:25]
	v_mfma_f32_16x16x32_bf16 v[18:21], v[138:141], v[178:181], v[18:21]
	v_mfma_f32_16x16x32_bf16 v[14:17], v[130:133], v[170:173], v[14:17]
	v_mfma_f32_16x16x32_bf16 v[10:13], v[138:141], v[170:173], v[10:13]
	v_mfma_f32_16x16x32_bf16 v[6:9], v[130:133], v[162:165], v[6:9]
	v_mfma_f32_16x16x32_bf16 v[2:5], v[138:141], v[162:165], v[2:5]
	v_mfma_f32_16x16x32_bf16 v[30:33], v[134:137], v[190:193], v[30:33]
	v_mfma_f32_16x16x32_bf16 v[26:29], v[142:145], v[190:193], v[26:29]
	v_mfma_f32_16x16x32_bf16 v[22:25], v[134:137], v[182:185], v[22:25]
	v_mfma_f32_16x16x32_bf16 v[18:21], v[142:145], v[182:185], v[18:21]
	v_mfma_f32_16x16x32_bf16 v[14:17], v[134:137], v[174:177], v[14:17]
	v_mfma_f32_16x16x32_bf16 v[10:13], v[142:145], v[174:177], v[10:13]
	v_mfma_f32_16x16x32_bf16 v[6:9], v[134:137], v[166:169], v[6:9]
	v_mfma_f32_16x16x32_bf16 v[2:5], v[142:145], v[166:169], v[2:5]
	s_setprio 0
; #define PG8_STAGE(bufoff, gbase, voff) do { _Pragma("unroll") for (int _i = 0; _i < 2; ++_i) \
;         __builtin_amdgcn_global_load_lds((const unsigned*)((const char*)(gbase) + (voff)[_i]), (LAS unsigned*)(lds + (bufoff) + ldsw + _i * 8192), 16, 0, 0); } while (0)
; #define PG8_LDA(dst, b, h) do { _Pragma("unroll") for (int m = 0; m < 4; ++m) _Pragma("unroll") for (int k = 0; k < 2; ++k) dst[m][k] = *(const LAS f16x8*)(lds + PG8_SA(b, h) + aoff + m * 2048 + k * 1024); } while (0)
; #define PG8_LDB(dst, b, h) do { _Pragma("unroll") for (int n = 0; n < 2; ++n) _Pragma("unroll") for (int k = 0; k < 2; ++k) dst[n][k] = *(const LAS f16x8*)(lds + PG8_SB(b, h) + boff + n * 2048 + k * 1024); } while (0)
; #define PG8_MMA(ai, bj, At, Bt) do { __builtin_amdgcn_s_setprio(1); _Pragma("unroll") for (int m = 0; m < 4; ++m) _Pragma("unroll") for (int n = 0; n < 2; ++n) _Pragma("unroll") for (int k = 0; k < 2; ++k) \
;         acc[ai][bj][m][n] = mma16_<Epi::BF16>(Bt[n][k], At[m][k], acc[ai][bj][m][n]); __builtin_amdgcn_s_setprio(0); } while (0)
; #define PG8_WAIT_V(n) asm volatile("s_waitcnt vmcnt(" #n ")" ::: "memory")
; #define PG8_WAIT_L(n) asm volatile("s_waitcnt lgkmcnt(" #n ")" ::: "memory")
; #define PG8_BAR __builtin_amdgcn_s_barrier()
; #define PG8_SCHED __builtin_amdgcn_sched_barrier(0)
;     ...
;             PG8_LDB(B0, 1, 0); PG8_LDB(B1, 1, 1); PG8_SCHED; PG8_LDA(At, 1, 0); PG8_STAGE(PG8_SA(0, 1), a2 + hA, voffA);
;             PG8_WAIT_V(8); PG8_WAIT_L(0); PG8_BAR; PG8_MMA(0, 0, At, B0); PG8_MMA(0, 1, At, B1); PG8_BAR; PG8_SCHED;
;             PG8_LDA(At, 1, 1); PG8_STAGE(PG8_SB(1, 0), b3, voffB); PG8_STAGE(PG8_SB(1, 1), b3 + hB, voffB); PG8_STAGE(PG8_SA(1, 0), a3, voffA);
;             PG8_WAIT_V(8); PG8_WAIT_L(0); PG8_BAR; if (!cur.half) { PG8_MMA(1, 0, At, B0); PG8_MMA(1, 1, At, B1); } PG8_BAR; PG8_SCHED;
.LBB0_1105:
	s_barrier
	s_add_i32 s29, 0, 0x18000
	s_add_i32 s69, 0, 0x1c000
	v_add_u32_e32 v130, s29, v243
	v_add_u32_e32 v142, s69, v243
	ds_read_b128 v[146:149], v130
	ds_read_b128 v[150:153], v130 offset:1024
	ds_read_b128 v[154:157], v130 offset:2048
	ds_read_b128 v[158:161], v130 offset:3072
	ds_read_b128 v[130:133], v142
	ds_read_b128 v[134:137], v142 offset:1024
	ds_read_b128 v[138:141], v142 offset:2048
	ds_read_b128 v[142:145], v142 offset:3072
	s_add_u32 s44, s44, 0xb0000
	s_addc_u32 s45, s45, 0
	s_mov_b32 m0, s55
	v_lshl_add_u64 v[200:201], s[44:45], 0, v[194:195]
	s_waitcnt lgkmcnt(0)
	ds_read_b128 v[162:165], v244 offset:32768
	ds_read_b128 v[166:169], v244 offset:33792
	ds_read_b128 v[170:173], v244 offset:34816
	ds_read_b128 v[174:177], v244 offset:35840
	ds_read_b128 v[178:181], v244 offset:36864
	ds_read_b128 v[182:185], v244 offset:37888
	ds_read_b128 v[186:189], v244 offset:38912
	ds_read_b128 v[190:193], v244 offset:39936
	global_load_lds_dwordx4 v[200:201], off
	v_lshl_add_u64 v[200:201], s[44:45], 0, v[216:217]
	s_mov_b32 m0, s56
	s_nop 0
	global_load_lds_dwordx4 v[200:201], off
	s_waitcnt vmcnt(8)
	s_waitcnt lgkmcnt(0)
	s_barrier
	s_setprio 1
	v_mfma_f32_16x16x32_bf16 v[126:129], v[146:149], v[162:165], v[126:129]
	v_mfma_f32_16x16x32_bf16 v[122:125], v[154:157], v[162:165], v[122:125]
	v_mfma_f32_16x16x32_bf16 v[118:121], v[146:149], v[170:173], v[118:121]
	v_mfma_f32_16x16x32_bf16 v[114:117], v[154:157], v[170:173], v[114:117]
	v_mfma_f32_16x16x32_bf16 v[110:113], v[146:149], v[178:181], v[110:113]
	v_mfma_f32_16x16x32_bf16 v[106:109], v[154:157], v[178:181], v[106:109]
	v_mfma_f32_16x16x32_bf16 v[102:105], v[146:149], v[186:189], v[102:105]
	v_mfma_f32_16x16x32_bf16 v[98:101], v[154:157], v[186:189], v[98:101]
	v_mfma_f32_16x16x32_bf16 v[126:129], v[150:153], v[166:169], v[126:129]
	v_mfma_f32_16x16x32_bf16 v[122:125], v[158:161], v[166:169], v[122:125]
	v_mfma_f32_16x16x32_bf16 v[118:121], v[150:153], v[174:177], v[118:121]
	v_mfma_f32_16x16x32_bf16 v[114:117], v[158:161], v[174:177], v[114:117]
	v_mfma_f32_16x16x32_bf16 v[110:113], v[150:153], v[182:185], v[110:113]
	v_mfma_f32_16x16x32_bf16 v[106:109], v[158:161], v[182:185], v[106:109]
	v_mfma_f32_16x16x32_bf16 v[102:105], v[150:153], v[190:193], v[102:105]
	v_mfma_f32_16x16x32_bf16 v[98:101], v[158:161], v[190:193], v[98:101]
	s_setprio 0
	s_setprio 1
	v_mfma_f32_16x16x32_bf16 v[78:81], v[130:133], v[162:165], v[78:81]
	v_mfma_f32_16x16x32_bf16 v[74:77], v[138:141], v[162:165], v[74:77]
	v_mfma_f32_16x16x32_bf16 v[62:65], v[130:133], v[170:173], v[62:65]
	v_mfma_f32_16x16x32_bf16 v[58:61], v[138:141], v[170:173], v[58:61]
	v_mfma_f32_16x16x32_bf16 v[46:49], v[130:133], v[178:181], v[46:49]
	v_mfma_f32_16x16x32_bf16 v[42:45], v[138:141], v[178:181], v[42:45]
	v_mfma_f32_16x16x32_bf16 v[38:41], v[130:133], v[186:189], v[38:41]
	v_mfma_f32_16x16x32_bf16 v[34:37], v[138:141], v[186:189], v[34:37]
	v_mfma_f32_16x16x32_bf16 v[78:81], v[134:137], v[166:169], v[78:81]
	v_mfma_f32_16x16x32_bf16 v[74:77], v[142:145], v[166:169], v[74:77]
	v_mfma_f32_16x16x32_bf16 v[62:65], v[134:137], v[174:177], v[62:65]
	v_mfma_f32_16x16x32_bf16 v[58:61], v[142:145], v[174:177], v[58:61]
	v_mfma_f32_16x16x32_bf16 v[46:49], v[134:137], v[182:185], v[46:49]
	v_mfma_f32_16x16x32_bf16 v[42:45], v[142:145], v[182:185], v[42:45]
	v_mfma_f32_16x16x32_bf16 v[38:41], v[134:137], v[190:193], v[38:41]
	v_mfma_f32_16x16x32_bf16 v[34:37], v[142:145], v[190:193], v[34:37]
	s_setprio 0
	s_barrier
	s_add_i32 s29, s29, s52
	v_lshl_add_u64 v[200:201], v[226:227], 0, s[96:97]
	s_mov_b32 m0, s29
	ds_read_b128 v[186:189], v244 offset:49152
	ds_read_b128 v[190:193], v244 offset:50176
	ds_read_b128 v[178:181], v244 offset:51200
	ds_read_b128 v[182:185], v244 offset:52224
	ds_read_b128 v[170:173], v244 offset:53248
	ds_read_b128 v[174:177], v244 offset:54272
	ds_read_b128 v[162:165], v244 offset:55296
	ds_read_b128 v[166:169], v244 offset:56320
	global_load_lds_dwordx4 v[200:201], off
	s_add_i32 m0, s29, 0x2000
	s_add_u32 s36, s36, 0xb0080
	v_lshl_add_u64 v[200:201], v[228:229], 0, s[96:97]
	s_addc_u32 s37, s37, 0
	s_add_i32 s29, s69, s52
	global_load_lds_dwordx4 v[200:201], off
	v_lshl_add_u64 v[200:201], s[36:37], 0, v[214:215]
	s_mov_b32 m0, s29
	s_and_b64 vcc, exec, s[42:43]
	global_load_lds_dwordx4 v[200:201], off
	v_lshl_add_u64 v[200:201], s[36:37], 0, v[218:219]
	s_add_i32 m0, s29, 0x2000
	s_nop 0
	global_load_lds_dwordx4 v[200:201], off
	v_lshl_add_u64 v[200:201], v[230:231], 0, s[96:97]
	s_mov_b32 m0, s59
	s_nop 0
	global_load_lds_dwordx4 v[200:201], off
	v_lshl_add_u64 v[200:201], v[232:233], 0, s[96:97]
	s_mov_b32 m0, s60
	s_nop 0
	global_load_lds_dwordx4 v[200:201], off
	s_waitcnt vmcnt(8)
	s_waitcnt lgkmcnt(0)
	s_barrier
	s_cbranch_vccnz .LBB0_1102
	s_setprio 1
	v_mfma_f32_16x16x32_bf16 v[94:97], v[146:149], v[186:189], v[94:97]
	v_mfma_f32_16x16x32_bf16 v[90:93], v[154:157], v[186:189], v[90:93]
	v_mfma_f32_16x16x32_bf16 v[86:89], v[146:149], v[178:181], v[86:89]
	v_mfma_f32_16x16x32_bf16 v[82:85], v[154:157], v[178:181], v[82:85]
	v_mfma_f32_16x16x32_bf16 v[70:73], v[146:149], v[170:173], v[70:73]
	v_mfma_f32_16x16x32_bf16 v[66:69], v[154:157], v[170:173], v[66:69]
	v_mfma_f32_16x16x32_bf16 v[54:57], v[146:149], v[162:165], v[54:57]
	v_mfma_f32_16x16x32_bf16 v[50:53], v[154:157], v[162:165], v[50:53]
	v_mfma_f32_16x16x32_bf16 v[94:97], v[150:153], v[190:193], v[94:97]
	v_mfma_f32_16x16x32_bf16 v[90:93], v[158:161], v[190:193], v[90:93]
	v_mfma_f32_16x16x32_bf16 v[86:89], v[150:153], v[182:185], v[86:89]
	v_mfma_f32_16x16x32_bf16 v[82:85], v[158:161], v[182:185], v[82:85]
	v_mfma_f32_16x16x32_bf16 v[70:73], v[150:153], v[174:177], v[70:73]
	v_mfma_f32_16x16x32_bf16 v[66:69], v[158:161], v[174:177], v[66:69]
	v_mfma_f32_16x16x32_bf16 v[54:57], v[150:153], v[166:169], v[54:57]
	v_mfma_f32_16x16x32_bf16 v[50:53], v[158:161], v[166:169], v[50:53]
	s_setprio 0
	s_setprio 1
	v_mfma_f32_16x16x32_bf16 v[30:33], v[130:133], v[186:189], v[30:33]
	v_mfma_f32_16x16x32_bf16 v[26:29], v[138:141], v[186:189], v[26:29]
	v_mfma_f32_16x16x32_bf16 v[22:25], v[130:133], v[178:181], v[22:25]
	v_mfma_f32_16x16x32_bf16 v[18:21], v[138:141], v[178:181], v[18:21]
	v_mfma_f32_16x16x32_bf16 v[14:17], v[130:133], v[170:173], v[14:17]
	v_mfma_f32_16x16x32_bf16 v[10:13], v[138:141], v[170:173], v[10:13]
	v_mfma_f32_16x16x32_bf16 v[6:9], v[130:133], v[162:165], v[6:9]
	v_mfma_f32_16x16x32_bf16 v[2:5], v[138:141], v[162:165], v[2:5]
	v_mfma_f32_16x16x32_bf16 v[30:33], v[134:137], v[190:193], v[30:33]
	v_mfma_f32_16x16x32_bf16 v[26:29], v[142:145], v[190:193], v[26:29]
	v_mfma_f32_16x16x32_bf16 v[22:25], v[134:137], v[182:185], v[22:25]
	v_mfma_f32_16x16x32_bf16 v[18:21], v[142:145], v[182:185], v[18:21]
	v_mfma_f32_16x16x32_bf16 v[14:17], v[134:137], v[174:177], v[14:17]
	v_mfma_f32_16x16x32_bf16 v[10:13], v[142:145], v[174:177], v[10:13]
	v_mfma_f32_16x16x32_bf16 v[6:9], v[134:137], v[166:169], v[6:9]
	v_mfma_f32_16x16x32_bf16 v[2:5], v[142:145], v[166:169], v[2:5]
	s_setprio 0
	s_branch .LBB0_1102
